# attention loop: softmax VALU interleaved between MFMAs with double-buffered S and rolling LDS fragment reloads; GEMM k-loop barrier sunk below MFMAs to hide LDS read latency
# speedup vs baseline: 1.0430x; 1.0430x over previous
; #define RAW_BARRIER() do { asm volatile("s_waitcnt lgkmcnt(0)" ::: "memory"); __builtin_amdgcn_s_barrier(); } while (0)
; #define WAIT_VM(n) asm volatile("s_waitcnt vmcnt(" #n ")" ::: "memory")
; template <bool AF32>
; DI void gemm_main(const void* Ap, int lda, const short* Bp, int K, char* smem, f32x16 (&acc)[4][2]) {
;     ...
;   const int x = (r >> 2) & 3;
;   const int off0 = ((h ^ x) << 4);
;   const int aoff = (wm * 128 + r) * 64, boff = GBOFF + (wn * 64 + r) * 64;
;   struct Frag { bf16x8 a[4], b0, b1; };
;     ...
;   const int nk = K >> 5;
;   Frag F0, F1;
;   GLDS(0, 0);
;   GLDS(1, 1);
;   GLDS(2, 2);
;   GLDS(3, 3);
;   WAIT_VM(12);
;   RAW_BARRIER();
;   LOADF(F0, 0, 0);
;   for (int kt = 0; kt < nk - 3; kt++) {
;     LOADF(F1, kt & 3, 1);
;     MM(F0);
;     WAIT_VM(8);
;     RAW_BARRIER();
;     if (kt + 4 < nk) GLDS(kt + 4, kt & 3);
;     LOADF(F0, (kt + 1) & 3, 0);
;     MM(F1);
;   }
.LBB0_14:
	s_and_b32 s9, s7, 0x10000
	s_waitcnt lgkmcnt(0)
	v_mfma_f32_32x32x16_bf16 v[96:111], v[150:153], v[134:137], v[96:111]
	v_lshl_add_u64 v[182:183], v[180:181], 0, s[20:21]
	s_mov_b64 s[22:23], 0x1638100
	v_or_b32_e32 v154, s9, v188
	v_add3_u32 v158, s9, v186, v187
	v_add_u32_e32 v154, v154, v187
	v_lshl_add_u64 v[184:185], v[178:179], 0, s[20:21]
	ds_read_b128 v[162:165], v154 offset:16384
	ds_read_b128 v[154:157], v154 offset:18432
	ds_read_b128 v[174:177], v158
	ds_read_b128 v[170:173], v158 offset:2048
	ds_read_b128 v[166:169], v158 offset:4096
	ds_read_b128 v[158:161], v158 offset:6144
	v_mfma_f32_32x32x16_bf16 v[64:79], v[146:149], v[134:137], v[64:79]
	v_mfma_f32_32x32x16_bf16 v[32:47], v[142:145], v[134:137], v[32:47]
	v_mfma_f32_32x32x16_bf16 v[0:15], v[130:133], v[134:137], v[0:15]
	v_mfma_f32_32x32x16_bf16 v[16:31], v[130:133], v[138:141], v[16:31]
	v_lshl_add_u64 v[130:131], v[182:183], 0, s[22:23]
	s_mov_b64 s[22:23], 0x1630100
	v_lshl_add_u64 v[132:133], v[182:183], 0, s[22:23]
	s_mov_b64 s[22:23], 0x36e0100
	v_lshl_add_u64 v[134:135], v[184:185], 0, s[22:23]
	s_mov_b64 s[22:23], 0x36d8100
	v_lshl_add_u64 v[136:137], v[184:185], 0, s[22:23]
	v_mfma_f32_32x32x16_bf16 v[112:127], v[150:153], v[138:141], v[112:127]
	s_mov_b64 s[22:23], 0x1638140
	v_mfma_f32_32x32x16_bf16 v[80:95], v[146:149], v[138:141], v[80:95]
	v_mfma_f32_32x32x16_bf16 v[48:63], v[142:145], v[138:141], v[48:63]
	v_add_u32_e32 v138, s9, v189
	v_add_u32_e32 v141, 0x400, v138
	v_readfirstlane_b32 s9, v138
	v_add_u32_e32 v140, 0x4000, v138
	s_mov_b32 m0, s9
	v_readfirstlane_b32 s9, v141
	v_add_u32_e32 v139, 0x4400, v138
	s_waitcnt vmcnt(8)
	s_waitcnt lgkmcnt(0)
	s_barrier
	global_load_lds_dwordx4 v[136:137], off
	s_mov_b32 m0, s9
	v_readfirstlane_b32 s9, v140
	global_load_lds_dwordx4 v[134:135], off
	s_mov_b32 m0, s9
	v_readfirstlane_b32 s9, v139
	global_load_lds_dwordx4 v[132:133], off
	s_mov_b32 m0, s9
	s_add_i32 s9, s7, 0x8000
	s_and_b32 s9, s9, 0x18000
	s_waitcnt lgkmcnt(0)
	v_mfma_f32_32x32x16_bf16 v[96:111], v[174:177], v[154:157], v[96:111]
	v_add_u32_e32 v190, s9, v186
	v_or_b32_e32 v191, s9, v188
	global_load_lds_dwordx4 v[130:131], off
	v_add_u32_e32 v138, v190, v128
	v_add_u32_e32 v130, v191, v128
	ds_read_b128 v[134:137], v130 offset:16384
	ds_read_b128 v[130:133], v130 offset:18432
	ds_read_b128 v[150:153], v138
	ds_read_b128 v[146:149], v138 offset:2048
	ds_read_b128 v[142:145], v138 offset:4096
	ds_read_b128 v[138:141], v138 offset:6144
	v_mfma_f32_32x32x16_bf16 v[64:79], v[170:173], v[154:157], v[64:79]
	s_add_i32 s7, s7, 0x10000
	v_mfma_f32_32x32x16_bf16 v[32:47], v[166:169], v[154:157], v[32:47]
	v_mfma_f32_32x32x16_bf16 v[0:15], v[158:161], v[154:157], v[0:15]
	v_add_u32_e32 v154, v191, v187
	v_mfma_f32_32x32x16_bf16 v[16:31], v[158:161], v[162:165], v[16:31]
	v_add_u32_e32 v158, v190, v187
	v_mfma_f32_32x32x16_bf16 v[112:127], v[174:177], v[162:165], v[112:127]
	v_mfma_f32_32x32x16_bf16 v[80:95], v[170:173], v[162:165], v[80:95]
	v_mfma_f32_32x32x16_bf16 v[48:63], v[166:169], v[162:165], v[48:63]
	ds_read_b128 v[162:165], v154 offset:16384
	ds_read_b128 v[154:157], v154 offset:18432
	ds_read_b128 v[190:193], v158
	ds_read_b128 v[170:173], v158 offset:2048
	ds_read_b128 v[166:169], v158 offset:4096
	ds_read_b128 v[158:161], v158 offset:6144
	s_waitcnt lgkmcnt(6)
	v_mfma_f32_32x32x16_bf16 v[96:111], v[150:153], v[130:133], v[96:111]
	v_mfma_f32_32x32x16_bf16 v[64:79], v[146:149], v[130:133], v[64:79]
	v_mfma_f32_32x32x16_bf16 v[32:47], v[142:145], v[130:133], v[32:47]
	v_mfma_f32_32x32x16_bf16 v[0:15], v[138:141], v[130:133], v[0:15]
	v_lshl_add_u64 v[130:131], v[182:183], 0, s[22:23]
	s_mov_b64 s[22:23], 0x1630140
	v_lshl_add_u64 v[132:133], v[182:183], 0, s[22:23]
	s_mov_b64 s[22:23], 0x36e0140
	v_mfma_f32_32x32x16_bf16 v[16:31], v[138:141], v[134:137], v[16:31]
	v_add_u32_e32 v138, s9, v189
	v_add_u32_e32 v141, 0x400, v138
	v_readfirstlane_b32 s9, v138
	v_add_u32_e32 v140, 0x4000, v138
	s_mov_b32 m0, s9
	v_readfirstlane_b32 s9, v141
	v_add_u32_e32 v139, 0x4400, v138
	v_mfma_f32_32x32x16_bf16 v[112:127], v[150:153], v[134:137], v[112:127]
	v_mfma_f32_32x32x16_bf16 v[80:95], v[146:149], v[134:137], v[80:95]
	v_mfma_f32_32x32x16_bf16 v[48:63], v[142:145], v[134:137], v[48:63]
	v_lshl_add_u64 v[134:135], v[184:185], 0, s[22:23]
	s_mov_b64 s[22:23], 0x36d8140
	v_lshl_add_u64 v[136:137], v[184:185], 0, s[22:23]
	s_waitcnt vmcnt(8)
	s_waitcnt lgkmcnt(0)
	s_barrier
	global_load_lds_dwordx4 v[136:137], off
	s_mov_b32 m0, s9
	v_readfirstlane_b32 s9, v140
	global_load_lds_dwordx4 v[134:135], off
	s_mov_b32 m0, s9
	v_readfirstlane_b32 s9, v139
	global_load_lds_dwordx4 v[132:133], off
	s_mov_b32 m0, s9
	s_and_b32 s9, s7, 0x10000
	global_load_lds_dwordx4 v[130:131], off
	v_add_u32_e32 v174, s9, v186
	v_or_b32_e32 v131, s9, v188
	v_add_u32_e32 v130, v174, v128
	v_add_u32_e32 v131, v131, v128
	ds_read_b128 v[138:141], v131 offset:16384
	ds_read_b128 v[134:137], v131 offset:18432
	ds_read_b128 v[150:153], v130
	ds_read_b128 v[146:149], v130 offset:2048
	ds_read_b128 v[142:145], v130 offset:4096
	ds_read_b128 v[130:133], v130 offset:6144
	v_mfma_f32_32x32x16_bf16 v[112:127], v[190:193], v[162:165], v[112:127]
	s_add_u32 s20, s20, 0x80
	s_addc_u32 s21, s21, 0
	s_cmpk_eq_i32 s20, 0x700
	v_mfma_f32_32x32x16_bf16 v[96:111], v[190:193], v[154:157], v[96:111]
	v_mfma_f32_32x32x16_bf16 v[80:95], v[170:173], v[162:165], v[80:95]
	v_mfma_f32_32x32x16_bf16 v[64:79], v[170:173], v[154:157], v[64:79]
	v_mfma_f32_32x32x16_bf16 v[48:63], v[166:169], v[162:165], v[48:63]
	v_mfma_f32_32x32x16_bf16 v[32:47], v[166:169], v[154:157], v[32:47]
	v_mfma_f32_32x32x16_bf16 v[16:31], v[158:161], v[162:165], v[16:31]
	v_mfma_f32_32x32x16_bf16 v[0:15], v[158:161], v[154:157], v[0:15]
	s_cbranch_scc0 .LBB0_14
; #define RAW_BARRIER() do { asm volatile("s_waitcnt lgkmcnt(0)" ::: "memory"); __builtin_amdgcn_s_barrier(); } while (0)
; #define WAIT_VM(n) asm volatile("s_waitcnt vmcnt(" #n ")" ::: "memory")
; template <bool AF32>
; DI void gemm_main(const void* Ap, int lda, const short* Bp, int K, char* smem, f32x16 (&acc)[4][2]) {
;     ...
;   for (int kt = 0; kt < nk - 3; kt++) {
;     LOADF(F1, kt & 3, 1);
;     MM(F0);
;     WAIT_VM(8);
;     RAW_BARRIER();
;     if (kt + 4 < nk) GLDS(kt + 4, kt & 3);
;     LOADF(F0, (kt + 1) & 3, 0);
;     MM(F1);
;   }
;   LOADF(F1, (nk - 3) & 3, 1);
;   MM(F0);
;   WAIT_VM(4);
;   RAW_BARRIER();
;   LOADF(F0, (nk - 2) & 3, 0);
;   MM(F1);
;   LOADF(F1, (nk - 2) & 3, 1);
;   MM(F0);
;   WAIT_VM(0);
;   RAW_BARRIER();
;   LOADF(F0, (nk - 1) & 3, 0);
;   MM(F1);
;   LOADF(F1, (nk - 1) & 3, 1);
;   MM(F0);
;   MM(F1);
	s_waitcnt lgkmcnt(0)
	v_mfma_f32_32x32x16_bf16 v[80:95], v[146:149], v[138:141], v[80:95]
	s_lshl_b32 s36, s6, 8
	v_mfma_f32_32x32x16_bf16 v[64:79], v[146:149], v[134:137], v[64:79]
	v_add_u32_e32 v146, v174, v187
	v_add_u32_e32 v147, v188, v187
	v_mfma_f32_32x32x16_bf16 v[16:31], v[130:133], v[138:141], v[16:31]
	v_mfma_f32_32x32x16_bf16 v[0:15], v[130:133], v[134:137], v[0:15]
	ds_read_b128 v[130:133], v146
	v_mfma_f32_32x32x16_bf16 v[112:127], v[150:153], v[138:141], v[112:127]
	v_mfma_f32_32x32x16_bf16 v[96:111], v[150:153], v[134:137], v[96:111]
	v_mfma_f32_32x32x16_bf16 v[48:63], v[142:145], v[138:141], v[48:63]
	v_mfma_f32_32x32x16_bf16 v[32:47], v[142:145], v[134:137], v[32:47]
	ds_read_b128 v[134:137], v147 offset:16384
	ds_read_b128 v[138:141], v147 offset:18432
	ds_read_b128 v[142:145], v146 offset:2048
	s_waitcnt lgkmcnt(0)
	v_mfma_f32_32x32x16_bf16 v[112:127], v[130:133], v[134:137], v[112:127]
	v_mfma_f32_32x32x16_bf16 v[96:111], v[130:133], v[138:141], v[96:111]
	v_mfma_f32_32x32x16_bf16 v[80:95], v[142:145], v[134:137], v[80:95]
	v_mfma_f32_32x32x16_bf16 v[64:79], v[142:145], v[138:141], v[64:79]
	ds_read_b128 v[130:133], v146 offset:4096
	ds_read_b128 v[142:145], v146 offset:6144
	s_waitcnt vmcnt(8)
	v_add_u32_e32 v146, v186, v128
	s_waitcnt lgkmcnt(0)
	s_barrier
	s_waitcnt lgkmcnt(0)
	v_mfma_f32_32x32x16_bf16 v[48:63], v[130:133], v[134:137], v[48:63]
	v_mfma_f32_32x32x16_bf16 v[32:47], v[130:133], v[138:141], v[32:47]
	ds_read_b128 v[130:133], v146 offset:32768
	v_mfma_f32_32x32x16_bf16 v[0:15], v[142:145], v[138:141], v[0:15]
	v_add_u32_e32 v138, v188, v128
	v_mfma_f32_32x32x16_bf16 v[16:31], v[142:145], v[134:137], v[16:31]
	ds_read_b128 v[134:137], v138 offset:49152
	ds_read_b128 v[138:141], v138 offset:51200
	ds_read_b128 v[142:145], v146 offset:34816
	s_waitcnt lgkmcnt(0)
	v_mfma_f32_32x32x16_bf16 v[112:127], v[130:133], v[134:137], v[112:127]
	v_mfma_f32_32x32x16_bf16 v[96:111], v[130:133], v[138:141], v[96:111]
	v_mfma_f32_32x32x16_bf16 v[80:95], v[142:145], v[134:137], v[80:95]
	v_mfma_f32_32x32x16_bf16 v[64:79], v[142:145], v[138:141], v[64:79]
	ds_read_b128 v[130:133], v146 offset:36864
	ds_read_b128 v[142:145], v146 offset:38912
	v_add_u32_e32 v146, v186, v187
	s_waitcnt lgkmcnt(0)
	v_mfma_f32_32x32x16_bf16 v[48:63], v[130:133], v[134:137], v[48:63]
	v_mfma_f32_32x32x16_bf16 v[32:47], v[130:133], v[138:141], v[32:47]
	v_mfma_f32_32x32x16_bf16 v[16:31], v[142:145], v[134:137], v[16:31]
	v_mfma_f32_32x32x16_bf16 v[0:15], v[142:145], v[138:141], v[0:15]
	ds_read_b128 v[130:133], v146 offset:32768
	ds_read_b128 v[134:137], v147 offset:49152
	ds_read_b128 v[138:141], v147 offset:51200
	ds_read_b128 v[142:145], v146 offset:34816
	v_add_u32_e32 v147, 0x10000, v186
	v_add_u32_e32 v148, v147, v128
	v_add_u32_e32 v147, v147, v187
	s_waitcnt lgkmcnt(0)
	v_mfma_f32_32x32x16_bf16 v[112:127], v[130:133], v[134:137], v[112:127]
	v_mfma_f32_32x32x16_bf16 v[96:111], v[130:133], v[138:141], v[96:111]
	v_mfma_f32_32x32x16_bf16 v[80:95], v[142:145], v[134:137], v[80:95]
	v_mfma_f32_32x32x16_bf16 v[64:79], v[142:145], v[138:141], v[64:79]
	ds_read_b128 v[130:133], v146 offset:36864
	ds_read_b128 v[142:145], v146 offset:38912
	s_waitcnt vmcnt(4)
	s_waitcnt lgkmcnt(0)
	s_barrier
	v_or_b32_e32 v146, 0x4000, v188
	v_add_u32_e32 v149, v146, v128
	v_add_u32_e32 v146, v146, v187
	s_waitcnt lgkmcnt(0)
	v_mfma_f32_32x32x16_bf16 v[48:63], v[130:133], v[134:137], v[48:63]
	v_mfma_f32_32x32x16_bf16 v[32:47], v[130:133], v[138:141], v[32:47]
	ds_read_b128 v[130:133], v148
	v_mfma_f32_32x32x16_bf16 v[16:31], v[142:145], v[134:137], v[16:31]
	v_or_b32_e32 v134, 0x10000, v149
	ds_read_b128 v[134:137], v134
	v_mfma_f32_32x32x16_bf16 v[0:15], v[142:145], v[138:141], v[0:15]
	v_add_u32_e32 v138, 0x10800, v149
	ds_read_b128 v[138:141], v138
	ds_read_b128 v[142:145], v148 offset:2048
	s_waitcnt lgkmcnt(0)
	v_mfma_f32_32x32x16_bf16 v[112:127], v[130:133], v[134:137], v[112:127]
	v_mfma_f32_32x32x16_bf16 v[96:111], v[130:133], v[138:141], v[96:111]
	v_mfma_f32_32x32x16_bf16 v[80:95], v[142:145], v[134:137], v[80:95]
	v_mfma_f32_32x32x16_bf16 v[64:79], v[142:145], v[138:141], v[64:79]
	ds_read_b128 v[130:133], v148 offset:4096
	ds_read_b128 v[142:145], v148 offset:6144
	s_waitcnt lgkmcnt(0)
	v_mfma_f32_32x32x16_bf16 v[48:63], v[130:133], v[134:137], v[48:63]
	v_mfma_f32_32x32x16_bf16 v[32:47], v[130:133], v[138:141], v[32:47]
	ds_read_b128 v[130:133], v147
	v_mfma_f32_32x32x16_bf16 v[16:31], v[142:145], v[134:137], v[16:31]
	v_or_b32_e32 v134, 0x10000, v146
	ds_read_b128 v[134:137], v134
	v_mfma_f32_32x32x16_bf16 v[0:15], v[142:145], v[138:141], v[0:15]
	v_add_u32_e32 v138, 0x10800, v146
	ds_read_b128 v[138:141], v138
	ds_read_b128 v[142:145], v147 offset:2048
	s_waitcnt lgkmcnt(0)
	v_mfma_f32_32x32x16_bf16 v[112:127], v[130:133], v[134:137], v[112:127]
	v_mfma_f32_32x32x16_bf16 v[96:111], v[130:133], v[138:141], v[96:111]
	v_mfma_f32_32x32x16_bf16 v[80:95], v[142:145], v[134:137], v[80:95]
	v_mfma_f32_32x32x16_bf16 v[64:79], v[142:145], v[138:141], v[64:79]
	ds_read_b128 v[130:133], v147 offset:4096
	ds_read_b128 v[142:145], v147 offset:6144
	v_add_u32_e32 v147, 0x18000, v186
	s_waitcnt vmcnt(0)
	v_add_u32_e32 v128, v147, v128
	s_waitcnt lgkmcnt(0)
	s_barrier
; DI int my_tid() { int t = threadIdx.x; asm volatile("" : "+v"(t)); return t; }
; template <bool AF32>
; DI void gemm_main(const void* Ap, int lda, const short* Bp, int K, char* smem, f32x16 (&acc)[4][2]) {
;     ...
;   LOADF(F0, (nk - 1) & 3, 0);
;   MM(F1);
;   LOADF(F1, (nk - 1) & 3, 1);
;   MM(F0);
;   MM(F1);
;   __syncthreads();
; DI void prefetch_ssq(u32x4 (&pre)[8], const float* ssq, int m0) {
;   const int t_ = my_tid() & 255, ln_ = t_ & 63, ww_ = t_ >> 6;
; #pragma unroll
;   for (int s_ = 0; s_ < 8; s_++) pre[s_] = u32x4{__float_as_uint(ssq[m0 + ww_ * 32 + s_ * 4 + (ln_ >> 4)]), 0u, 0u, 0u};
; }
	s_waitcnt lgkmcnt(0)
	v_mfma_f32_32x32x16_bf16 v[48:63], v[130:133], v[134:137], v[48:63]
	v_mfma_f32_32x32x16_bf16 v[32:47], v[130:133], v[138:141], v[32:47]
	ds_read_b128 v[130:133], v128
	v_mfma_f32_32x32x16_bf16 v[0:15], v[142:145], v[138:141], v[0:15]
	v_add_u32_e32 v138, 0x18000, v149
	v_mfma_f32_32x32x16_bf16 v[16:31], v[142:145], v[134:137], v[16:31]
	ds_read_b128 v[134:137], v138
	ds_read_b128 v[138:141], v138 offset:2048
	ds_read_b128 v[142:145], v128 offset:2048
	s_waitcnt lgkmcnt(0)
	v_mfma_f32_32x32x16_bf16 v[112:127], v[130:133], v[134:137], v[112:127]
	v_mfma_f32_32x32x16_bf16 v[96:111], v[130:133], v[138:141], v[96:111]
	v_mfma_f32_32x32x16_bf16 v[80:95], v[142:145], v[134:137], v[80:95]
	v_mfma_f32_32x32x16_bf16 v[64:79], v[142:145], v[138:141], v[64:79]
	ds_read_b128 v[130:133], v128 offset:4096
	ds_read_b128 v[142:145], v128 offset:6144
	v_add_u32_e32 v128, v147, v187
	s_waitcnt lgkmcnt(0)
	v_mfma_f32_32x32x16_bf16 v[48:63], v[130:133], v[134:137], v[48:63]
	v_mfma_f32_32x32x16_bf16 v[32:47], v[130:133], v[138:141], v[32:47]
	ds_read_b128 v[130:133], v128
	v_mfma_f32_32x32x16_bf16 v[16:31], v[142:145], v[134:137], v[16:31]
	v_add_u32_e32 v134, 0x18000, v146
	v_mfma_f32_32x32x16_bf16 v[0:15], v[142:145], v[138:141], v[0:15]
	ds_read_b128 v[138:141], v134
	ds_read_b128 v[142:145], v134 offset:2048
	ds_read_b128 v[134:137], v128 offset:2048
	s_waitcnt lgkmcnt(0)
	v_mfma_f32_32x32x16_bf16 v[112:127], v[130:133], v[138:141], v[112:127]
	v_mfma_f32_32x32x16_bf16 v[96:111], v[130:133], v[142:145], v[96:111]
	ds_read_b128 v[130:133], v128 offset:4096
	ds_read_b128 v[146:149], v128 offset:6144
	v_mov_b32_e32 v128, v196
	s_waitcnt vmcnt(0) lgkmcnt(0)
	s_barrier
	v_mfma_f32_32x32x16_bf16 v[80:95], v[134:137], v[138:141], v[80:95]
	v_mfma_f32_32x32x16_bf16 v[64:79], v[134:137], v[142:145], v[64:79]
	v_mov_b32_e32 v137, v196
	v_mfma_f32_32x32x16_bf16 v[48:63], v[130:133], v[138:141], v[48:63]
	v_mfma_f32_32x32x16_bf16 v[32:47], v[130:133], v[142:145], v[32:47]
	v_lshrrev_b32_e32 v130, 1, v128
	v_and_b32_e32 v130, 0x60, v130
	v_bfe_u32 v128, v128, 4, 2
	v_or3_b32 v130, v130, v128, s36
	v_ashrrev_i32_e32 v131, 31, v130
	v_lshl_add_u64 v[150:151], v[130:131], 2, s[12:13]
	global_load_dword v128, v[150:151], off
	global_load_dword v131, v[150:151], off offset:16
	global_load_dword v132, v[150:151], off offset:32
	global_load_dword v133, v[150:151], off offset:48
	global_load_dword v134, v[150:151], off offset:64
	global_load_dword v135, v[150:151], off offset:80
	global_load_dword v136, v[150:151], off offset:96
	global_load_dword v130, v[150:151], off offset:112
	v_mfma_f32_32x32x16_bf16 v[16:31], v[146:149], v[138:141], v[16:31]
	v_mov_b32_e32 v138, v196
	s_nop 0
	v_cmp_gt_u32_e32 vcc, s49, v138
	v_mfma_f32_32x32x16_bf16 v[0:15], v[146:149], v[142:145], v[0:15]
	s_and_saveexec_b64 s[20:21], vcc
	s_cbranch_execz .LBB0_17
; DI int my_tid() { int t = threadIdx.x; asm volatile("" : "+v"(t)); return t; }
; DI void stage_half(const f32x16 (&acc)[4][2], int pm, char* smem) {
;   const int tid = my_tid(), lane = tid & 63, w = tid >> 6, r = lane & 31, h = lane >> 5;
;   const int wm = w >> 2, wn = w & 3;
;   float* sf = (float*)(smem + (wn >> 1) * SF_BYTES);
;   if (wm == pm) {
; #pragma unroll
;     for (int mi = 0; mi < 4; mi++)
; #pragma unroll
;       for (int ni = 0; ni < 2; ni++)
; #pragma unroll
;         for (int i = 0; i < 16; i++) {
;           int row = mi * 32 + (i & 3) + 8 * (i >> 2) + 4 * h;
;           int col = (wn & 1) * 64 + ni * 32 + r;
;           sf[row * SF_LD + col] = acc[mi][ni][i];
;         }
;   }
;   __syncthreads();
	s_movk_i32 s7, 0x80
	v_cmp_gt_u32_e32 vcc, s7, v138
	v_lshrrev_b32_e32 v140, 3, v138
	v_and_b32_e32 v138, 0x5f, v138
	v_cndmask_b32_e64 v139, v199, 0, vcc
	v_and_b32_e32 v140, 4, v140
	v_lshl_or_b32 v138, v138, 2, v139
	v_mad_u32_u24 v138, v140, s3, v138
	v_add_u32_e32 v139, 0x400, v138
	ds_write2_b32 v138, v112, v96 offset1:32
	ds_write2_b32 v138, v113, v97 offset0:132 offset1:164
	ds_write2_b32 v139, v114, v98 offset0:8 offset1:40
	ds_write2_b32 v139, v115, v99 offset0:140 offset1:172
	v_add_u32_e32 v139, 0x1000, v138
	ds_write2_b32 v139, v116, v100 offset0:32 offset1:64
	ds_write2_b32 v139, v117, v101 offset0:164 offset1:196
	v_add_u32_e32 v139, 0x1400, v138
	ds_write2_b32 v139, v118, v102 offset0:40 offset1:72
	ds_write2_b32 v139, v119, v103 offset0:172 offset1:204
	v_add_u32_e32 v139, 0x2000, v138
	ds_write2_b32 v139, v120, v104 offset0:64 offset1:96
	ds_write2_b32 v139, v121, v105 offset0:196 offset1:228
	v_add_u32_e32 v139, 0x2400, v138
	ds_write2_b32 v139, v122, v106 offset0:72 offset1:104
	ds_write2_b32 v139, v123, v107 offset0:204 offset1:236
	v_add_u32_e32 v139, 0x3000, v138
	ds_write2_b32 v139, v124, v108 offset0:96 offset1:128
	v_add_u32_e32 v139, 0x3200, v138
	ds_write2_b32 v139, v125, v109 offset0:100 offset1:132
	v_add_u32_e32 v139, 0x3400, v138
	ds_write2_b32 v139, v126, v110 offset0:104 offset1:136
	v_add_u32_e32 v139, 0x3600, v138
	ds_write2_b32 v139, v127, v111 offset0:108 offset1:140
	v_add_u32_e32 v139, 0x4000, v138
	ds_write2_b32 v139, v80, v64 offset0:128 offset1:160
	v_add_u32_e32 v139, 0x4400, v138
	ds_write2_b32 v139, v81, v65 offset0:4 offset1:36
	ds_write2_b32 v139, v82, v66 offset0:136 offset1:168
	v_add_u32_e32 v139, 0x4800, v138
	ds_write2_b32 v139, v83, v67 offset0:12 offset1:44
	v_add_u32_e32 v139, 0x5000, v138
	ds_write2_b32 v139, v84, v68 offset0:160 offset1:192
	v_add_u32_e32 v139, 0x5400, v138
	ds_write2_b32 v139, v85, v69 offset0:36 offset1:68
	ds_write2_b32 v139, v86, v70 offset0:168 offset1:200
	v_add_u32_e32 v139, 0x5800, v138
	ds_write2_b32 v139, v87, v71 offset0:44 offset1:76
	v_add_u32_e32 v139, 0x6000, v138
	ds_write2_b32 v139, v88, v72 offset0:192 offset1:224
	v_add_u32_e32 v139, 0x6400, v138
	ds_write2_b32 v139, v89, v73 offset0:68 offset1:100
	ds_write2_b32 v139, v90, v74 offset0:200 offset1:232
	v_add_u32_e32 v139, 0x6800, v138
	ds_write2_b32 v139, v91, v75 offset0:76 offset1:108
	v_add_u32_e32 v139, 0x7200, v138
	ds_write2_b32 v139, v92, v76 offset0:96 offset1:128
	v_add_u32_e32 v139, 0x7400, v138
	ds_write2_b32 v139, v93, v77 offset0:100 offset1:132
	v_add_u32_e32 v139, 0x7600, v138
	ds_write2_b32 v139, v94, v78 offset0:104 offset1:136
	v_add_u32_e32 v139, 0x7800, v138
	ds_write2_b32 v139, v95, v79 offset0:108 offset1:140
	v_add_u32_e32 v139, 0x8400, v138
	ds_write2_b32 v139, v48, v32 offset1:32
	ds_write2_b32 v139, v49, v33 offset0:132 offset1:164
	v_add_u32_e32 v139, 0x8800, v138
	ds_write2_b32 v139, v50, v34 offset0:8 offset1:40
	ds_write2_b32 v139, v51, v35 offset0:140 offset1:172
	v_add_u32_e32 v139, 0x9400, v138
	ds_write2_b32 v139, v52, v36 offset0:32 offset1:64
	ds_write2_b32 v139, v53, v37 offset0:164 offset1:196
	v_add_u32_e32 v139, 0x9800, v138
	ds_write2_b32 v139, v54, v38 offset0:40 offset1:72
	ds_write2_b32 v139, v55, v39 offset0:172 offset1:204
	v_add_u32_e32 v139, 0xa400, v138
	ds_write2_b32 v139, v56, v40 offset0:64 offset1:96
	ds_write2_b32 v139, v57, v41 offset0:196 offset1:228
	v_add_u32_e32 v139, 0xa800, v138
	ds_write2_b32 v139, v58, v42 offset0:72 offset1:104
	ds_write2_b32 v139, v59, v43 offset0:204 offset1:236
	v_add_u32_e32 v139, 0xb400, v138
	ds_write2_b32 v139, v60, v44 offset0:96 offset1:128
	v_add_u32_e32 v139, 0xb600, v138
	ds_write2_b32 v139, v61, v45 offset0:100 offset1:132
	v_add_u32_e32 v139, 0xb800, v138
	ds_write2_b32 v139, v62, v46 offset0:104 offset1:136
	v_add_u32_e32 v139, 0xba00, v138
	ds_write2_b32 v139, v63, v47 offset0:108 offset1:140
	v_add_u32_e32 v139, 0xc400, v138
	ds_write2_b32 v139, v16, v0 offset0:128 offset1:160
	v_add_u32_e32 v139, 0xc800, v138
	ds_write2_b32 v139, v17, v1 offset0:4 offset1:36
	ds_write2_b32 v139, v18, v2 offset0:136 offset1:168
	v_add_u32_e32 v139, 0xcc00, v138
	ds_write2_b32 v139, v19, v3 offset0:12 offset1:44
	v_add_u32_e32 v139, 0xd400, v138
	ds_write2_b32 v139, v20, v4 offset0:160 offset1:192
	v_add_u32_e32 v139, 0xd800, v138
	ds_write2_b32 v139, v21, v5 offset0:36 offset1:68
	ds_write2_b32 v139, v22, v6 offset0:168 offset1:200
	v_add_u32_e32 v139, 0xdc00, v138
	ds_write2_b32 v139, v23, v7 offset0:44 offset1:76
	v_add_u32_e32 v139, 0xe400, v138
	ds_write2_b32 v139, v24, v8 offset0:192 offset1:224
	v_add_u32_e32 v139, 0xe800, v138
	ds_write2_b32 v139, v25, v9 offset0:68 offset1:100
	ds_write2_b32 v139, v26, v10 offset0:200 offset1:232
	v_add_u32_e32 v139, 0xec00, v138
	ds_write2_b32 v139, v27, v11 offset0:76 offset1:108
	v_add_u32_e32 v139, 0xf600, v138
	ds_write2_b32 v139, v28, v12 offset0:96 offset1:128
	v_add_u32_e32 v139, 0xf800, v138
	ds_write2_b32 v139, v29, v13 offset0:100 offset1:132
	v_add_u32_e32 v139, 0xfa00, v138
	v_add_u32_e32 v138, 0xfc00, v138
	ds_write2_b32 v139, v30, v14 offset0:104 offset1:136
	ds_write2_b32 v138, v31, v15 offset0:108 offset1:140

; #define RAW_BARRIER() do { asm volatile("s_waitcnt lgkmcnt(0)" ::: "memory"); __builtin_amdgcn_s_barrier(); } while (0)
; #define WAIT_VM(n) asm volatile("s_waitcnt vmcnt(" #n ")" ::: "memory")
; template <bool AF32>
; DI void gemm_main(const void* Ap, int lda, const short* Bp, int K, char* smem, f32x16 (&acc)[4][2]) {
;     ...
;   const int x = (r >> 2) & 3;
;   const int off0 = ((h ^ x) << 4);
;   const int aoff = (wm * 128 + r) * 64, boff = GBOFF + (wn * 64 + r) * 64;
;   struct Frag { bf16x8 a[4], b0, b1; };
;     ...
;   const int nk = K >> 5;
;   Frag F0, F1;
;   GLDS(0, 0);
;   GLDS(1, 1);
;   GLDS(2, 2);
;   GLDS(3, 3);
;   WAIT_VM(12);
;   RAW_BARRIER();
;   LOADF(F0, 0, 0);
;   for (int kt = 0; kt < nk - 3; kt++) {
;     LOADF(F1, kt & 3, 1);
;     MM(F0);
;     WAIT_VM(8);
;     RAW_BARRIER();
;     if (kt + 4 < nk) GLDS(kt + 4, kt & 3);
;     LOADF(F0, (kt + 1) & 3, 0);
;     MM(F1);
;   }
.LBB0_42:
	s_and_b32 s9, s8, 0x10000
	s_waitcnt lgkmcnt(0)
	v_mfma_f32_32x32x16_bf16 v[16:31], v[130:133], v[138:141], v[16:31]
	v_or_b32_e32 v154, s9, v188
	v_add3_u32 v158, s9, v186, v187
	v_add_u32_e32 v154, v154, v187
	v_lshl_add_u64 v[184:185], v[178:179], 0, s[6:7]
	s_mov_b64 s[10:11], 0xdf60100
	ds_read_b128 v[162:165], v154 offset:16384
	ds_read_b128 v[154:157], v154 offset:18432
	ds_read_b128 v[174:177], v158
	ds_read_b128 v[170:173], v158 offset:2048
	ds_read_b128 v[166:169], v158 offset:4096
	ds_read_b128 v[158:161], v158 offset:6144
	v_mfma_f32_32x32x16_bf16 v[0:15], v[130:133], v[134:137], v[0:15]
	v_lshl_add_u64 v[182:183], v[180:181], 0, s[6:7]
	v_lshl_add_u64 v[132:133], v[182:183], 0, s[78:79]
	v_lshl_add_u64 v[130:131], v[182:183], 0, s[76:77]
	v_mfma_f32_32x32x16_bf16 v[112:127], v[150:153], v[138:141], v[112:127]
	v_mfma_f32_32x32x16_bf16 v[80:95], v[146:149], v[138:141], v[80:95]
	v_mfma_f32_32x32x16_bf16 v[48:63], v[142:145], v[138:141], v[48:63]
	v_add_u32_e32 v138, s9, v189
	v_add_u32_e32 v141, 0x400, v138
	v_readfirstlane_b32 s9, v138
	v_add_u32_e32 v140, 0x4000, v138
	s_mov_b32 m0, s9
	v_readfirstlane_b32 s9, v141
	v_add_u32_e32 v139, 0x4400, v138
	v_mfma_f32_32x32x16_bf16 v[96:111], v[150:153], v[134:137], v[96:111]
	v_mfma_f32_32x32x16_bf16 v[64:79], v[146:149], v[134:137], v[64:79]
	v_mfma_f32_32x32x16_bf16 v[32:47], v[142:145], v[134:137], v[32:47]
	v_lshl_add_u64 v[134:135], v[184:185], 0, s[10:11]
	s_mov_b64 s[10:11], 0xdf58100
	v_lshl_add_u64 v[136:137], v[184:185], 0, s[10:11]
	s_waitcnt vmcnt(8)
	s_waitcnt lgkmcnt(0)
	s_barrier
	global_load_lds_dwordx4 v[136:137], off
	s_mov_b32 m0, s9
	v_readfirstlane_b32 s9, v140
	global_load_lds_dwordx4 v[134:135], off
	s_mov_b32 m0, s9
	v_readfirstlane_b32 s9, v139
	global_load_lds_dwordx4 v[132:133], off
	s_mov_b32 m0, s9
	s_add_i32 s9, s8, 0x8000
	s_and_b32 s9, s9, 0x18000
	s_waitcnt lgkmcnt(0)
	v_mfma_f32_32x32x16_bf16 v[16:31], v[158:161], v[162:165], v[16:31]
	v_add_u32_e32 v190, s9, v186
	v_or_b32_e32 v191, s9, v188
	global_load_lds_dwordx4 v[130:131], off
	v_add_u32_e32 v138, v190, v128
	v_add_u32_e32 v130, v191, v128
	ds_read_b128 v[134:137], v130 offset:16384
	ds_read_b128 v[130:133], v130 offset:18432
	ds_read_b128 v[150:153], v138
	ds_read_b128 v[146:149], v138 offset:2048
	ds_read_b128 v[142:145], v138 offset:4096
	ds_read_b128 v[138:141], v138 offset:6144
	v_mfma_f32_32x32x16_bf16 v[0:15], v[158:161], v[154:157], v[0:15]
	s_mov_b64 s[10:11], 0xdf60140
	v_add_u32_e32 v158, v190, v187
	s_add_i32 s8, s8, 0x10000
	v_mfma_f32_32x32x16_bf16 v[112:127], v[174:177], v[162:165], v[112:127]
	v_mfma_f32_32x32x16_bf16 v[80:95], v[170:173], v[162:165], v[80:95]
	v_mfma_f32_32x32x16_bf16 v[48:63], v[166:169], v[162:165], v[48:63]
	v_mfma_f32_32x32x16_bf16 v[96:111], v[174:177], v[154:157], v[96:111]
	v_mfma_f32_32x32x16_bf16 v[64:79], v[170:173], v[154:157], v[64:79]
	v_mfma_f32_32x32x16_bf16 v[32:47], v[166:169], v[154:157], v[32:47]
	v_add_u32_e32 v154, v191, v187
	ds_read_b128 v[162:165], v154 offset:16384
	ds_read_b128 v[154:157], v154 offset:18432
	ds_read_b128 v[190:193], v158
	ds_read_b128 v[170:173], v158 offset:2048
	ds_read_b128 v[166:169], v158 offset:4096
	ds_read_b128 v[158:161], v158 offset:6144
	s_waitcnt lgkmcnt(6)
	v_mfma_f32_32x32x16_bf16 v[16:31], v[138:141], v[134:137], v[16:31]
	v_mfma_f32_32x32x16_bf16 v[0:15], v[138:141], v[130:133], v[0:15]
	v_add_u32_e32 v138, s9, v189
	v_add_u32_e32 v141, 0x400, v138
	v_readfirstlane_b32 s9, v138
	v_add_u32_e32 v140, 0x4000, v138
	s_mov_b32 m0, s9
	v_readfirstlane_b32 s9, v141
	v_add_u32_e32 v139, 0x4400, v138
	v_mfma_f32_32x32x16_bf16 v[112:127], v[150:153], v[134:137], v[112:127]
	v_mfma_f32_32x32x16_bf16 v[80:95], v[146:149], v[134:137], v[80:95]
	v_mfma_f32_32x32x16_bf16 v[48:63], v[142:145], v[134:137], v[48:63]
	v_lshl_add_u64 v[134:135], v[184:185], 0, s[10:11]
	s_mov_b64 s[10:11], 0xdf58140
	v_lshl_add_u64 v[136:137], v[184:185], 0, s[10:11]
	s_waitcnt vmcnt(8)
	s_waitcnt lgkmcnt(0)
	s_barrier
	global_load_lds_dwordx4 v[136:137], off
	s_mov_b32 m0, s9
	v_readfirstlane_b32 s9, v140
	v_mfma_f32_32x32x16_bf16 v[96:111], v[150:153], v[130:133], v[96:111]
	global_load_lds_dwordx4 v[134:135], off
	s_mov_b32 m0, s9
	v_readfirstlane_b32 s9, v139
	v_mfma_f32_32x32x16_bf16 v[64:79], v[146:149], v[130:133], v[64:79]
	v_mfma_f32_32x32x16_bf16 v[32:47], v[142:145], v[130:133], v[32:47]
	v_lshl_add_u64 v[132:133], v[182:183], 0, s[82:83]
	v_lshl_add_u64 v[130:131], v[182:183], 0, s[80:81]
	global_load_lds_dwordx4 v[132:133], off
	s_mov_b32 m0, s9
	s_and_b32 s9, s8, 0x10000
	global_load_lds_dwordx4 v[130:131], off
	v_add_u32_e32 v174, s9, v186
	v_or_b32_e32 v131, s9, v188
	v_add_u32_e32 v130, v174, v128
	v_add_u32_e32 v131, v131, v128
	ds_read_b128 v[138:141], v131 offset:16384
	ds_read_b128 v[134:137], v131 offset:18432
	ds_read_b128 v[150:153], v130
	ds_read_b128 v[146:149], v130 offset:2048
	ds_read_b128 v[142:145], v130 offset:4096
	ds_read_b128 v[130:133], v130 offset:6144
	v_mfma_f32_32x32x16_bf16 v[112:127], v[190:193], v[162:165], v[112:127]
	s_add_u32 s6, s6, 0x80
	s_addc_u32 s7, s7, 0
	s_cmpk_eq_i32 s6, 0x700
	v_mfma_f32_32x32x16_bf16 v[96:111], v[190:193], v[154:157], v[96:111]
	v_mfma_f32_32x32x16_bf16 v[80:95], v[170:173], v[162:165], v[80:95]
	v_mfma_f32_32x32x16_bf16 v[64:79], v[170:173], v[154:157], v[64:79]
	v_mfma_f32_32x32x16_bf16 v[48:63], v[166:169], v[162:165], v[48:63]
	v_mfma_f32_32x32x16_bf16 v[32:47], v[166:169], v[154:157], v[32:47]
	v_mfma_f32_32x32x16_bf16 v[16:31], v[158:161], v[162:165], v[16:31]
	v_mfma_f32_32x32x16_bf16 v[0:15], v[158:161], v[154:157], v[0:15]
	s_cbranch_scc0 .LBB0_42
; #define RAW_BARRIER() do { asm volatile("s_waitcnt lgkmcnt(0)" ::: "memory"); __builtin_amdgcn_s_barrier(); } while (0)
; #define WAIT_VM(n) asm volatile("s_waitcnt vmcnt(" #n ")" ::: "memory")
; template <bool AF32>
; DI void gemm_main(const void* Ap, int lda, const short* Bp, int K, char* smem, f32x16 (&acc)[4][2]) {
;     ...
;   for (int kt = 0; kt < nk - 3; kt++) {
;     LOADF(F1, kt & 3, 1);
;     MM(F0);
;     WAIT_VM(8);
;     RAW_BARRIER();
;     if (kt + 4 < nk) GLDS(kt + 4, kt & 3);
;     LOADF(F0, (kt + 1) & 3, 0);
;     MM(F1);
;   }
;   LOADF(F1, (nk - 3) & 3, 1);
;   MM(F0);
;   WAIT_VM(4);
;   RAW_BARRIER();
;   LOADF(F0, (nk - 2) & 3, 0);
;   MM(F1);
;   LOADF(F1, (nk - 2) & 3, 1);
;   MM(F0);
;   WAIT_VM(0);
;   RAW_BARRIER();
;   LOADF(F0, (nk - 1) & 3, 0);
;   MM(F1);
;   LOADF(F1, (nk - 1) & 3, 1);
;   MM(F0);
;   MM(F1);
	s_waitcnt lgkmcnt(0)
	v_mfma_f32_32x32x16_bf16 v[80:95], v[146:149], v[138:141], v[80:95]
	s_lshl_b32 s86, s56, 8
	v_mfma_f32_32x32x16_bf16 v[64:79], v[146:149], v[134:137], v[64:79]
	v_add_u32_e32 v146, v174, v187
	v_add_u32_e32 v147, v188, v187
	v_mfma_f32_32x32x16_bf16 v[16:31], v[130:133], v[138:141], v[16:31]
	v_mfma_f32_32x32x16_bf16 v[0:15], v[130:133], v[134:137], v[0:15]
	ds_read_b128 v[130:133], v146
	v_mfma_f32_32x32x16_bf16 v[112:127], v[150:153], v[138:141], v[112:127]
	v_mfma_f32_32x32x16_bf16 v[96:111], v[150:153], v[134:137], v[96:111]
	v_mfma_f32_32x32x16_bf16 v[48:63], v[142:145], v[138:141], v[48:63]
	v_mfma_f32_32x32x16_bf16 v[32:47], v[142:145], v[134:137], v[32:47]
	ds_read_b128 v[134:137], v147 offset:16384
	ds_read_b128 v[138:141], v147 offset:18432
	ds_read_b128 v[142:145], v146 offset:2048
	s_waitcnt lgkmcnt(0)
	v_mfma_f32_32x32x16_bf16 v[112:127], v[130:133], v[134:137], v[112:127]
	v_mfma_f32_32x32x16_bf16 v[96:111], v[130:133], v[138:141], v[96:111]
	v_mfma_f32_32x32x16_bf16 v[80:95], v[142:145], v[134:137], v[80:95]
	v_mfma_f32_32x32x16_bf16 v[64:79], v[142:145], v[138:141], v[64:79]
	ds_read_b128 v[130:133], v146 offset:4096
	ds_read_b128 v[142:145], v146 offset:6144
	s_waitcnt vmcnt(8)
	v_add_u32_e32 v146, v186, v128
	s_waitcnt lgkmcnt(0)
	s_barrier
	s_waitcnt lgkmcnt(0)
	v_mfma_f32_32x32x16_bf16 v[48:63], v[130:133], v[134:137], v[48:63]
	v_mfma_f32_32x32x16_bf16 v[32:47], v[130:133], v[138:141], v[32:47]
	ds_read_b128 v[130:133], v146 offset:32768
	v_mfma_f32_32x32x16_bf16 v[0:15], v[142:145], v[138:141], v[0:15]
	v_add_u32_e32 v138, v188, v128
	v_mfma_f32_32x32x16_bf16 v[16:31], v[142:145], v[134:137], v[16:31]
	ds_read_b128 v[134:137], v138 offset:49152
	ds_read_b128 v[138:141], v138 offset:51200
	ds_read_b128 v[142:145], v146 offset:34816
	s_waitcnt lgkmcnt(0)
	v_mfma_f32_32x32x16_bf16 v[112:127], v[130:133], v[134:137], v[112:127]
	v_mfma_f32_32x32x16_bf16 v[96:111], v[130:133], v[138:141], v[96:111]
	v_mfma_f32_32x32x16_bf16 v[80:95], v[142:145], v[134:137], v[80:95]
	v_mfma_f32_32x32x16_bf16 v[64:79], v[142:145], v[138:141], v[64:79]
	ds_read_b128 v[130:133], v146 offset:36864
	ds_read_b128 v[142:145], v146 offset:38912
	v_add_u32_e32 v146, v186, v187
	s_waitcnt lgkmcnt(0)
	v_mfma_f32_32x32x16_bf16 v[48:63], v[130:133], v[134:137], v[48:63]
	v_mfma_f32_32x32x16_bf16 v[32:47], v[130:133], v[138:141], v[32:47]
	v_mfma_f32_32x32x16_bf16 v[16:31], v[142:145], v[134:137], v[16:31]
	v_mfma_f32_32x32x16_bf16 v[0:15], v[142:145], v[138:141], v[0:15]
	ds_read_b128 v[130:133], v146 offset:32768
	ds_read_b128 v[134:137], v147 offset:49152
	ds_read_b128 v[138:141], v147 offset:51200
	ds_read_b128 v[142:145], v146 offset:34816
	v_add_u32_e32 v147, 0x10000, v186
	v_add_u32_e32 v148, v147, v128
	v_add_u32_e32 v147, v147, v187
	s_waitcnt lgkmcnt(0)
	v_mfma_f32_32x32x16_bf16 v[112:127], v[130:133], v[134:137], v[112:127]
	v_mfma_f32_32x32x16_bf16 v[96:111], v[130:133], v[138:141], v[96:111]
	v_mfma_f32_32x32x16_bf16 v[80:95], v[142:145], v[134:137], v[80:95]
	v_mfma_f32_32x32x16_bf16 v[64:79], v[142:145], v[138:141], v[64:79]
	ds_read_b128 v[130:133], v146 offset:36864
	ds_read_b128 v[142:145], v146 offset:38912
	s_waitcnt vmcnt(4)
	s_waitcnt lgkmcnt(0)
	s_barrier
	v_or_b32_e32 v146, 0x4000, v188
	v_add_u32_e32 v149, v146, v128
	v_add_u32_e32 v146, v146, v187
	s_waitcnt lgkmcnt(0)
	v_mfma_f32_32x32x16_bf16 v[48:63], v[130:133], v[134:137], v[48:63]
	v_mfma_f32_32x32x16_bf16 v[32:47], v[130:133], v[138:141], v[32:47]
	ds_read_b128 v[130:133], v148
	v_mfma_f32_32x32x16_bf16 v[16:31], v[142:145], v[134:137], v[16:31]
	v_or_b32_e32 v134, 0x10000, v149
	ds_read_b128 v[134:137], v134
	v_mfma_f32_32x32x16_bf16 v[0:15], v[142:145], v[138:141], v[0:15]
	v_add_u32_e32 v138, 0x10800, v149
	ds_read_b128 v[138:141], v138
	ds_read_b128 v[142:145], v148 offset:2048
	s_waitcnt lgkmcnt(0)
	v_mfma_f32_32x32x16_bf16 v[112:127], v[130:133], v[134:137], v[112:127]
	v_mfma_f32_32x32x16_bf16 v[96:111], v[130:133], v[138:141], v[96:111]
	v_mfma_f32_32x32x16_bf16 v[80:95], v[142:145], v[134:137], v[80:95]
	v_mfma_f32_32x32x16_bf16 v[64:79], v[142:145], v[138:141], v[64:79]
	ds_read_b128 v[130:133], v148 offset:4096
	ds_read_b128 v[142:145], v148 offset:6144
	s_waitcnt lgkmcnt(0)
	v_mfma_f32_32x32x16_bf16 v[48:63], v[130:133], v[134:137], v[48:63]
	v_mfma_f32_32x32x16_bf16 v[32:47], v[130:133], v[138:141], v[32:47]
	ds_read_b128 v[130:133], v147
	v_mfma_f32_32x32x16_bf16 v[16:31], v[142:145], v[134:137], v[16:31]
	v_or_b32_e32 v134, 0x10000, v146
	ds_read_b128 v[134:137], v134
	v_mfma_f32_32x32x16_bf16 v[0:15], v[142:145], v[138:141], v[0:15]
	v_add_u32_e32 v138, 0x10800, v146
	ds_read_b128 v[138:141], v138
	ds_read_b128 v[142:145], v147 offset:2048
	s_waitcnt lgkmcnt(0)
	v_mfma_f32_32x32x16_bf16 v[112:127], v[130:133], v[134:137], v[112:127]
	v_mfma_f32_32x32x16_bf16 v[96:111], v[130:133], v[138:141], v[96:111]
	v_mfma_f32_32x32x16_bf16 v[80:95], v[142:145], v[134:137], v[80:95]
	v_mfma_f32_32x32x16_bf16 v[64:79], v[142:145], v[138:141], v[64:79]
	ds_read_b128 v[130:133], v147 offset:4096
	ds_read_b128 v[142:145], v147 offset:6144
	v_add_u32_e32 v147, 0x18000, v186
	s_waitcnt vmcnt(0)
	v_add_u32_e32 v128, v147, v128
	s_waitcnt lgkmcnt(0)
	s_barrier
; DI int my_tid() { int t = threadIdx.x; asm volatile("" : "+v"(t)); return t; }
; template <bool AF32>
; DI void gemm_main(const void* Ap, int lda, const short* Bp, int K, char* smem, f32x16 (&acc)[4][2]) {
;     ...
;   LOADF(F0, (nk - 1) & 3, 0);
;   MM(F1);
;   LOADF(F1, (nk - 1) & 3, 1);
;   MM(F0);
;   MM(F1);
;   __syncthreads();
; DI void prefetch_ssq(u32x4 (&pre)[8], const float* ssq, int m0) {
;   const int t_ = my_tid() & 255, ln_ = t_ & 63, ww_ = t_ >> 6;
; #pragma unroll
;   for (int s_ = 0; s_ < 8; s_++) pre[s_] = u32x4{__float_as_uint(ssq[m0 + ww_ * 32 + s_ * 4 + (ln_ >> 4)]), 0u, 0u, 0u};
; }
	s_waitcnt lgkmcnt(0)
	v_mfma_f32_32x32x16_bf16 v[48:63], v[130:133], v[134:137], v[48:63]
	v_mfma_f32_32x32x16_bf16 v[32:47], v[130:133], v[138:141], v[32:47]
	ds_read_b128 v[130:133], v128
	v_mfma_f32_32x32x16_bf16 v[0:15], v[142:145], v[138:141], v[0:15]
	v_add_u32_e32 v138, 0x18000, v149
	v_mfma_f32_32x32x16_bf16 v[16:31], v[142:145], v[134:137], v[16:31]
	ds_read_b128 v[134:137], v138
	ds_read_b128 v[138:141], v138 offset:2048
	ds_read_b128 v[142:145], v128 offset:2048
	s_waitcnt lgkmcnt(0)
	v_mfma_f32_32x32x16_bf16 v[112:127], v[130:133], v[134:137], v[112:127]
	v_mfma_f32_32x32x16_bf16 v[96:111], v[130:133], v[138:141], v[96:111]
	v_mfma_f32_32x32x16_bf16 v[80:95], v[142:145], v[134:137], v[80:95]
	v_mfma_f32_32x32x16_bf16 v[64:79], v[142:145], v[138:141], v[64:79]
	ds_read_b128 v[130:133], v128 offset:4096
	ds_read_b128 v[142:145], v128 offset:6144
	v_add_u32_e32 v128, v147, v187
	s_waitcnt lgkmcnt(0)
	v_mfma_f32_32x32x16_bf16 v[48:63], v[130:133], v[134:137], v[48:63]
	v_mfma_f32_32x32x16_bf16 v[32:47], v[130:133], v[138:141], v[32:47]
	ds_read_b128 v[130:133], v128
	v_mfma_f32_32x32x16_bf16 v[0:15], v[142:145], v[138:141], v[0:15]
	v_add_u32_e32 v138, 0x18000, v146
	v_mfma_f32_32x32x16_bf16 v[16:31], v[142:145], v[134:137], v[16:31]
	ds_read_b128 v[134:137], v138
	ds_read_b128 v[138:141], v138 offset:2048
	ds_read_b128 v[142:145], v128 offset:2048
	s_waitcnt lgkmcnt(0)
	v_mfma_f32_32x32x16_bf16 v[112:127], v[130:133], v[134:137], v[112:127]
	v_mfma_f32_32x32x16_bf16 v[96:111], v[130:133], v[138:141], v[96:111]
	v_mov_b32_e32 v130, v196
	v_mfma_f32_32x32x16_bf16 v[80:95], v[142:145], v[134:137], v[80:95]
	v_mfma_f32_32x32x16_bf16 v[64:79], v[142:145], v[138:141], v[64:79]
	ds_read_b128 v[142:145], v128 offset:4096
	ds_read_b128 v[146:149], v128 offset:6144
	v_mov_b32_e32 v128, v196
	s_waitcnt vmcnt(0) lgkmcnt(0)
	s_barrier
	v_mfma_f32_32x32x16_bf16 v[48:63], v[142:145], v[134:137], v[48:63]
	v_lshrrev_b32_e32 v131, 1, v128
	v_and_b32_e32 v131, 0x60, v131
	v_bfe_u32 v128, v128, 4, 2
	v_or3_b32 v132, v128, v131, s86
	v_ashrrev_i32_e32 v133, 31, v132
	v_lshl_add_u64 v[132:133], v[132:133], 2, s[18:19]
	global_load_dword v128, v[132:133], off
	global_load_dword v164, v[132:133], off offset:16
	global_load_dword v160, v[132:133], off offset:32
	global_load_dword v159, v[132:133], off offset:48
	global_load_dword v158, v[132:133], off offset:64
	global_load_dword v157, v[132:133], off offset:80
	global_load_dword v156, v[132:133], off offset:96
	global_load_dword v155, v[132:133], off offset:112
	v_mfma_f32_32x32x16_bf16 v[32:47], v[142:145], v[138:141], v[32:47]
	v_mov_b32_e32 v131, v196
	s_nop 0
	v_cmp_gt_u32_e32 vcc, s49, v131
	v_mfma_f32_32x32x16_bf16 v[16:31], v[146:149], v[134:137], v[16:31]
	v_mfma_f32_32x32x16_bf16 v[0:15], v[146:149], v[138:141], v[0:15]
	s_and_saveexec_b64 s[6:7], vcc
	s_cbranch_execz .LBB0_45
; DI int my_tid() { int t = threadIdx.x; asm volatile("" : "+v"(t)); return t; }
; DI void stage_half(const f32x16 (&acc)[4][2], int pm, char* smem) {
;   const int tid = my_tid(), lane = tid & 63, w = tid >> 6, r = lane & 31, h = lane >> 5;
;   const int wm = w >> 2, wn = w & 3;
;   float* sf = (float*)(smem + (wn >> 1) * SF_BYTES);
;   if (wm == pm) {
; #pragma unroll
;     for (int mi = 0; mi < 4; mi++)
; #pragma unroll
;       for (int ni = 0; ni < 2; ni++)
; #pragma unroll
;         for (int i = 0; i < 16; i++) {
;           int row = mi * 32 + (i & 3) + 8 * (i >> 2) + 4 * h;
;           int col = (wn & 1) * 64 + ni * 32 + r;
;           sf[row * SF_LD + col] = acc[mi][ni][i];
;         }
;   }
;   __syncthreads();
	s_movk_i32 s8, 0x80
	v_cmp_gt_u32_e32 vcc, s8, v131
	v_lshrrev_b32_e32 v133, 3, v131
	v_and_b32_e32 v131, 0x5f, v131
	v_cndmask_b32_e64 v132, v199, 0, vcc
	v_and_b32_e32 v133, 4, v133
	v_lshl_or_b32 v131, v131, 2, v132
	v_mad_u32_u24 v131, v133, s3, v131
	v_add_u32_e32 v132, 0x400, v131
	ds_write2_b32 v131, v112, v96 offset1:32
	ds_write2_b32 v131, v113, v97 offset0:132 offset1:164
	ds_write2_b32 v132, v114, v98 offset0:8 offset1:40
	ds_write2_b32 v132, v115, v99 offset0:140 offset1:172
	v_add_u32_e32 v132, 0x1000, v131
	ds_write2_b32 v132, v116, v100 offset0:32 offset1:64
	ds_write2_b32 v132, v117, v101 offset0:164 offset1:196
	v_add_u32_e32 v132, 0x1400, v131
	ds_write2_b32 v132, v118, v102 offset0:40 offset1:72
	ds_write2_b32 v132, v119, v103 offset0:172 offset1:204
	v_add_u32_e32 v132, 0x2000, v131
	ds_write2_b32 v132, v120, v104 offset0:64 offset1:96
	ds_write2_b32 v132, v121, v105 offset0:196 offset1:228
	v_add_u32_e32 v132, 0x2400, v131
	ds_write2_b32 v132, v122, v106 offset0:72 offset1:104
	ds_write2_b32 v132, v123, v107 offset0:204 offset1:236
	v_add_u32_e32 v132, 0x3000, v131
	ds_write2_b32 v132, v124, v108 offset0:96 offset1:128
	v_add_u32_e32 v132, 0x3200, v131
	ds_write2_b32 v132, v125, v109 offset0:100 offset1:132
	v_add_u32_e32 v132, 0x3400, v131
	ds_write2_b32 v132, v126, v110 offset0:104 offset1:136
	v_add_u32_e32 v132, 0x3600, v131
	ds_write2_b32 v132, v127, v111 offset0:108 offset1:140
	v_add_u32_e32 v132, 0x4000, v131
	ds_write2_b32 v132, v80, v64 offset0:128 offset1:160
	v_add_u32_e32 v132, 0x4400, v131
	ds_write2_b32 v132, v81, v65 offset0:4 offset1:36
	ds_write2_b32 v132, v82, v66 offset0:136 offset1:168
	v_add_u32_e32 v132, 0x4800, v131
	ds_write2_b32 v132, v83, v67 offset0:12 offset1:44
	v_add_u32_e32 v132, 0x5000, v131
	ds_write2_b32 v132, v84, v68 offset0:160 offset1:192
	v_add_u32_e32 v132, 0x5400, v131
	ds_write2_b32 v132, v85, v69 offset0:36 offset1:68
	ds_write2_b32 v132, v86, v70 offset0:168 offset1:200
	v_add_u32_e32 v132, 0x5800, v131
	ds_write2_b32 v132, v87, v71 offset0:44 offset1:76
	v_add_u32_e32 v132, 0x6000, v131
	ds_write2_b32 v132, v88, v72 offset0:192 offset1:224
	v_add_u32_e32 v132, 0x6400, v131
	ds_write2_b32 v132, v89, v73 offset0:68 offset1:100
	ds_write2_b32 v132, v90, v74 offset0:200 offset1:232
	v_add_u32_e32 v132, 0x6800, v131
	ds_write2_b32 v132, v91, v75 offset0:76 offset1:108
	v_add_u32_e32 v132, 0x7200, v131
	ds_write2_b32 v132, v92, v76 offset0:96 offset1:128
	v_add_u32_e32 v132, 0x7400, v131
	ds_write2_b32 v132, v93, v77 offset0:100 offset1:132
	v_add_u32_e32 v132, 0x7600, v131
	ds_write2_b32 v132, v94, v78 offset0:104 offset1:136
	v_add_u32_e32 v132, 0x7800, v131
	ds_write2_b32 v132, v95, v79 offset0:108 offset1:140
	v_add_u32_e32 v132, 0x8400, v131
	ds_write2_b32 v132, v48, v32 offset1:32
	ds_write2_b32 v132, v49, v33 offset0:132 offset1:164
	v_add_u32_e32 v132, 0x8800, v131
	ds_write2_b32 v132, v50, v34 offset0:8 offset1:40
	ds_write2_b32 v132, v51, v35 offset0:140 offset1:172
	v_add_u32_e32 v132, 0x9400, v131
	ds_write2_b32 v132, v52, v36 offset0:32 offset1:64
	ds_write2_b32 v132, v53, v37 offset0:164 offset1:196
	v_add_u32_e32 v132, 0x9800, v131
	ds_write2_b32 v132, v54, v38 offset0:40 offset1:72
	ds_write2_b32 v132, v55, v39 offset0:172 offset1:204
	v_add_u32_e32 v132, 0xa400, v131
	ds_write2_b32 v132, v56, v40 offset0:64 offset1:96
	ds_write2_b32 v132, v57, v41 offset0:196 offset1:228
	v_add_u32_e32 v132, 0xa800, v131
	ds_write2_b32 v132, v58, v42 offset0:72 offset1:104
	ds_write2_b32 v132, v59, v43 offset0:204 offset1:236
	v_add_u32_e32 v132, 0xb400, v131
	ds_write2_b32 v132, v60, v44 offset0:96 offset1:128
	v_add_u32_e32 v132, 0xb600, v131
	ds_write2_b32 v132, v61, v45 offset0:100 offset1:132
	v_add_u32_e32 v132, 0xb800, v131
	ds_write2_b32 v132, v62, v46 offset0:104 offset1:136
	v_add_u32_e32 v132, 0xba00, v131
	ds_write2_b32 v132, v63, v47 offset0:108 offset1:140
	v_add_u32_e32 v132, 0xc400, v131
	ds_write2_b32 v132, v16, v0 offset0:128 offset1:160
	v_add_u32_e32 v132, 0xc800, v131
	ds_write2_b32 v132, v17, v1 offset0:4 offset1:36
	ds_write2_b32 v132, v18, v2 offset0:136 offset1:168
	v_add_u32_e32 v132, 0xcc00, v131
	ds_write2_b32 v132, v19, v3 offset0:12 offset1:44
	v_add_u32_e32 v132, 0xd400, v131
	ds_write2_b32 v132, v20, v4 offset0:160 offset1:192
	v_add_u32_e32 v132, 0xd800, v131
	ds_write2_b32 v132, v21, v5 offset0:36 offset1:68
	ds_write2_b32 v132, v22, v6 offset0:168 offset1:200
	v_add_u32_e32 v132, 0xdc00, v131
	ds_write2_b32 v132, v23, v7 offset0:44 offset1:76
	v_add_u32_e32 v132, 0xe400, v131
	ds_write2_b32 v132, v24, v8 offset0:192 offset1:224
	v_add_u32_e32 v132, 0xe800, v131
	ds_write2_b32 v132, v25, v9 offset0:68 offset1:100
	ds_write2_b32 v132, v26, v10 offset0:200 offset1:232
	v_add_u32_e32 v132, 0xec00, v131
	ds_write2_b32 v132, v27, v11 offset0:76 offset1:108
	v_add_u32_e32 v132, 0xf600, v131
	ds_write2_b32 v132, v28, v12 offset0:96 offset1:128
	v_add_u32_e32 v132, 0xf800, v131
	ds_write2_b32 v132, v29, v13 offset0:100 offset1:132
	v_add_u32_e32 v132, 0xfa00, v131
	v_add_u32_e32 v131, 0xfc00, v131
	ds_write2_b32 v132, v30, v14 offset0:104 offset1:136
	ds_write2_b32 v131, v31, v15 offset0:108 offset1:140

; DI int my_tid() { int t = threadIdx.x; asm volatile("" : "+v"(t)); return t; }
; DI float bf_lo(unsigned u) { return __uint_as_float(u << 16); }
; DI float bf_hi(unsigned u) { return __uint_as_float(u & 0xffff0000u); }
; DI float rsqrt_f(float x) { return __builtin_amdgcn_rsqf(x); }
; DI void mla_item(PRef p, int j, int seq, int head, int qb, char* smem) {
;   const int tid = my_tid(), lane = tid & 63, w = tid >> 6, r = lane & 31, h = lane >> 5;
;   const int s0 = seq == 0 ? 0 : TP + (seq - 1) * SS;
;   const int S = seq == 0 ? TP : SS;
;   const int pos = qb * 256 + w * 32 + r;
;   const int tok = s0 + pos;
;   const short* Q = (const short*)(p.ws + OFF_Q);
;   const float* gq = p.in[10] + j * 96;
;   float qv[6][8];
;   float ss = 0.f;
; #pragma unroll
;   for (int ks = 0; ks < 6; ks++) {
;     u32x4 t = *(const u32x4*)(Q + (size_t)tok * 1152 + head * 96 + ks * 16 + 8 * h);
; #pragma unroll
;     for (int e = 0; e < 4; e++) {
;       qv[ks][2 * e] = bf_lo(t[e]);
;       qv[ks][2 * e + 1] = bf_hi(t[e]);
;     }
; #pragma unroll
;     for (int e = 0; e < 8; e++) ss += qv[ks][e] * qv[ks][e];
;   }
;   ss += __shfl_xor(ss, 32);
;   const float f = rsqrt_f(ss * (1.f / 96.f) + EPS);
;   const float sc = 0.10206207261596575f * LOG2E;
; #pragma unroll
;   for (int ks = 0; ks < 6; ks++)
; #pragma unroll
;     for (int e = 0; e < 8; e++) qv[ks][e] *= f * gq[ks * 16 + 8 * h + e];
; #pragma unroll
;   for (int e = 0; e < 8; e++) {
;     float cs, sn;
;     rope_cs(pos, 8 * h + e, cs, sn);
;     float x1 = qv[4][e], x2 = qv[5][e];
;     qv[4][e] = x1 * cs - x2 * sn;
;     qv[5][e] = x1 * sn + x2 * cs;
;   }
.LBB0_165:
	v_mov_b32_e32 v10, v196
	s_getpc_b64 s[8:9]
	s_add_u32 s8, s8, _ZL10ROPE_TURNS@rel32@lo+4
	s_addc_u32 s9, s9, _ZL10ROPE_TURNS@rel32@hi+12
	s_waitcnt vmcnt(0)
	v_lshrrev_b32_e32 v0, 2, v10
	v_and_b32_e32 v11, 8, v0
	v_lshlrev_b32_e32 v4, 3, v11
	global_load_dwordx4 v[0:3], v4, s[8:9]
	global_load_dwordx4 v[18:21], v4, s[8:9] offset:16
	global_load_dwordx4 v[22:25], v4, s[8:9] offset:32
	global_load_dwordx4 v[6:9], v4, s[8:9] offset:48
	s_ashr_i32 s8, s20, 2
	s_and_b32 s9, s20, 31
	s_and_b32 s8, s8, -8
	v_readlane_b32 s16, v226, 15
	v_ashrrev_i32_e32 v12, 1, v10
	s_or_b32 s9, s9, s16
	s_or_b32 s8, s8, s52
	v_and_b32_e32 v12, 0xffffffe0, v12
	s_ashr_i32 s16, s8, 1
	v_lshl_add_u32 v12, s9, 8, v12
	v_mov_b64_e32 v[4:5], s[4:5]
	s_mul_i32 s8, s16, 0x60
	v_and_or_b32 v102, v10, 31, v12
	s_movk_i32 s21, 0x900
	s_ashr_i32 s9, s8, 31
	v_mad_i64_i32 v[4:5], s[22:23], v102, s21, v[4:5]
	s_waitcnt vmcnt(11)
	v_lshlrev_b32_e32 v128, 1, v11
	v_lshl_add_u64 v[4:5], s[8:9], 1, v[4:5]
	v_lshl_add_u64 v[4:5], v[4:5], 0, v[128:129]
	global_load_dwordx4 v[44:47], v[4:5], off offset:128
	global_load_dwordx4 v[52:55], v[4:5], off offset:160
	global_load_dwordx4 v[56:59], v[4:5], off offset:64
	global_load_dwordx4 v[60:63], v[4:5], off offset:96
	v_and_b32_e32 v12, 64, v200
	v_xor_b32_e32 v10, 32, v200
	v_add_u32_e32 v12, 64, v12
	v_cmp_lt_i32_e32 vcc, v10, v12
	v_lshlrev_b32_e32 v128, 2, v11
	v_cvt_f64_i32_e32 v[48:49], v102
	v_cndmask_b32_e32 v10, v200, v10, vcc
	v_lshlrev_b32_e32 v103, 2, v10
	global_load_dwordx4 v[10:13], v[4:5], off
	global_load_dwordx4 v[14:17], v[4:5], off offset:32
	s_mul_i32 s8, s16, 0xf00000
	s_mul_hi_i32 s9, s16, 0xf00000
	s_add_u32 s8, s10, s8
	s_addc_u32 s9, s11, s9
	s_mul_i32 s28, s16, 0xa00000
	s_mul_hi_i32 s29, s16, 0xa00000
	s_add_u32 s28, s12, s28
	s_addc_u32 s29, s13, s29
	s_mov_b32 s37, 0x500000
	s_mov_b32 s30, 0x3e16c740
	s_mov_b32 s23, 2
	s_mov_b32 s22, 1
	s_mov_b32 s21, 0
	s_waitcnt vmcnt(9)
	v_mul_f64 v[4:5], v[0:1], v[48:49]
	v_mul_f64 v[26:27], v[2:3], v[48:49]
	s_waitcnt vmcnt(8)
	v_mul_f64 v[28:29], v[18:19], v[48:49]
	v_mul_f64 v[30:31], v[20:21], v[48:49]
	s_waitcnt vmcnt(7)
	v_mul_f64 v[32:33], v[22:23], v[48:49]
	v_mul_f64 v[34:35], v[24:25], v[48:49]
	s_waitcnt vmcnt(6)
	v_mul_f64 v[36:37], v[6:7], v[48:49]
	v_floor_f64_e32 v[4:5], v[4:5]
	v_floor_f64_e32 v[26:27], v[26:27]
	v_floor_f64_e32 v[28:29], v[28:29]
	v_floor_f64_e32 v[30:31], v[30:31]
	v_floor_f64_e32 v[32:33], v[32:33]
	v_floor_f64_e32 v[34:35], v[34:35]
	v_floor_f64_e32 v[36:37], v[36:37]
	v_fma_f64 v[0:1], v[0:1], v[48:49], -v[4:5]
	v_fma_f64 v[2:3], v[2:3], v[48:49], -v[26:27]
	v_fma_f64 v[4:5], v[18:19], v[48:49], -v[28:29]
	v_fma_f64 v[18:19], v[20:21], v[48:49], -v[30:31]
	v_fma_f64 v[20:21], v[22:23], v[48:49], -v[32:33]
	v_fma_f64 v[22:23], v[24:25], v[48:49], -v[34:35]
	v_fma_f64 v[6:7], v[6:7], v[48:49], -v[36:37]
	v_cvt_f32_f64_e32 v0, v[0:1]
	v_cvt_f32_f64_e32 v1, v[2:3]
	v_cvt_f32_f64_e32 v2, v[4:5]
	v_cvt_f32_f64_e32 v3, v[18:19]
	v_cvt_f32_f64_e32 v4, v[20:21]
	v_cvt_f32_f64_e32 v5, v[22:23]
	v_cvt_f32_f64_e32 v6, v[6:7]
	v_sin_f32_e32 v28, v0
	v_cos_f32_e32 v26, v0
	v_sin_f32_e32 v29, v1
	v_cos_f32_e32 v27, v1
	v_sin_f32_e32 v66, v2
	v_cos_f32_e32 v30, v2
	v_sin_f32_e32 v67, v3
	v_cos_f32_e32 v31, v3
	v_sin_f32_e32 v24, v4
	v_cos_f32_e32 v22, v4
	v_sin_f32_e32 v25, v5
	v_cos_f32_e32 v23, v5
	v_sin_f32_e32 v20, v6
	v_cos_f32_e32 v18, v6
	s_waitcnt vmcnt(5)
	v_lshlrev_b32_e32 v34, 16, v47
	v_and_b32_e32 v35, 0xffff0000, v47
	s_waitcnt vmcnt(4)
	v_lshlrev_b32_e32 v32, 16, v55
	v_and_b32_e32 v33, 0xffff0000, v55
	global_load_dwordx4 v[0:3], v128, s[6:7] offset:272
	global_load_dwordx4 v[4:7], v128, s[6:7] offset:256
	v_lshlrev_b32_e32 v38, 16, v46
	v_and_b32_e32 v39, 0xffff0000, v46
	v_lshlrev_b32_e32 v36, 16, v54
	v_and_b32_e32 v37, 0xffff0000, v54
	v_lshlrev_b32_e32 v42, 16, v45
	v_and_b32_e32 v43, 0xffff0000, v45
	v_lshlrev_b32_e32 v40, 16, v53
	v_and_b32_e32 v41, 0xffff0000, v53
	v_lshlrev_b32_e32 v46, 16, v44
	v_and_b32_e32 v47, 0xffff0000, v44
	v_lshlrev_b32_e32 v44, 16, v52
	v_and_b32_e32 v45, 0xffff0000, v52
	s_waitcnt vmcnt(4)
	v_lshlrev_b32_e32 v104, 16, v63
	v_and_b32_e32 v105, 0xffff0000, v63
	global_load_dwordx4 v[52:55], v128, s[6:7] offset:208
	global_load_dwordx4 v[68:71], v128, s[6:7] offset:192
	v_lshlrev_b32_e32 v108, 16, v62
	v_and_b32_e32 v109, 0xffff0000, v62
	v_lshlrev_b32_e32 v112, 16, v61
	v_and_b32_e32 v113, 0xffff0000, v61
	v_lshlrev_b32_e32 v116, 16, v60
	v_and_b32_e32 v117, 0xffff0000, v60
	v_lshlrev_b32_e32 v120, 16, v59
	v_and_b32_e32 v121, 0xffff0000, v59
	global_load_dwordx4 v[60:63], v128, s[6:7] offset:144
	global_load_dwordx4 v[72:75], v128, s[6:7] offset:128
	v_lshlrev_b32_e32 v124, 16, v58
	v_and_b32_e32 v125, 0xffff0000, v58
	v_lshlrev_b32_e32 v130, 16, v57
	v_and_b32_e32 v131, 0xffff0000, v57
	v_lshlrev_b32_e32 v134, 16, v56
	v_and_b32_e32 v135, 0xffff0000, v56
	global_load_dwordx4 v[56:59], v128, s[6:7] offset:80
	global_load_dwordx4 v[76:79], v128, s[6:7] offset:64
	global_load_dwordx4 v[80:83], v128, s[6:7] offset:16
	global_load_dwordx4 v[84:87], v128, s[6:7]
	s_waitcnt vmcnt(11)
	v_lshlrev_b32_e32 v160, 16, v10
	v_and_b32_e32 v161, 0xffff0000, v10
	v_lshlrev_b32_e32 v156, 16, v11
	v_and_b32_e32 v157, 0xffff0000, v11
	v_pk_mul_f32 v[10:11], v[160:161], v[160:161]
	v_pk_mul_f32 v[158:159], v[156:157], v[156:157]
	v_add_f32_e32 v10, v10, v11
	v_lshlrev_b32_e32 v154, 16, v12
	v_and_b32_e32 v155, 0xffff0000, v12
	v_add_f32_e32 v10, v158, v10
	v_lshlrev_b32_e32 v150, 16, v13
	v_and_b32_e32 v151, 0xffff0000, v13
	v_pk_mul_f32 v[12:13], v[154:155], v[154:155]
	v_add_f32_e32 v10, v159, v10
	v_add_f32_e32 v10, v12, v10
	v_pk_mul_f32 v[152:153], v[150:151], v[150:151]
	v_add_f32_e32 v10, v13, v10
	s_waitcnt vmcnt(10)
; DI float rsqrt_f(float x) { return __builtin_amdgcn_rsqf(x); }
; template <int DK>
; DI void attn_core(const bf16x8 (&qf)[DK / 16], const short* Kg, const short* VTg, size_t ldvt, int ntiles, char* smem,
;                   f32x16 (&O)[2], float& lsum) {
;     ...
;   for (int i = 0; i < NKC; i++) { int c = tid + 512 * i; koff[i] = (c / KCH) * KROW + (c % KCH) * 16; }
;   const int vrow = tid >> 4, vcol = tid & 15;
;   const short* vg = VTg + (size_t)vrow * ldvt + vcol * 8;
;   const int voff = KT_BYTES + vrow * VROW + vcol * 16;
; #pragma unroll
;   for (int i = 0; i < 16; i++) { O[0][i] = 0.f; O[1][i] = 0.f; }
;   float l0 = 0.f;
; DI void mla_item(PRef p, int j, int seq, int head, int qb, char* smem) {
;     ...
;   ss += __shfl_xor(ss, 32);
;   const float f = rsqrt_f(ss * (1.f / 96.f) + EPS);
;   const float sc = 0.10206207261596575f * LOG2E;
; #pragma unroll
;   for (int ks = 0; ks < 6; ks++)
; #pragma unroll
;     for (int e = 0; e < 8; e++) qv[ks][e] *= f * gq[ks * 16 + 8 * h + e];
	v_lshlrev_b32_e32 v148, 16, v14
	v_and_b32_e32 v149, 0xffff0000, v14
	v_add_f32_e32 v10, v152, v10
	v_lshlrev_b32_e32 v144, 16, v15
	v_and_b32_e32 v145, 0xffff0000, v15
	v_pk_mul_f32 v[14:15], v[148:149], v[148:149]
	v_add_f32_e32 v10, v153, v10
	v_add_f32_e32 v10, v14, v10
	v_pk_mul_f32 v[146:147], v[144:145], v[144:145]
	v_add_f32_e32 v10, v15, v10
	v_lshlrev_b32_e32 v142, 16, v16
	v_and_b32_e32 v143, 0xffff0000, v16
	v_add_f32_e32 v10, v146, v10
	v_lshlrev_b32_e32 v138, 16, v17
	v_and_b32_e32 v139, 0xffff0000, v17
	v_pk_mul_f32 v[16:17], v[142:143], v[142:143]
	v_add_f32_e32 v10, v147, v10
	v_add_f32_e32 v10, v16, v10
	v_pk_mul_f32 v[140:141], v[138:139], v[138:139]
	v_add_f32_e32 v10, v17, v10
	v_add_f32_e32 v10, v140, v10
	v_pk_mul_f32 v[136:137], v[134:135], v[134:135]
	v_add_f32_e32 v10, v141, v10
	v_add_f32_e32 v10, v136, v10
	v_pk_mul_f32 v[132:133], v[130:131], v[130:131]
	v_add_f32_e32 v10, v137, v10
	v_add_f32_e32 v10, v132, v10
	v_pk_mul_f32 v[126:127], v[124:125], v[124:125]
	v_add_f32_e32 v10, v133, v10
	v_add_f32_e32 v10, v126, v10
	v_pk_mul_f32 v[122:123], v[120:121], v[120:121]
	v_add_f32_e32 v10, v127, v10
	v_add_f32_e32 v10, v122, v10
	v_pk_mul_f32 v[118:119], v[116:117], v[116:117]
	v_add_f32_e32 v10, v123, v10
	v_add_f32_e32 v10, v118, v10
	v_pk_mul_f32 v[114:115], v[112:113], v[112:113]
	v_add_f32_e32 v10, v119, v10
	v_add_f32_e32 v10, v114, v10
	v_pk_mul_f32 v[110:111], v[108:109], v[108:109]
	v_add_f32_e32 v10, v115, v10
	v_add_f32_e32 v10, v110, v10
	v_pk_mul_f32 v[106:107], v[104:105], v[104:105]
	v_add_f32_e32 v10, v111, v10
	v_add_f32_e32 v10, v106, v10
	v_pk_mul_f32 v[98:99], v[46:47], v[46:47]
	v_add_f32_e32 v10, v107, v10
	v_add_f32_e32 v10, v98, v10
	v_pk_mul_f32 v[94:95], v[42:43], v[42:43]
	v_add_f32_e32 v10, v99, v10
	v_add_f32_e32 v10, v94, v10
	v_pk_mul_f32 v[90:91], v[38:39], v[38:39]
	v_add_f32_e32 v10, v95, v10
	v_add_f32_e32 v10, v90, v10
	v_pk_mul_f32 v[64:65], v[34:35], v[34:35]
	v_add_f32_e32 v10, v91, v10
	v_add_f32_e32 v10, v64, v10
	v_pk_mul_f32 v[100:101], v[44:45], v[44:45]
	v_add_f32_e32 v10, v65, v10
	v_add_f32_e32 v10, v100, v10
	v_pk_mul_f32 v[96:97], v[40:41], v[40:41]
	v_add_f32_e32 v10, v101, v10
	v_add_f32_e32 v10, v96, v10
	v_pk_mul_f32 v[92:93], v[36:37], v[36:37]
	v_add_f32_e32 v10, v97, v10
	v_add_f32_e32 v10, v92, v10
	v_pk_mul_f32 v[88:89], v[32:33], v[32:33]
	v_add_f32_e32 v10, v93, v10
	v_add_f32_e32 v10, v88, v10
	v_add_f32_e32 v12, v89, v10
	ds_bpermute_b32 v13, v103, v12
	v_mul_f64 v[50:51], v[8:9], v[48:49]
	v_floor_f64_e32 v[10:11], v[50:51]
	v_fma_f64 v[8:9], v[8:9], v[48:49], -v[10:11]
	v_cvt_f32_f64_e32 v8, v[8:9]
	s_waitcnt lgkmcnt(0)
	v_add_f32_e32 v9, v12, v13
	v_fmamk_f32 v9, v9, 0x3c2aaaab, v198
	v_rsq_f32_e32 v100, v9
	global_load_dwordx4 v[48:51], v128, s[6:7] offset:336
	global_load_dwordx4 v[88:91], v128, s[6:7] offset:320
	v_sin_f32_e32 v21, v8
	v_cos_f32_e32 v19, v8
	s_waitcnt vmcnt(2)
	v_pk_mul_f32 v[8:9], v[84:85], v[100:101] op_sel_hi:[1,0]
	v_pk_mul_f32 v[10:11], v[52:53], v[100:101] op_sel_hi:[1,0]
	v_pk_mul_f32 v[106:107], v[8:9], v[160:161]
	v_pk_mul_f32 v[8:9], v[86:87], v[100:101] op_sel_hi:[1,0]
	v_mov_b32_e32 v160, v196
	v_pk_mul_f32 v[126:127], v[8:9], v[156:157]
	v_pk_mul_f32 v[8:9], v[80:81], v[100:101] op_sel_hi:[1,0]
	v_pk_mul_f32 v[12:13], v[54:55], v[100:101] op_sel_hi:[1,0]
	v_pk_mul_f32 v[132:133], v[8:9], v[154:155]
	v_pk_mul_f32 v[8:9], v[82:83], v[100:101] op_sel_hi:[1,0]
	v_lshlrev_b32_e32 v52, 4, v160
	v_pk_mul_f32 v[136:137], v[8:9], v[150:151]
	v_pk_mul_f32 v[8:9], v[76:77], v[100:101] op_sel_hi:[1,0]
	v_pk_mul_f32 v[4:5], v[4:5], v[100:101] op_sel_hi:[1,0]
	v_pk_mul_f32 v[140:141], v[8:9], v[148:149]
	v_pk_mul_f32 v[8:9], v[78:79], v[100:101] op_sel_hi:[1,0]
	v_and_b32_e32 v128, 0xf0, v52
	v_pk_mul_f32 v[144:145], v[8:9], v[144:145]
	v_pk_mul_f32 v[8:9], v[56:57], v[100:101] op_sel_hi:[1,0]
	v_mov_b64_e32 v[52:53], s[28:29]
	v_pk_mul_f32 v[56:57], v[8:9], v[142:143]
	v_pk_mul_f32 v[8:9], v[58:59], v[100:101] op_sel_hi:[1,0]
	s_mov_b32 s28, 0x28000
	v_pk_mul_f32 v[58:59], v[8:9], v[138:139]
	v_pk_mul_f32 v[8:9], v[72:73], v[100:101] op_sel_hi:[1,0]
	v_lshlrev_b32_e32 v92, 3, v160
	v_pk_mul_f32 v[134:135], v[8:9], v[134:135]
	v_pk_mul_f32 v[8:9], v[74:75], v[100:101] op_sel_hi:[1,0]
	v_add_u32_e32 v94, 0x1000, v92
	v_pk_mul_f32 v[130:131], v[8:9], v[130:131]
	v_pk_mul_f32 v[8:9], v[60:61], v[100:101] op_sel_hi:[1,0]
	v_add_u32_e32 v96, 0x2000, v92
	v_pk_mul_f32 v[14:15], v[8:9], v[124:125]
	v_pk_mul_f32 v[8:9], v[62:63], v[100:101] op_sel_hi:[1,0]
	v_ashrrev_i32_e32 v93, 31, v92
	v_pk_mul_f32 v[16:17], v[8:9], v[120:121]
	v_pk_mul_f32 v[8:9], v[68:69], v[100:101] op_sel_hi:[1,0]
	v_ashrrev_i32_e32 v95, 31, v94
	v_pk_mul_f32 v[60:61], v[8:9], v[116:117]
	v_pk_mul_f32 v[8:9], v[70:71], v[100:101] op_sel_hi:[1,0]
	v_ashrrev_i32_e32 v101, 4, v160
	v_mad_i64_i32 v[52:53], s[28:29], v101, s28, v[52:53]
	v_ashrrev_i32_e32 v97, 31, v96
	s_add_u32 s28, s8, 0x6000
	v_pk_mul_f32 v[10:11], v[10:11], v[108:109]
	v_pk_mul_f32 v[12:13], v[12:13], v[104:105]
	v_lshlrev_b64 v[54:55], 1, v[92:93]
	v_lshlrev_b64 v[104:105], 1, v[94:95]
	v_lshlrev_b64 v[108:109], 1, v[96:97]
	v_lshl_add_u64 v[98:99], v[52:53], 0, v[128:129]
	s_addc_u32 s29, s9, 0
	v_lshl_add_u64 v[62:63], s[8:9], 0, v[54:55]
	v_lshl_add_u64 v[68:69], s[8:9], 0, v[104:105]
	v_lshl_add_u64 v[76:77], s[8:9], 0, v[108:109]
	v_add_co_u32_e32 v52, vcc, s37, v98
	v_lshl_add_u64 v[54:55], s[28:29], 0, v[54:55]
	global_load_dwordx4 v[62:65], v[62:63], off
	s_nop 0
	global_load_dwordx4 v[68:71], v[68:69], off
	v_addc_co_u32_e32 v53, vcc, 0, v99, vcc
	global_load_dwordx4 v[72:75], v[98:99], off
	s_nop 0
	global_load_dwordx4 v[76:79], v[76:77], off
	s_nop 0
	global_load_dwordx4 v[80:83], v[52:53], off
	global_load_dwordx4 v[84:87], v[54:55], off
	v_lshl_add_u64 v[54:55], s[28:29], 0, v[104:105]
	v_pk_mul_f32 v[8:9], v[8:9], v[112:113]
	v_lshl_add_u64 v[104:105], s[28:29], 0, v[108:109]
	global_load_dwordx4 v[108:111], v[54:55], off
	global_load_dwordx4 v[112:115], v[104:105], off
	global_load_dwordx4 v[116:119], v[98:99], off offset:256
	global_load_dwordx4 v[120:123], v[52:53], off offset:256
	v_pk_mul_f32 v[0:1], v[0:1], v[100:101] op_sel_hi:[1,0]
	v_pk_mul_f32 v[124:125], v[4:5], v[46:47]
	v_pk_mul_f32 v[142:143], v[0:1], v[38:39]
	v_pk_mul_f32 v[0:1], v[2:3], v[100:101] op_sel_hi:[1,0]
	v_pk_mul_f32 v[4:5], v[6:7], v[100:101] op_sel_hi:[1,0]
	v_pk_mul_f32 v[146:147], v[0:1], v[34:35]
	v_pk_mul_f32 v[138:139], v[4:5], v[42:43]
	v_mul_hi_i32 v3, v160, s41
	s_waitcnt vmcnt(10)
; #define KLOAD(kf_, base)                                                                       \
;   { _Pragma("unroll") for (int ks = 0; ks < NKS; ks++) kf_[ks] = *(const bf16x8*)((base) + kfo + ks * 32); }
; #define QKM(dst, kf_)                                                                          \
;   {                                                                                            \
;     _Pragma("unroll") for (int i = 0; i < 16; i++) dst[i] = 0.f;                               \
;     _Pragma("unroll") for (int ks = 0; ks < NKS; ks++) dst = MFMA(kf_[ks], qf[ks], dst);       \
;   }
; template <int DK>
; DI void attn_core(const bf16x8 (&qf)[DK / 16], const short* Kg, const short* VTg, size_t ldvt, int ntiles, char* smem,
;                   f32x16 (&O)[2], float& lsum) {
;     ...
;   const int kfo = pr * KROW + h * 16;
;   const int vfo = KT_BYTES + r * VROW + h * 16;
;   AGLOAD(0);
;   ASTORE(0);
;   AGLOAD(ntiles > 1 ? 1 : 0);
;   ASTORE(1);
;   __syncthreads();
;   f32x16 Sc;
;   {
;     bf16x8 kf[NKS];
;     KLOAD(kf, smem);
;     QKM(Sc, kf);
;   }
; DI void mla_item(PRef p, int j, int seq, int head, int qb, char* smem) {
;     ...
;   for (int e = 0; e < 8; e++) {
;     float cs, sn;
;     rope_cs(pos, 8 * h + e, cs, sn);
;     float x1 = qv[4][e], x2 = qv[5][e];
;     qv[4][e] = x1 * cs - x2 * sn;
;     qv[5][e] = x1 * sn + x2 * cs;
;   }
;   bf16x8 qf[6];
; #pragma unroll
;   for (int ks = 0; ks < 6; ks++) {
;     u32x4 t;
; #pragma unroll
;     for (int e = 0; e < 4; e++) t[e] = pack_bf16(qv[ks][2 * e] * sc, qv[ks][2 * e + 1] * sc);
;     qf[ks] = __builtin_bit_cast(bf16x8, t);
;   }
	v_pk_mul_f32 v[0:1], v[88:89], v[100:101] op_sel_hi:[1,0]
	v_lshrrev_b32_e32 v6, 31, v3
	v_pk_mul_f32 v[88:89], v[0:1], v[44:45]
	v_pk_mul_f32 v[0:1], v[90:91], v[100:101] op_sel_hi:[1,0]
	v_lshrrev_b32_e32 v3, 1, v3
	v_pk_mul_f32 v[90:91], v[0:1], v[40:41]
	v_pk_mul_f32 v[0:1], v[48:49], v[100:101] op_sel_hi:[1,0]
	v_add_u32_e32 v3, v3, v6
	v_pk_mul_f32 v[148:149], v[0:1], v[36:37]
	v_pk_mul_f32 v[0:1], v[50:51], v[100:101] op_sel_hi:[1,0]
	v_add_lshl_u32 v104, v3, v160, 4
	v_pk_mul_f32 v[150:151], v[0:1], v[32:33]
	v_pk_mul_f32 v[0:1], v[88:89], v[26:27]
	v_add_u32_e32 v3, 0x200, v160
	v_pk_fma_f32 v[152:153], v[124:125], v[28:29], v[0:1]
	v_pk_mul_f32 v[0:1], v[90:91], v[30:31]
	v_mul_hi_i32 v6, v3, s41
	v_pk_fma_f32 v[154:155], v[138:139], v[66:67], v[0:1]
	v_pk_mul_f32 v[0:1], v[148:149], v[22:23]
	v_lshrrev_b32_e32 v7, 31, v6
	v_pk_fma_f32 v[156:157], v[142:143], v[24:25], v[0:1]
	v_pk_mul_f32 v[0:1], v[150:151], v[18:19]
	v_lshrrev_b32_e32 v6, 1, v6
	v_pk_fma_f32 v[158:159], v[146:147], v[20:21], v[0:1]
	v_pk_mul_f32 v[0:1], v[106:107], s[30:31] op_sel_hi:[1,0]
	v_add_u32_e32 v6, v6, v7
	v_cvt_pk_bf16_f32 v48, v0, v1
	v_pk_mul_f32 v[0:1], v[126:127], s[30:31] op_sel_hi:[1,0]
	v_add_lshl_u32 v105, v6, v3, 4
	v_cvt_pk_bf16_f32 v49, v0, v1
	v_pk_mul_f32 v[0:1], v[132:133], s[30:31] op_sel_hi:[1,0]
	v_add_u32_e32 v3, 0x400, v160
	v_cvt_pk_bf16_f32 v50, v0, v1
	v_pk_mul_f32 v[0:1], v[136:137], s[30:31] op_sel_hi:[1,0]
	v_mul_hi_i32 v6, v3, s41
	v_cvt_pk_bf16_f32 v51, v0, v1
	v_pk_mul_f32 v[0:1], v[140:141], s[30:31] op_sel_hi:[1,0]
	v_lshrrev_b32_e32 v7, 31, v6
	v_cvt_pk_bf16_f32 v52, v0, v1
	v_pk_mul_f32 v[0:1], v[144:145], s[30:31] op_sel_hi:[1,0]
	v_lshrrev_b32_e32 v6, 1, v6
	v_cvt_pk_bf16_f32 v53, v0, v1
	v_pk_mul_f32 v[0:1], v[56:57], s[30:31] op_sel_hi:[1,0]
	v_add_u32_e32 v6, v6, v7
	v_cvt_pk_bf16_f32 v54, v0, v1
	v_pk_mul_f32 v[0:1], v[58:59], s[30:31] op_sel_hi:[1,0]
	v_add_lshl_u32 v106, v6, v3, 4
	v_cvt_pk_bf16_f32 v55, v0, v1
	v_pk_mul_f32 v[0:1], v[134:135], s[30:31] op_sel_hi:[1,0]
	v_and_b32_e32 v3, 19, v160
	v_cvt_pk_bf16_f32 v56, v0, v1
	v_lshlrev_b32_e32 v0, 1, v160
	v_lshrrev_b32_e32 v1, 1, v160
	v_and_b32_e32 v0, 8, v0
	v_and_b32_e32 v2, 4, v1
	v_and_b32_e32 v126, 16, v1
	v_or3_b32 v0, v3, v0, v2
	s_movk_i32 s28, 0xd0
	v_mad_u32_u24 v107, v0, s28, v126
	v_mad_u64_u32 v[100:101], s[28:29], v101, s36, v[128:129]
	v_add_u32_e32 v0, 0x6800, v100
	s_waitcnt vmcnt(9)
	ds_write_b128 v104, v[62:65]
	s_waitcnt vmcnt(8)
	ds_write_b128 v105, v[68:71]
	s_waitcnt vmcnt(6)
	ds_write_b128 v106, v[76:79]
	ds_write_b128 v100, v[72:75] offset:26624
	s_waitcnt vmcnt(5)
	ds_write_b128 v100, v[80:83] offset:35328
	s_waitcnt vmcnt(4)
	ds_write_b128 v104, v[84:87] offset:44032
	s_waitcnt vmcnt(3)
	ds_write_b128 v105, v[108:111] offset:44032
	s_waitcnt vmcnt(2)
	ds_write_b128 v106, v[112:115] offset:44032
	s_waitcnt vmcnt(1)
	ds_write_b128 v0, v[116:119] offset:44032
	s_waitcnt vmcnt(0)
	ds_write_b128 v0, v[120:123] offset:52736
	s_waitcnt lgkmcnt(0)
	s_barrier
	ds_read_b128 v[0:3], v107
	v_pk_mul_f32 v[4:5], v[130:131], s[30:31] op_sel_hi:[1,0]
	v_mov_b32_e32 v108, 0
	v_cvt_pk_bf16_f32 v57, v4, v5
	v_pk_mul_f32 v[4:5], v[14:15], s[30:31] op_sel_hi:[1,0]
	s_mov_b32 s28, 0
	v_cvt_pk_bf16_f32 v58, v4, v5
	v_pk_mul_f32 v[4:5], v[16:17], s[30:31] op_sel_hi:[1,0]
	v_mov_b32_e32 v14, v108
	v_cvt_pk_bf16_f32 v59, v4, v5
	v_pk_mul_f32 v[4:5], v[60:61], s[30:31] op_sel_hi:[1,0]
	v_mov_b32_e32 v15, v108
	v_cvt_pk_bf16_f32 v60, v4, v5
	ds_read_b128 v[4:7], v107 offset:32
	s_waitcnt lgkmcnt(1)
	v_mfma_f32_32x32x16_bf16 v[32:47], v[0:3], v[48:51], 0
	v_mul_f32_e64 v0, v8, s30
	v_mul_f32_e64 v1, v9, s30
	v_mov_b32_e32 v16, 0
	v_cvt_pk_bf16_f32 v61, v0, v1
	v_mul_f32_e64 v0, v10, s30
	v_mul_f32_e64 v1, v11, s30
	v_mov_b32_e32 v10, v108
	v_cvt_pk_bf16_f32 v62, v0, v1
	v_pk_mul_f32 v[0:1], v[12:13], s[30:31] op_sel_hi:[1,0]
	s_waitcnt lgkmcnt(0)
	v_mfma_f32_32x32x16_bf16 v[32:47], v[4:7], v[52:55], v[32:47]
	v_cvt_pk_bf16_f32 v63, v0, v1
	ds_read_b128 v[0:3], v107 offset:64
	v_mul_f32_e64 v4, v88, v28
	v_mul_f32_e64 v5, v89, v29
	v_mov_b32_e32 v11, v108
	v_pk_fma_f32 v[4:5], v[124:125], v[26:27], v[4:5] neg_lo:[0,0,1] neg_hi:[0,0,1]
	v_mov_b32_e32 v12, v108
	v_pk_mul_f32 v[4:5], v[4:5], s[30:31] op_sel_hi:[1,0]
	v_mov_b32_e32 v13, v108
	v_cvt_pk_bf16_f32 v64, v4, v5
	v_pk_mul_f32 v[4:5], v[90:91], v[66:67]
	v_mov_b32_e32 v17, v108
	v_pk_fma_f32 v[8:9], v[138:139], v[30:31], v[4:5] neg_lo:[0,0,1] neg_hi:[0,0,1]
	ds_read_b128 v[4:7], v107 offset:96
	s_waitcnt lgkmcnt(1)
	v_mfma_f32_32x32x16_bf16 v[32:47], v[0:3], v[56:59], v[32:47]
	v_mul_f32_e64 v0, v8, s30
	v_mul_f32_e64 v1, v9, s30
	v_mov_b32_e32 v8, v108
	v_cvt_pk_bf16_f32 v65, v0, v1
	v_mul_f32_e64 v0, v148, v24
	v_mul_f32_e64 v1, v149, v25
	v_mov_b32_e32 v9, v108
	v_pk_fma_f32 v[0:1], v[142:143], v[22:23], v[0:1] neg_lo:[0,0,1] neg_hi:[0,0,1]
	v_mov_b32_e32 v22, v108
	v_pk_mul_f32 v[0:1], v[0:1], s[30:31] op_sel_hi:[1,0]
	s_waitcnt lgkmcnt(0)
	v_mfma_f32_32x32x16_bf16 v[32:47], v[4:7], v[60:63], v[32:47]
	v_cvt_pk_bf16_f32 v66, v0, v1
	ds_read_b128 v[0:3], v107 offset:128
	v_mul_f32_e64 v4, v150, v20
	v_mul_f32_e64 v5, v151, v21
	v_mov_b32_e32 v20, v108
	v_pk_fma_f32 v[4:5], v[146:147], v[18:19], v[4:5] neg_lo:[0,0,1] neg_hi:[0,0,1]
	v_mov_b32_e32 v18, v108
	v_pk_mul_f32 v[4:5], v[4:5], s[30:31] op_sel_hi:[1,0]
	v_mov_b32_e32 v19, v108
	v_cvt_pk_bf16_f32 v67, v4, v5
	v_pk_mul_f32 v[4:5], v[152:153], s[30:31] op_sel_hi:[1,0]
	v_mov_b32_e32 v21, v108
	v_cvt_pk_bf16_f32 v68, v4, v5
	ds_read_b128 v[4:7], v107 offset:160
	s_waitcnt lgkmcnt(1)
; #define KLOAD(kf_, base)                                                                       \
;   { _Pragma("unroll") for (int ks = 0; ks < NKS; ks++) kf_[ks] = *(const bf16x8*)((base) + kfo + ks * 32); }
; #define VLOAD(vf_, base)                                                                       \
;   { _Pragma("unroll") for (int q = 0; q < 4; q++) vf_[q] = *(const bf16x8*)((base) + vfo + (q >> 1) * 32 * VROW + (q & 1) * 32); }
; #define QKM(dst, kf_)                                                                          \
;   {                                                                                            \
;     _Pragma("unroll") for (int i = 0; i < 16; i++) dst[i] = 0.f;                               \
;     _Pragma("unroll") for (int ks = 0; ks < NKS; ks++) dst = MFMA(kf_[ks], qf[ks], dst);       \
;   }
; template <int DK>
; DI void attn_core(const bf16x8 (&qf)[DK / 16], const short* Kg, const short* VTg, size_t ldvt, int ntiles, char* smem,
;                   f32x16 (&O)[2], float& lsum) {
;     ...
;   const int kfo = pr * KROW + h * 16;
;   const int vfo = KT_BYTES + r * VROW + h * 16;
;   AGLOAD(0);
;   ASTORE(0);
;   AGLOAD(ntiles > 1 ? 1 : 0);
;   ASTORE(1);
;   __syncthreads();
;   f32x16 Sc;
;   {
;     bf16x8 kf[NKS];
;     KLOAD(kf, smem);
;     QKM(Sc, kf);
;   }
;   int sc = 0, sn = 1, sw = 2;
;   for (int t = 0; t < ntiles; t++) {
;     const int tn = t + 2 < ntiles ? t + 2 : ntiles - 1;
;     AGLOAD(tn);
;     const char* cur = smem + sc * ST;
;     const char* nxt = smem + sn * ST;
;     f32x16 Sn;
;     bf16x8 pa, pb, qa, qb;
;     bf16x8 kf[NKS], vf[4];
;     KLOAD(kf, cur + 32 * KROW);
;     SB();
;     SOFTMAX(Sc, pa, pb, l0);
;     SB();
;     QKM(Sn, kf);
;     SB();
;     KLOAD(kf, cur + 64 * KROW);
;     VLOAD(vf, cur);
;     SB();
;     SOFTMAX(Sn, qa, qb, l0);
;     SB();
;     QKM(Sc, kf);
;     PVM(vf, pa, pb);
;     SB();
;     KLOAD(kf, cur + 96 * KROW);
;     VLOAD(vf, cur + 64);
;     SB();
;     SOFTMAX(Sc, pa, pb, l0);
;     SB();
;     QKM(Sn, kf);
;     PVM(vf, qa, qb);
;     SB();
;     KLOAD(kf, nxt);
;     VLOAD(vf, cur + 128);
;     SB();
;     SOFTMAX(Sn, qa, qb, l0);
;     SB();
;     QKM(Sc, kf);
;     PVM(vf, pa, pb);
;     SB();
;     VLOAD(vf, cur + 192);
;     PVM(vf, qa, qb);
;     ASTORE(sw);
;     __syncthreads();
;     const int tmp = sc; sc = sn; sn = sw; sw = tmp;
;   }
	v_mfma_f32_32x32x16_bf16 v[32:47], v[0:3], v[64:67], v[32:47]
	v_mul_f32_e64 v0, v154, s30
	v_mul_f32_e64 v1, v155, s30
	v_mov_b32_e32 v2, v108
	v_cvt_pk_bf16_f32 v69, v0, v1
	v_mul_f32_e64 v0, v156, s30
	v_mul_f32_e64 v1, v157, s30
	v_mov_b32_e32 v3, v108
	v_cvt_pk_bf16_f32 v70, v0, v1
	v_pk_mul_f32 v[0:1], v[158:159], s[30:31] op_sel_hi:[1,0]
	v_mov_b32_e32 v23, v108
	v_cvt_pk_bf16_f32 v71, v0, v1
	v_and_b32_e32 v0, 31, v160
	v_mad_u32_u24 v101, v0, s36, v126
	s_waitcnt lgkmcnt(0)
	v_mfma_f32_32x32x16_bf16 v[32:47], v[4:7], v[68:71], v[32:47]
	v_mov_b32_e32 v0, 0
	v_mov_b32_e32 v1, v108
	v_mov_b32_e32 v4, v108
	v_mov_b32_e32 v5, v108
	v_mov_b32_e32 v6, v108
	v_mov_b32_e32 v7, v108
	v_mov_b32_e32 v24, v108
	v_mov_b32_e32 v25, v108
	v_mov_b32_e32 v26, v108
	v_mov_b32_e32 v27, v108
	v_mov_b32_e32 v28, v108
	v_mov_b32_e32 v29, v108
	v_mov_b32_e32 v30, v108
	v_mov_b32_e32 v31, v108
	v_mov_b32_e32 v162, 0
	v_mov_b32_e32 v163, 0
	v_mov_b32_e32 v164, 0
	v_mov_b32_e32 v165, 0
	v_mov_b32_e32 v166, 0
	v_mov_b32_e32 v167, 0
	v_mov_b32_e32 v168, 0
	v_mov_b32_e32 v169, 0
	v_mov_b32_e32 v138, 0
	v_mov_b32_e32 v139, 0
	v_mov_b32_e32 v140, 0
	v_mov_b32_e32 v141, 0
	v_mov_b32_e32 v142, 0
	v_mov_b32_e32 v143, 0
	v_mov_b32_e32 v144, 0
	v_mov_b32_e32 v145, 0
	v_mov_b32_e32 v146, 0
	v_mov_b32_e32 v147, 0
	v_mov_b32_e32 v148, 0
	v_mov_b32_e32 v149, 0
	v_mov_b32_e32 v150, 0
	v_mov_b32_e32 v151, 0
	v_mov_b32_e32 v152, 0
	v_mov_b32_e32 v153, 0
	ds_read_b128 v[110:113], v107 offset:6656
	ds_read_b128 v[114:117], v107 offset:6688
	ds_read_b128 v[118:121], v107 offset:6720
	ds_read_b128 v[122:125], v107 offset:6752
	ds_read_b128 v[130:133], v107 offset:6784
	ds_read_b128 v[134:137], v107 offset:6816
	s_waitcnt lgkmcnt(0)
.Lmla_prompt_loop:
	s_min_u32 s29, s21, 0x7d
	s_add_i32 s29, s29, 2
	s_mul_i32 s34, s29, 0x6000
	s_add_u32 s34, s8, s34
	s_addc_u32 s35, s9, 0
	s_lshl_b32 s30, s29, 8
	s_mul_i32 s29, s28, 0xac00
	v_add_u32_e32 v128, s29, v107
	v_add_u32_e32 v170, s29, v101
	s_mul_i32 s29, s22, 0xac00
	v_add_u32_e32 v109, s29, v107
	s_waitcnt lgkmcnt(14)
	v_mfma_f32_32x32x16_bf16 v[172:187], v[110:113], v[48:51], 0
	ds_read_b128 v[110:113], v128 offset:13312
	v_exp_f32_e32 v32, v32
	v_exp_f32_e32 v33, v33
	v_add_f32_e32 v108, v32, v108
	v_exp_f32_e32 v34, v34
	v_lshl_add_u64 v[188:189], v[92:93], 1, s[34:35]
	global_load_dwordx4 v[84:87], v[188:189], off
	s_waitcnt lgkmcnt(13)
	v_mfma_f32_32x32x16_bf16 v[172:187], v[114:117], v[52:55], v[172:187]
	ds_read_b128 v[114:117], v128 offset:13344
	v_add_f32_e32 v108, v33, v108
	v_cvt_pk_bf16_f32 v154, v32, v33
	v_exp_f32_e32 v35, v35
	v_add_f32_e32 v108, v34, v108
	v_lshl_add_u64 v[190:191], v[94:95], 1, s[34:35]
	global_load_dwordx4 v[72:75], v[190:191], off
	s_waitcnt lgkmcnt(12)
	v_mfma_f32_32x32x16_bf16 v[172:187], v[118:121], v[56:59], v[172:187]
	ds_read_b128 v[118:121], v128 offset:13376
	v_exp_f32_e32 v36, v36
	v_add_f32_e32 v108, v35, v108
	v_cvt_pk_bf16_f32 v155, v34, v35
	v_exp_f32_e32 v37, v37
	v_lshl_add_u64 v[192:193], v[96:97], 1, s[34:35]
	global_load_dwordx4 v[76:79], v[192:193], off
	s_waitcnt lgkmcnt(11)
	v_mfma_f32_32x32x16_bf16 v[172:187], v[122:125], v[60:63], v[172:187]
	ds_read_b128 v[122:125], v128 offset:13408
	v_add_f32_e32 v108, v36, v108
	v_exp_f32_e32 v38, v38
	v_add_f32_e32 v108, v37, v108
	v_cvt_pk_bf16_f32 v156, v36, v37
	v_lshl_add_u64 v[188:189], v[98:99], 0, s[30:31]
	global_load_dwordx4 v[80:83], v[188:189], off
	s_add_u32 s30, s30, s37
	s_waitcnt lgkmcnt(10)
	v_mfma_f32_32x32x16_bf16 v[172:187], v[130:133], v[64:67], v[172:187]
	ds_read_b128 v[130:133], v128 offset:13440
	v_exp_f32_e32 v39, v39
	v_add_f32_e32 v108, v38, v108
	v_exp_f32_e32 v40, v40
	v_add_f32_e32 v108, v39, v108
	v_lshl_add_u64 v[190:191], v[98:99], 0, s[30:31]
	global_load_dwordx4 v[88:91], v[190:191], off
	s_mul_i32 s29, s23, 0xac00
	s_waitcnt lgkmcnt(9)
	v_mfma_f32_32x32x16_bf16 v[172:187], v[134:137], v[68:71], v[172:187]
	ds_read_b128 v[134:137], v128 offset:13472
	v_cvt_pk_bf16_f32 v157, v38, v39
	v_exp_f32_e32 v41, v41
	v_add_f32_e32 v108, v40, v108
	v_exp_f32_e32 v42, v42
	s_waitcnt lgkmcnt(9)
	v_mfma_f32_32x32x16_bf16 v[0:15], v[138:141], v[162:165], v[0:15]
	ds_read_b128 v[138:141], v170 offset:26624
	v_add_f32_e32 v108, v41, v108
	v_cvt_pk_bf16_f32 v158, v40, v41
	v_exp_f32_e32 v43, v43
	v_add_f32_e32 v108, v42, v108
	s_waitcnt lgkmcnt(9)
	v_mfma_f32_32x32x16_bf16 v[16:31], v[146:149], v[162:165], v[16:31]
	ds_read_b128 v[146:149], v170 offset:35328
	v_exp_f32_e32 v44, v44
	v_add_f32_e32 v108, v43, v108
	v_cvt_pk_bf16_f32 v159, v42, v43
	v_exp_f32_e32 v45, v45
	s_waitcnt lgkmcnt(9)
	v_mfma_f32_32x32x16_bf16 v[0:15], v[142:145], v[166:169], v[0:15]
	ds_read_b128 v[142:145], v170 offset:26656
	v_add_f32_e32 v108, v44, v108
	v_exp_f32_e32 v46, v46
	v_add_f32_e32 v108, v45, v108
	v_cvt_pk_bf16_f32 v160, v44, v45
	s_waitcnt lgkmcnt(9)
	v_mfma_f32_32x32x16_bf16 v[16:31], v[150:153], v[166:169], v[16:31]
	ds_read_b128 v[150:153], v170 offset:35360
	v_exp_f32_e32 v47, v47
	v_add_f32_e32 v108, v46, v108
	v_add_f32_e32 v108, v47, v108
	v_cvt_pk_bf16_f32 v161, v46, v47
	s_waitcnt lgkmcnt(9)
	v_mfma_f32_32x32x16_bf16 v[32:47], v[110:113], v[48:51], 0
	ds_read_b128 v[110:113], v128 offset:19968
	v_exp_f32_e32 v172, v172
	v_exp_f32_e32 v173, v173
	v_add_f32_e32 v108, v172, v108
	v_exp_f32_e32 v174, v174
	s_waitcnt lgkmcnt(9)
	v_mfma_f32_32x32x16_bf16 v[32:47], v[114:117], v[52:55], v[32:47]
	ds_read_b128 v[114:117], v128 offset:20000
	v_add_f32_e32 v108, v173, v108
	v_cvt_pk_bf16_f32 v162, v172, v173
	v_exp_f32_e32 v175, v175
	v_add_f32_e32 v108, v174, v108
	s_waitcnt lgkmcnt(9)
; #define KLOAD(kf_, base)                                                                       \
;   { _Pragma("unroll") for (int ks = 0; ks < NKS; ks++) kf_[ks] = *(const bf16x8*)((base) + kfo + ks * 32); }
; #define VLOAD(vf_, base)                                                                       \
;   { _Pragma("unroll") for (int q = 0; q < 4; q++) vf_[q] = *(const bf16x8*)((base) + vfo + (q >> 1) * 32 * VROW + (q & 1) * 32); }
; #define QKM(dst, kf_)                                                                          \
;   {                                                                                            \
;     _Pragma("unroll") for (int i = 0; i < 16; i++) dst[i] = 0.f;                               \
;     _Pragma("unroll") for (int ks = 0; ks < NKS; ks++) dst = MFMA(kf_[ks], qf[ks], dst);       \
;   }
; template <int DK>
; DI void attn_core(const bf16x8 (&qf)[DK / 16], const short* Kg, const short* VTg, size_t ldvt, int ntiles, char* smem,
;                   f32x16 (&O)[2], float& lsum) {
;     ...
;   const int kfo = pr * KROW + h * 16;
;   const int vfo = KT_BYTES + r * VROW + h * 16;
;   AGLOAD(0);
;   ASTORE(0);
;   AGLOAD(ntiles > 1 ? 1 : 0);
;   ASTORE(1);
;   __syncthreads();
;   f32x16 Sc;
;   {
;     bf16x8 kf[NKS];
;     KLOAD(kf, smem);
;     QKM(Sc, kf);
;   }
;   int sc = 0, sn = 1, sw = 2;
;   for (int t = 0; t < ntiles; t++) {
;     const int tn = t + 2 < ntiles ? t + 2 : ntiles - 1;
;     AGLOAD(tn);
;     const char* cur = smem + sc * ST;
;     const char* nxt = smem + sn * ST;
;     f32x16 Sn;
;     bf16x8 pa, pb, qa, qb;
;     bf16x8 kf[NKS], vf[4];
;     KLOAD(kf, cur + 32 * KROW);
;     SB();
;     SOFTMAX(Sc, pa, pb, l0);
;     SB();
;     QKM(Sn, kf);
;     SB();
;     KLOAD(kf, cur + 64 * KROW);
;     VLOAD(vf, cur);
;     SB();
;     SOFTMAX(Sn, qa, qb, l0);
;     SB();
;     QKM(Sc, kf);
;     PVM(vf, pa, pb);
;     SB();
;     KLOAD(kf, cur + 96 * KROW);
;     VLOAD(vf, cur + 64);
;     SB();
;     SOFTMAX(Sc, pa, pb, l0);
;     SB();
;     QKM(Sn, kf);
;     PVM(vf, qa, qb);
;     SB();
;     KLOAD(kf, nxt);
;     VLOAD(vf, cur + 128);
;     SB();
;     SOFTMAX(Sn, qa, qb, l0);
;     SB();
;     QKM(Sc, kf);
;     PVM(vf, pa, pb);
;     SB();
;     VLOAD(vf, cur + 192);
;     PVM(vf, qa, qb);
;     ASTORE(sw);
;     __syncthreads();
;     const int tmp = sc; sc = sn; sn = sw; sw = tmp;
;   }
	v_mfma_f32_32x32x16_bf16 v[32:47], v[118:121], v[56:59], v[32:47]
	ds_read_b128 v[118:121], v128 offset:20032
	v_exp_f32_e32 v176, v176
	v_add_f32_e32 v108, v175, v108
	v_cvt_pk_bf16_f32 v163, v174, v175
	v_exp_f32_e32 v177, v177
	s_waitcnt lgkmcnt(9)
	v_mfma_f32_32x32x16_bf16 v[32:47], v[122:125], v[60:63], v[32:47]
	ds_read_b128 v[122:125], v128 offset:20064
	v_add_f32_e32 v108, v176, v108
	v_exp_f32_e32 v178, v178
	v_add_f32_e32 v108, v177, v108
	v_cvt_pk_bf16_f32 v164, v176, v177
	s_waitcnt lgkmcnt(9)
	v_mfma_f32_32x32x16_bf16 v[32:47], v[130:133], v[64:67], v[32:47]
	ds_read_b128 v[130:133], v128 offset:20096
	v_exp_f32_e32 v179, v179
	v_add_f32_e32 v108, v178, v108
	v_exp_f32_e32 v180, v180
	v_add_f32_e32 v108, v179, v108
	s_waitcnt lgkmcnt(9)
	v_mfma_f32_32x32x16_bf16 v[32:47], v[134:137], v[68:71], v[32:47]
	ds_read_b128 v[134:137], v128 offset:20128
	v_cvt_pk_bf16_f32 v165, v178, v179
	v_exp_f32_e32 v181, v181
	v_add_f32_e32 v108, v180, v108
	v_exp_f32_e32 v182, v182
	s_waitcnt lgkmcnt(9)
	v_mfma_f32_32x32x16_bf16 v[0:15], v[138:141], v[154:157], v[0:15]
	ds_read_b128 v[138:141], v170 offset:26688
	v_add_f32_e32 v108, v181, v108
	v_cvt_pk_bf16_f32 v166, v180, v181
	v_exp_f32_e32 v183, v183
	v_add_f32_e32 v108, v182, v108
	s_waitcnt lgkmcnt(9)
	v_mfma_f32_32x32x16_bf16 v[16:31], v[146:149], v[154:157], v[16:31]
	ds_read_b128 v[146:149], v170 offset:35392
	v_exp_f32_e32 v184, v184
	v_add_f32_e32 v108, v183, v108
	v_cvt_pk_bf16_f32 v167, v182, v183
	v_exp_f32_e32 v185, v185
	s_waitcnt lgkmcnt(9)
	v_mfma_f32_32x32x16_bf16 v[0:15], v[142:145], v[158:161], v[0:15]
	ds_read_b128 v[142:145], v170 offset:26720
	v_add_f32_e32 v108, v184, v108
	v_exp_f32_e32 v186, v186
	v_add_f32_e32 v108, v185, v108
	v_cvt_pk_bf16_f32 v168, v184, v185
	s_waitcnt lgkmcnt(9)
	v_mfma_f32_32x32x16_bf16 v[16:31], v[150:153], v[158:161], v[16:31]
	ds_read_b128 v[150:153], v170 offset:35424
	v_exp_f32_e32 v187, v187
	v_add_f32_e32 v108, v186, v108
	v_add_f32_e32 v108, v187, v108
	v_cvt_pk_bf16_f32 v169, v186, v187
	s_waitcnt lgkmcnt(9)
	v_mfma_f32_32x32x16_bf16 v[172:187], v[110:113], v[48:51], 0
	ds_read_b128 v[110:113], v109 offset:0
	v_exp_f32_e32 v32, v32
	v_exp_f32_e32 v33, v33
	v_add_f32_e32 v108, v32, v108
	v_exp_f32_e32 v34, v34
	s_waitcnt lgkmcnt(9)
	v_mfma_f32_32x32x16_bf16 v[172:187], v[114:117], v[52:55], v[172:187]
	ds_read_b128 v[114:117], v109 offset:32
	v_add_f32_e32 v108, v33, v108
	v_cvt_pk_bf16_f32 v154, v32, v33
	v_exp_f32_e32 v35, v35
	v_add_f32_e32 v108, v34, v108
	s_waitcnt lgkmcnt(9)
	v_mfma_f32_32x32x16_bf16 v[172:187], v[118:121], v[56:59], v[172:187]
	ds_read_b128 v[118:121], v109 offset:64
	v_exp_f32_e32 v36, v36
	v_add_f32_e32 v108, v35, v108
	v_cvt_pk_bf16_f32 v155, v34, v35
	v_exp_f32_e32 v37, v37
	s_waitcnt lgkmcnt(9)
	v_mfma_f32_32x32x16_bf16 v[172:187], v[122:125], v[60:63], v[172:187]
	ds_read_b128 v[122:125], v109 offset:96
	v_add_f32_e32 v108, v36, v108
	v_exp_f32_e32 v38, v38
	v_add_f32_e32 v108, v37, v108
	v_cvt_pk_bf16_f32 v156, v36, v37
	s_waitcnt lgkmcnt(9)
	v_mfma_f32_32x32x16_bf16 v[172:187], v[130:133], v[64:67], v[172:187]
	ds_read_b128 v[130:133], v109 offset:128
	v_exp_f32_e32 v39, v39
	v_add_f32_e32 v108, v38, v108
	v_exp_f32_e32 v40, v40
	v_add_f32_e32 v108, v39, v108
	s_waitcnt lgkmcnt(9)
	v_mfma_f32_32x32x16_bf16 v[172:187], v[134:137], v[68:71], v[172:187]
	ds_read_b128 v[134:137], v109 offset:160
	v_cvt_pk_bf16_f32 v157, v38, v39
	v_exp_f32_e32 v41, v41
	v_add_f32_e32 v108, v40, v108
	v_exp_f32_e32 v42, v42
	s_waitcnt lgkmcnt(9)
	v_mfma_f32_32x32x16_bf16 v[0:15], v[138:141], v[162:165], v[0:15]
	ds_read_b128 v[138:141], v170 offset:26752
	v_add_f32_e32 v108, v41, v108
	v_cvt_pk_bf16_f32 v158, v40, v41
	v_exp_f32_e32 v43, v43
	v_add_f32_e32 v108, v42, v108
	s_waitcnt lgkmcnt(9)
	v_mfma_f32_32x32x16_bf16 v[16:31], v[146:149], v[162:165], v[16:31]
	ds_read_b128 v[146:149], v170 offset:35456
	v_exp_f32_e32 v44, v44
	v_add_f32_e32 v108, v43, v108
	v_cvt_pk_bf16_f32 v159, v42, v43
	v_exp_f32_e32 v45, v45
	s_waitcnt lgkmcnt(9)
	v_mfma_f32_32x32x16_bf16 v[0:15], v[142:145], v[166:169], v[0:15]
	ds_read_b128 v[142:145], v170 offset:26784
	v_add_f32_e32 v108, v44, v108
	v_exp_f32_e32 v46, v46
	v_add_f32_e32 v108, v45, v108
	v_cvt_pk_bf16_f32 v160, v44, v45
	s_waitcnt lgkmcnt(9)
	v_mfma_f32_32x32x16_bf16 v[16:31], v[150:153], v[166:169], v[16:31]
	ds_read_b128 v[150:153], v170 offset:35488
	v_exp_f32_e32 v47, v47
	v_add_f32_e32 v108, v46, v108
	v_add_f32_e32 v108, v47, v108
	v_cvt_pk_bf16_f32 v161, v46, v47
	s_waitcnt lgkmcnt(9)
	v_mfma_f32_32x32x16_bf16 v[32:47], v[110:113], v[48:51], 0
	ds_read_b128 v[110:113], v109 offset:6656
	v_exp_f32_e32 v172, v172
	v_exp_f32_e32 v173, v173
	v_add_f32_e32 v108, v172, v108
	v_exp_f32_e32 v174, v174
	v_add_u32_e32 v188, s29, v104
	s_waitcnt vmcnt(4)
	ds_write_b128 v188, v[84:87]
	s_waitcnt lgkmcnt(10)
	v_mfma_f32_32x32x16_bf16 v[32:47], v[114:117], v[52:55], v[32:47]
	ds_read_b128 v[114:117], v109 offset:6688
	v_add_f32_e32 v108, v173, v108
	v_cvt_pk_bf16_f32 v162, v172, v173
	v_exp_f32_e32 v175, v175
	v_add_f32_e32 v108, v174, v108
	v_add_u32_e32 v189, s29, v105
	s_waitcnt vmcnt(3)
	ds_write_b128 v189, v[72:75]
	s_waitcnt lgkmcnt(11)
	v_mfma_f32_32x32x16_bf16 v[32:47], v[118:121], v[56:59], v[32:47]
	ds_read_b128 v[118:121], v109 offset:6720
	v_exp_f32_e32 v176, v176
	v_add_f32_e32 v108, v175, v108
	v_cvt_pk_bf16_f32 v163, v174, v175
	v_exp_f32_e32 v177, v177
	v_add_u32_e32 v190, s29, v106
	s_waitcnt vmcnt(2)
	ds_write_b128 v190, v[76:79]
	s_waitcnt lgkmcnt(12)
; #define KLOAD(kf_, base)                                                                       \
;   { _Pragma("unroll") for (int ks = 0; ks < NKS; ks++) kf_[ks] = *(const bf16x8*)((base) + kfo + ks * 32); }
; #define VLOAD(vf_, base)                                                                       \
;   { _Pragma("unroll") for (int q = 0; q < 4; q++) vf_[q] = *(const bf16x8*)((base) + vfo + (q >> 1) * 32 * VROW + (q & 1) * 32); }
; #define QKM(dst, kf_)                                                                          \
;   {                                                                                            \
;     _Pragma("unroll") for (int i = 0; i < 16; i++) dst[i] = 0.f;                               \
;     _Pragma("unroll") for (int ks = 0; ks < NKS; ks++) dst = MFMA(kf_[ks], qf[ks], dst);       \
;   }
; template <int DK>
; DI void attn_core(const bf16x8 (&qf)[DK / 16], const short* Kg, const short* VTg, size_t ldvt, int ntiles, char* smem,
;                   f32x16 (&O)[2], float& lsum) {
;     ...
;   const int kfo = pr * KROW + h * 16;
;   const int vfo = KT_BYTES + r * VROW + h * 16;
;   AGLOAD(0);
;   ASTORE(0);
;   AGLOAD(ntiles > 1 ? 1 : 0);
;   ASTORE(1);
;   __syncthreads();
;   f32x16 Sc;
;   {
;     bf16x8 kf[NKS];
;     KLOAD(kf, smem);
;     QKM(Sc, kf);
;   }
;   int sc = 0, sn = 1, sw = 2;
;   for (int t = 0; t < ntiles; t++) {
;     const int tn = t + 2 < ntiles ? t + 2 : ntiles - 1;
;     AGLOAD(tn);
;     const char* cur = smem + sc * ST;
;     const char* nxt = smem + sn * ST;
;     f32x16 Sn;
;     bf16x8 pa, pb, qa, qb;
;     bf16x8 kf[NKS], vf[4];
;     KLOAD(kf, cur + 32 * KROW);
;     SB();
;     SOFTMAX(Sc, pa, pb, l0);
;     SB();
;     QKM(Sn, kf);
;     SB();
;     KLOAD(kf, cur + 64 * KROW);
;     VLOAD(vf, cur);
;     SB();
;     SOFTMAX(Sn, qa, qb, l0);
;     SB();
;     QKM(Sc, kf);
;     PVM(vf, pa, pb);
;     SB();
;     KLOAD(kf, cur + 96 * KROW);
;     VLOAD(vf, cur + 64);
;     SB();
;     SOFTMAX(Sc, pa, pb, l0);
;     SB();
;     QKM(Sn, kf);
;     PVM(vf, qa, qb);
;     SB();
;     KLOAD(kf, nxt);
;     VLOAD(vf, cur + 128);
;     SB();
;     SOFTMAX(Sn, qa, qb, l0);
;     SB();
;     QKM(Sc, kf);
;     PVM(vf, pa, pb);
;     SB();
;     VLOAD(vf, cur + 192);
;     PVM(vf, qa, qb);
;     ASTORE(sw);
;     __syncthreads();
;     const int tmp = sc; sc = sn; sn = sw; sw = tmp;
;   }
	v_mfma_f32_32x32x16_bf16 v[32:47], v[122:125], v[60:63], v[32:47]
	ds_read_b128 v[122:125], v109 offset:6752
	v_add_f32_e32 v108, v176, v108
	v_exp_f32_e32 v178, v178
	v_add_f32_e32 v108, v177, v108
	v_cvt_pk_bf16_f32 v164, v176, v177
	v_add_u32_e32 v191, s29, v100
	s_waitcnt vmcnt(1)
	ds_write_b128 v191, v[80:83] offset:26624
	s_waitcnt lgkmcnt(13)
	v_mfma_f32_32x32x16_bf16 v[32:47], v[130:133], v[64:67], v[32:47]
	ds_read_b128 v[130:133], v109 offset:6784
	v_exp_f32_e32 v179, v179
	v_add_f32_e32 v108, v178, v108
	v_exp_f32_e32 v180, v180
	v_add_f32_e32 v108, v179, v108
	s_waitcnt vmcnt(0)
	ds_write_b128 v191, v[88:91] offset:35328
	s_waitcnt lgkmcnt(14)
	v_mfma_f32_32x32x16_bf16 v[32:47], v[134:137], v[68:71], v[32:47]
	ds_read_b128 v[134:137], v109 offset:6816
	v_cvt_pk_bf16_f32 v165, v178, v179
	v_exp_f32_e32 v181, v181
	v_add_f32_e32 v108, v180, v108
	v_exp_f32_e32 v182, v182
	s_waitcnt lgkmcnt(14)
	v_mfma_f32_32x32x16_bf16 v[0:15], v[138:141], v[154:157], v[0:15]
	ds_read_b128 v[138:141], v170 offset:26816
	v_add_f32_e32 v108, v181, v108
	v_cvt_pk_bf16_f32 v166, v180, v181
	v_exp_f32_e32 v183, v183
	v_add_f32_e32 v108, v182, v108
	s_waitcnt lgkmcnt(14)
	v_mfma_f32_32x32x16_bf16 v[16:31], v[146:149], v[154:157], v[16:31]
	ds_read_b128 v[146:149], v170 offset:35520
	v_exp_f32_e32 v184, v184
	v_add_f32_e32 v108, v183, v108
	v_cvt_pk_bf16_f32 v167, v182, v183
	v_exp_f32_e32 v185, v185
	s_waitcnt lgkmcnt(14)
	v_mfma_f32_32x32x16_bf16 v[0:15], v[142:145], v[158:161], v[0:15]
	ds_read_b128 v[142:145], v170 offset:26848
	v_add_f32_e32 v108, v184, v108
	v_exp_f32_e32 v186, v186
	v_add_f32_e32 v108, v185, v108
	v_cvt_pk_bf16_f32 v168, v184, v185
	s_waitcnt lgkmcnt(14)
	v_mfma_f32_32x32x16_bf16 v[16:31], v[150:153], v[158:161], v[16:31]
	ds_read_b128 v[150:153], v170 offset:35552
	v_exp_f32_e32 v187, v187
	v_add_f32_e32 v108, v186, v108
	v_add_f32_e32 v108, v187, v108
	v_cvt_pk_bf16_f32 v169, v186, v187
	s_add_i32 s21, s21, 1
	s_mov_b32 s30, s28
	s_mov_b32 s28, s22
	s_mov_b32 s22, s23
	s_mov_b32 s23, s30
	s_cmpk_lg_i32 s21, 0x80
	s_waitcnt lgkmcnt(5)
	s_barrier
	s_cbranch_scc1 .Lmla_prompt_loop
	s_waitcnt lgkmcnt(0)
	s_barrier
; DI int my_tid() { int t = threadIdx.x; asm volatile("" : "+v"(t)); return t; }
; DI float bf_lo(unsigned u) { return __uint_as_float(u << 16); }
; DI float bf_hi(unsigned u) { return __uint_as_float(u & 0xffff0000u); }
; DI void attn_store(const f32x16 (&O)[2], float lsum, int tok, int col0, const short* gate, short* o, char* smem) {
;   const int tid = my_tid(), lane = tid & 63, w = tid >> 6, r = lane & 31, h = lane >> 5;
;   float l = lsum + __shfl_xor(lsum, 32);
;   float inv = __builtin_amdgcn_rcpf(l);
;   float* pw = (float*)(smem + w * (32 * 68 * 4));
;   const int tokw = tok - r;
;   const int ch = lane & 7;
;   u32x4 gpre[4];
; #pragma unroll
;   for (int j = 0; j < 4; j++) gpre[j] = *(const u32x4*)(gate + (size_t)(tokw + j * 8 + (lane >> 3)) * 1024 + col0 + ch * 8);
; #pragma unroll
;   for (int dt = 0; dt < 2; dt++)
; #pragma unroll
;     for (int q = 0; q < 4; q++) {
;       f32x4 t = {O[dt][q * 4 + 0] * inv, O[dt][q * 4 + 1] * inv, O[dt][q * 4 + 2] * inv, O[dt][q * 4 + 3] * inv};
;       *(f32x4*)(pw + r * 68 + dt * 32 + 8 * q + 4 * h) = t;
;     }
;   asm volatile("s_waitcnt lgkmcnt(0)" ::: "memory");
; #pragma unroll
;   for (int j = 0; j < 4; j++) {
;     const int row = j * 8 + (lane >> 3);
;     const size_t g = (size_t)(tokw + row) * 1024 + col0 + ch * 8;
;     const u32x4 gv = gpre[j];
;     const f32x4 a = *(const f32x4*)(pw + row * 68 + ch * 8), c = *(const f32x4*)(pw + row * 68 + ch * 8 + 4);
;     u32x4 ov;
;     ov[0] = pack_bf16(a[0] * bf_lo(gv[0]), a[1] * bf_hi(gv[0]));
;     ov[1] = pack_bf16(a[2] * bf_lo(gv[1]), a[3] * bf_hi(gv[1]));
;     ov[2] = pack_bf16(c[0] * bf_lo(gv[2]), c[1] * bf_hi(gv[2]));
;     ov[3] = pack_bf16(c[2] * bf_lo(gv[3]), c[3] * bf_hi(gv[3]));
;     __builtin_nontemporal_store(ov, (u32x4*)(o + g));
;   }
;   __syncthreads();
; }
	v_mfma_f32_32x32x16_bf16 v[0:15], v[138:141], v[162:165], v[0:15]
	v_mfma_f32_32x32x16_bf16 v[16:31], v[146:149], v[162:165], v[16:31]
	v_mfma_f32_32x32x16_bf16 v[0:15], v[142:145], v[166:169], v[0:15]
	v_mfma_f32_32x32x16_bf16 v[16:31], v[150:153], v[166:169], v[16:31]
	s_nop 10
	ds_bpermute_b32 v33, v103, v108
	s_lshl_b32 s8, s16, 6
	v_mov_b32_e32 v57, v196
	s_ashr_i32 s9, s8, 31
	v_lshrrev_b32_e32 v32, 6, v57
	v_and_b32_e32 v58, 31, v57
	s_waitcnt lgkmcnt(0)
	v_add_f32_e32 v56, v108, v33
	v_mul_lo_u32 v59, v32, s38
	v_sub_u32_e32 v32, v102, v58
	v_bfe_u32 v60, v57, 3, 3
	s_lshl_b64 s[8:9], s[8:9], 1
	v_lshlrev_b32_e32 v33, 3, v57
	v_add_u32_e32 v32, v60, v32
	s_add_u32 s22, s14, s8
	v_and_b32_e32 v61, 56, v33
	s_addc_u32 s23, s15, s9
	v_lshlrev_b32_e32 v128, 1, v61
	v_ashrrev_i32_e32 v33, 31, v32
	v_lshl_add_u64 v[34:35], s[22:23], 0, v[128:129]
	v_lshlrev_b64 v[54:55], 11, v[32:33]
	v_lshl_add_u64 v[36:37], v[34:35], 0, v[54:55]
	global_load_dwordx4 v[44:47], v[36:37], off
	v_add_u32_e32 v36, 8, v32
	v_ashrrev_i32_e32 v37, 31, v36
	v_lshlrev_b64 v[52:53], 11, v[36:37]
	v_lshl_add_u64 v[36:37], v[34:35], 0, v[52:53]
	global_load_dwordx4 v[40:43], v[36:37], off
	v_add_u32_e32 v36, 16, v32
	v_ashrrev_i32_e32 v37, 31, v36
	v_lshlrev_b64 v[50:51], 11, v[36:37]
	v_lshl_add_u64 v[36:37], v[34:35], 0, v[50:51]
	global_load_dwordx4 v[36:39], v[36:37], off
	v_add_u32_e32 v32, 24, v32
	v_ashrrev_i32_e32 v33, 31, v32
	v_lshlrev_b64 v[48:49], 11, v[32:33]
	v_lshl_add_u64 v[32:33], v[34:35], 0, v[48:49]
	global_load_dwordx4 v[32:35], v[32:33], off
	v_rcp_f32_e32 v56, v56
	v_lshrrev_b32_e32 v57, 1, v57
	v_mul_u32_u24_e32 v58, 0x110, v58
	v_and_b32_e32 v57, 16, v57
	v_add3_u32 v57, v59, v58, v57
	v_pk_mul_f32 v[0:1], v[0:1], v[56:57] op_sel_hi:[1,0]
	v_pk_mul_f32 v[2:3], v[2:3], v[56:57] op_sel_hi:[1,0]
	ds_write_b128 v57, v[0:3]
	v_pk_mul_f32 v[0:1], v[4:5], v[56:57] op_sel_hi:[1,0]
	v_pk_mul_f32 v[2:3], v[6:7], v[56:57] op_sel_hi:[1,0]
	ds_write_b128 v57, v[0:3] offset:32
	v_pk_mul_f32 v[0:1], v[8:9], v[56:57] op_sel_hi:[1,0]
	v_pk_mul_f32 v[2:3], v[10:11], v[56:57] op_sel_hi:[1,0]
	ds_write_b128 v57, v[0:3] offset:64
	v_pk_mul_f32 v[0:1], v[12:13], v[56:57] op_sel_hi:[1,0]
	v_pk_mul_f32 v[2:3], v[14:15], v[56:57] op_sel_hi:[1,0]
	ds_write_b128 v57, v[0:3] offset:96
	v_pk_mul_f32 v[0:1], v[16:17], v[56:57] op_sel_hi:[1,0]
	v_pk_mul_f32 v[2:3], v[18:19], v[56:57] op_sel_hi:[1,0]
	ds_write_b128 v57, v[0:3] offset:128
	v_pk_mul_f32 v[0:1], v[20:21], v[56:57] op_sel_hi:[1,0]
	v_pk_mul_f32 v[2:3], v[22:23], v[56:57] op_sel_hi:[1,0]
	ds_write_b128 v57, v[0:3] offset:160
	v_pk_mul_f32 v[0:1], v[24:25], v[56:57] op_sel_hi:[1,0]
	v_pk_mul_f32 v[2:3], v[26:27], v[56:57] op_sel_hi:[1,0]
	ds_write_b128 v57, v[0:3] offset:192
	v_pk_mul_f32 v[0:1], v[28:29], v[56:57] op_sel_hi:[1,0]
	v_pk_mul_f32 v[2:3], v[30:31], v[56:57] op_sel_hi:[1,0]
	ds_write_b128 v57, v[0:3] offset:224
	v_lshl_or_b32 v2, v61, 2, v59
	s_movk_i32 s36, 0x110
	s_waitcnt lgkmcnt(0)
	v_mad_u32_u24 v12, v60, s36, v2
	ds_read_b128 v[2:5], v12
	ds_read_b128 v[6:9], v12 offset:16
	s_add_u32 s8, s18, s8
	s_addc_u32 s9, s19, s9
	v_lshl_add_u64 v[0:1], s[8:9], 0, v[128:129]
	v_readlane_b32 s8, v226, 12
	s_add_i32 s20, s20, s8
	s_cmpk_gt_i32 s20, 0x5f
	s_waitcnt vmcnt(3)
	v_lshlrev_b32_e32 v10, 16, v44
	v_and_b32_e32 v11, 0xffff0000, v44
	s_waitcnt lgkmcnt(1)
	v_pk_mul_f32 v[2:3], v[2:3], v[10:11]
	v_lshlrev_b32_e32 v10, 16, v45
	v_and_b32_e32 v11, 0xffff0000, v45
	v_pk_mul_f32 v[4:5], v[4:5], v[10:11]
	v_cvt_pk_bf16_f32 v2, v2, v3
	v_cvt_pk_bf16_f32 v3, v4, v5
	v_lshlrev_b32_e32 v4, 16, v46
	v_and_b32_e32 v5, 0xffff0000, v46
	s_waitcnt lgkmcnt(0)
	v_pk_mul_f32 v[4:5], v[6:7], v[4:5]
	v_lshlrev_b32_e32 v6, 16, v47
	v_and_b32_e32 v7, 0xffff0000, v47
	v_pk_mul_f32 v[6:7], v[8:9], v[6:7]
	v_cvt_pk_bf16_f32 v4, v4, v5
	v_cvt_pk_bf16_f32 v5, v6, v7
	v_lshl_add_u64 v[6:7], v[0:1], 0, v[54:55]
	global_store_dwordx4 v[6:7], v[2:5], off nt
	ds_read_b128 v[2:5], v12 offset:2176
	ds_read_b128 v[6:9], v12 offset:2192
	s_waitcnt vmcnt(3)
	v_lshlrev_b32_e32 v10, 16, v40
	v_and_b32_e32 v11, 0xffff0000, v40
	s_waitcnt lgkmcnt(1)
	v_pk_mul_f32 v[2:3], v[2:3], v[10:11]
	v_lshlrev_b32_e32 v10, 16, v41
	v_and_b32_e32 v11, 0xffff0000, v41
	v_pk_mul_f32 v[4:5], v[4:5], v[10:11]
	v_cvt_pk_bf16_f32 v2, v2, v3
	v_cvt_pk_bf16_f32 v3, v4, v5
	v_lshlrev_b32_e32 v4, 16, v42
	v_and_b32_e32 v5, 0xffff0000, v42
	s_waitcnt lgkmcnt(0)
	v_pk_mul_f32 v[4:5], v[6:7], v[4:5]
	v_lshlrev_b32_e32 v6, 16, v43
	v_and_b32_e32 v7, 0xffff0000, v43
	v_pk_mul_f32 v[6:7], v[8:9], v[6:7]
	v_cvt_pk_bf16_f32 v4, v4, v5
	v_cvt_pk_bf16_f32 v5, v6, v7
	v_lshl_add_u64 v[6:7], v[0:1], 0, v[52:53]
	global_store_dwordx4 v[6:7], v[2:5], off nt
	ds_read_b128 v[2:5], v12 offset:4352
	ds_read_b128 v[6:9], v12 offset:4368
	s_waitcnt vmcnt(3)
	v_lshlrev_b32_e32 v10, 16, v36
	v_and_b32_e32 v11, 0xffff0000, v36
	s_waitcnt lgkmcnt(1)
	v_pk_mul_f32 v[2:3], v[2:3], v[10:11]
	v_lshlrev_b32_e32 v10, 16, v37
	v_and_b32_e32 v11, 0xffff0000, v37
	v_pk_mul_f32 v[4:5], v[4:5], v[10:11]
	v_cvt_pk_bf16_f32 v2, v2, v3
	v_cvt_pk_bf16_f32 v3, v4, v5
	v_lshlrev_b32_e32 v4, 16, v38
	v_and_b32_e32 v5, 0xffff0000, v38
	s_waitcnt lgkmcnt(0)
	v_pk_mul_f32 v[4:5], v[6:7], v[4:5]
	v_lshlrev_b32_e32 v6, 16, v39
	v_and_b32_e32 v7, 0xffff0000, v39
	v_pk_mul_f32 v[6:7], v[8:9], v[6:7]
	v_cvt_pk_bf16_f32 v4, v4, v5
	v_cvt_pk_bf16_f32 v5, v6, v7
	v_lshl_add_u64 v[6:7], v[0:1], 0, v[50:51]
	global_store_dwordx4 v[6:7], v[2:5], off nt
	ds_read_b128 v[2:5], v12 offset:6528
	ds_read_b128 v[6:9], v12 offset:6544
	s_waitcnt vmcnt(3)
	v_lshlrev_b32_e32 v10, 16, v32
	v_and_b32_e32 v11, 0xffff0000, v32
	v_lshl_add_u64 v[0:1], v[0:1], 0, v[48:49]
	s_waitcnt lgkmcnt(1)
	v_pk_mul_f32 v[2:3], v[2:3], v[10:11]
	v_lshlrev_b32_e32 v10, 16, v33
	v_and_b32_e32 v11, 0xffff0000, v33
	v_pk_mul_f32 v[4:5], v[4:5], v[10:11]
	v_cvt_pk_bf16_f32 v2, v2, v3
	v_cvt_pk_bf16_f32 v3, v4, v5
	v_lshlrev_b32_e32 v4, 16, v34
	v_and_b32_e32 v5, 0xffff0000, v34
	s_waitcnt lgkmcnt(0)
	v_pk_mul_f32 v[4:5], v[6:7], v[4:5]
	v_lshlrev_b32_e32 v6, 16, v35
	v_and_b32_e32 v7, 0xffff0000, v35
	v_pk_mul_f32 v[6:7], v[8:9], v[6:7]
	v_cvt_pk_bf16_f32 v4, v4, v5
	v_cvt_pk_bf16_f32 v5, v6, v7
	global_store_dwordx4 v[0:1], v[2:5], off nt
	s_barrier
	s_cbranch_scc0 .LBB0_165

; DI int my_tid() { int t = threadIdx.x; asm volatile("" : "+v"(t)); return t; }
; DI float bf_lo(unsigned u) { return __uint_as_float(u << 16); }
; DI float bf_hi(unsigned u) { return __uint_as_float(u & 0xffff0000u); }
; DI float rsqrt_f(float x) { return __builtin_amdgcn_rsqf(x); }
; DI void mla_item(PRef p, int j, int seq, int head, int qb, char* smem) {
;   const int tid = my_tid(), lane = tid & 63, w = tid >> 6, r = lane & 31, h = lane >> 5;
;   const int s0 = seq == 0 ? 0 : TP + (seq - 1) * SS;
;   const int S = seq == 0 ? TP : SS;
;   const int pos = qb * 256 + w * 32 + r;
;   const int tok = s0 + pos;
;   const short* Q = (const short*)(p.ws + OFF_Q);
;   const float* gq = p.in[10] + j * 96;
;   float qv[6][8];
;   float ss = 0.f;
; #pragma unroll
;   for (int ks = 0; ks < 6; ks++) {
;     u32x4 t = *(const u32x4*)(Q + (size_t)tok * 1152 + head * 96 + ks * 16 + 8 * h);
; #pragma unroll
;     for (int e = 0; e < 4; e++) {
;       qv[ks][2 * e] = bf_lo(t[e]);
;       qv[ks][2 * e + 1] = bf_hi(t[e]);
;     }
; #pragma unroll
;     for (int e = 0; e < 8; e++) ss += qv[ks][e] * qv[ks][e];
;   }
;   ss += __shfl_xor(ss, 32);
;   const float f = rsqrt_f(ss * (1.f / 96.f) + EPS);
;   const float sc = 0.10206207261596575f * LOG2E;
; #pragma unroll
;   for (int ks = 0; ks < 6; ks++)
; #pragma unroll
;     for (int e = 0; e < 8; e++) qv[ks][e] *= f * gq[ks * 16 + 8 * h + e];
; #pragma unroll
;   for (int e = 0; e < 8; e++) {
;     float cs, sn;
;     rope_cs(pos, 8 * h + e, cs, sn);
;     float x1 = qv[4][e], x2 = qv[5][e];
;     qv[4][e] = x1 * cs - x2 * sn;
;     qv[5][e] = x1 * sn + x2 * cs;
;   }
; DI void run_phase(PRef p, int ph, char* smem, int noatom) {
;     ...
;         for (int li = l; li < 384; li += nl) {
;           const int u = xj + 8 * (li >> 4);
;           mla_item(p, j, 1 + u / 12, u % 12, li & 15, smem);
.LBB0_170:
	s_ashr_i32 s8, s22, 1
	s_and_b32 s8, s8, -8
	s_or_b32 s14, s8, s52
	s_mul_hi_i32 s8, s14, 0x2aaaaaab
	s_lshr_b32 s9, s8, 31
	s_ashr_i32 s8, s8, 1
	s_add_i32 s15, s8, s9
	s_waitcnt vmcnt(0)
	v_add_co_u32_e64 v0, s[8:9], s15, 1
	s_mul_i32 s15, s15, 12
	s_sub_i32 s16, s14, s15
	v_readfirstlane_b32 s14, v0
	s_lshl_b32 s14, s14, 12
	s_add_i32 s23, s14, 0x3000
	s_and_b64 s[14:15], s[8:9], exec
	v_mov_b32_e32 v6, v196
	s_cselect_b32 s14, 0, s23
	s_getpc_b64 s[28:29]
	s_add_u32 s28, s28, _ZL10ROPE_TURNS@rel32@lo+4
	s_addc_u32 s29, s29, _ZL10ROPE_TURNS@rel32@hi+12
	s_lshl_b32 s15, s22, 8
	v_lshrrev_b32_e32 v0, 2, v6
	v_ashrrev_i32_e32 v8, 1, v6
	v_and_b32_e32 v7, 8, v0
	v_and_b32_e32 v8, 0xffffffe0, v8
	s_and_b32 s15, s15, 0xf00
	v_lshlrev_b32_e32 v0, 3, v7
	v_add_u32_e32 v8, s15, v8
	global_load_dwordx4 v[30:33], v0, s[28:29]
	global_load_dwordx4 v[34:37], v0, s[28:29] offset:16
	global_load_dwordx4 v[38:41], v0, s[28:29] offset:32
	global_load_dwordx4 v[2:5], v0, s[28:29] offset:48
	v_and_or_b32 v6, v6, 31, v8
	v_mov_b64_e32 v[0:1], s[4:5]
	s_mul_i32 s28, s16, 0x60
	v_add_u32_e32 v102, s14, v6
	s_movk_i32 s15, 0x900
	s_ashr_i32 s29, s28, 31
	v_mad_i64_i32 v[0:1], s[34:35], v102, s15, v[0:1]
	s_waitcnt vmcnt(11)
	v_lshlrev_b32_e32 v128, 1, v7
	v_lshl_add_u64 v[0:1], s[28:29], 1, v[0:1]
	v_lshl_add_u64 v[0:1], v[0:1], 0, v[128:129]
	global_load_dwordx4 v[26:29], v[0:1], off offset:128
	global_load_dwordx4 v[22:25], v[0:1], off offset:160
	global_load_dwordx4 v[18:21], v[0:1], off offset:96
	v_and_b32_e32 v9, 64, v200
	v_xor_b32_e32 v8, 32, v200
	v_add_u32_e32 v9, 64, v9
	v_cmp_lt_i32_e32 vcc, v8, v9
	v_lshlrev_b32_e32 v128, 2, v7
	v_cvt_f64_i32_e32 v[42:43], v6
	v_cndmask_b32_e32 v8, v200, v8, vcc
	v_lshlrev_b32_e32 v103, 2, v8
	global_load_dwordx4 v[6:9], v[0:1], off
	global_load_dwordx4 v[10:13], v[0:1], off offset:32
	global_load_dwordx4 v[14:17], v[0:1], off offset:64
	s_and_b64 s[8:9], s[8:9], exec
	s_cselect_b32 s29, 0x80, 32
	s_mul_i32 s9, s16, 0x14000
	s_ashr_i32 s15, s14, 31
	s_mul_hi_i32 s8, s16, 0x14000
	s_add_u32 s9, s9, s14
	s_addc_u32 s8, s8, s15
	s_mulk_i32 s8, 0xc0
	s_mul_hi_u32 s30, s9, 0xc0
	s_add_i32 s30, s30, s8
	s_mulk_i32 s9, 0xc0
	s_add_u32 s8, s10, s9
	s_addc_u32 s9, s11, s30
	s_mul_i32 s35, s16, 0xa00000
	s_mul_hi_i32 s30, s16, 0xa00000
	s_add_u32 s35, s12, s35
	s_addc_u32 s30, s13, s30
	s_lshl_b64 s[14:15], s[14:15], 1
	s_add_u32 s14, s35, s14
	s_addc_u32 s15, s30, s15
	s_mov_b32 s39, 0x500000
	s_mov_b32 s30, 0x3e16c740
	s_mov_b32 s34, 1
	s_mov_b32 s23, 0
	s_mov_b32 s28, 2
	s_waitcnt vmcnt(9)
	v_mul_f64 v[0:1], v[30:31], v[42:43]
	v_mul_f64 v[44:45], v[32:33], v[42:43]
	v_floor_f64_e32 v[0:1], v[0:1]
	s_waitcnt vmcnt(6)
	v_mul_f64 v[54:55], v[2:3], v[42:43]
	v_floor_f64_e32 v[44:45], v[44:45]
	v_floor_f64_e32 v[54:55], v[54:55]
	v_fma_f64 v[0:1], v[30:31], v[42:43], -v[0:1]
	v_fma_f64 v[30:31], v[32:33], v[42:43], -v[44:45]
	v_fma_f64 v[2:3], v[2:3], v[42:43], -v[54:55]
	v_cvt_f32_f64_e32 v0, v[0:1]
	v_mul_f64 v[46:47], v[34:35], v[42:43]
	v_mul_f64 v[48:49], v[36:37], v[42:43]
	v_mul_f64 v[50:51], v[38:39], v[42:43]
	v_mul_f64 v[52:53], v[40:41], v[42:43]
	v_cvt_f32_f64_e32 v1, v[30:31]
	v_sin_f32_e32 v72, v0
	v_cos_f32_e32 v64, v0
	v_cvt_f32_f64_e32 v0, v[2:3]
	v_floor_f64_e32 v[46:47], v[46:47]
	v_floor_f64_e32 v[48:49], v[48:49]
	v_floor_f64_e32 v[50:51], v[50:51]
	v_floor_f64_e32 v[52:53], v[52:53]
	v_sin_f32_e32 v73, v1
	v_cos_f32_e32 v65, v1
	v_sin_f32_e32 v70, v0
	v_cos_f32_e32 v68, v0
	v_mul_f64 v[0:1], v[4:5], v[42:43]
	v_fma_f64 v[32:33], v[34:35], v[42:43], -v[46:47]
	v_fma_f64 v[34:35], v[36:37], v[42:43], -v[48:49]
	v_fma_f64 v[36:37], v[38:39], v[42:43], -v[50:51]
	v_fma_f64 v[38:39], v[40:41], v[42:43], -v[52:53]
	v_floor_f64_e32 v[44:45], v[0:1]
	global_load_dwordx4 v[0:3], v128, s[6:7] offset:256
	s_waitcnt vmcnt(4)
	v_lshlrev_b32_e32 v104, 16, v21
	v_and_b32_e32 v105, 0xffff0000, v21
	global_load_dwordx4 v[82:85], v128, s[6:7] offset:208
	global_load_dwordx4 v[86:89], v128, s[6:7] offset:192
	v_lshlrev_b32_e32 v108, 16, v20
	v_and_b32_e32 v109, 0xffff0000, v20
	v_lshlrev_b32_e32 v112, 16, v19
	v_and_b32_e32 v113, 0xffff0000, v19
	v_lshlrev_b32_e32 v116, 16, v18
	v_and_b32_e32 v117, 0xffff0000, v18
	global_load_dwordx4 v[18:21], v128, s[6:7] offset:144
	global_load_dwordx4 v[78:81], v128, s[6:7] offset:128
	global_load_dwordx4 v[60:63], v128, s[6:7] offset:80
	global_load_dwordx4 v[56:59], v128, s[6:7] offset:64
	global_load_dwordx4 v[50:53], v128, s[6:7]
	global_load_dwordx4 v[90:93], v128, s[6:7] offset:16
	s_waitcnt vmcnt(11)
	v_lshlrev_b32_e32 v156, 16, v6
	v_and_b32_e32 v157, 0xffff0000, v6
	v_lshlrev_b32_e32 v152, 16, v7
	v_and_b32_e32 v153, 0xffff0000, v7
	v_pk_mul_f32 v[6:7], v[156:157], v[156:157]
	v_pk_mul_f32 v[154:155], v[152:153], v[152:153]
	v_add_f32_e32 v6, v6, v7
	v_lshlrev_b32_e32 v150, 16, v8
	v_and_b32_e32 v151, 0xffff0000, v8
	v_add_f32_e32 v6, v154, v6
	v_lshlrev_b32_e32 v146, 16, v9
	v_and_b32_e32 v147, 0xffff0000, v9
	v_pk_mul_f32 v[8:9], v[150:151], v[150:151]
	v_add_f32_e32 v6, v155, v6
	v_add_f32_e32 v6, v8, v6
	v_pk_mul_f32 v[148:149], v[146:147], v[146:147]
	v_add_f32_e32 v6, v9, v6
	s_waitcnt vmcnt(10)
	v_lshlrev_b32_e32 v144, 16, v10
	v_and_b32_e32 v145, 0xffff0000, v10
	v_add_f32_e32 v6, v148, v6
	v_lshlrev_b32_e32 v140, 16, v11
	v_and_b32_e32 v141, 0xffff0000, v11
	v_pk_mul_f32 v[10:11], v[144:145], v[144:145]
	v_add_f32_e32 v6, v149, v6
	v_add_f32_e32 v6, v10, v6
	v_pk_mul_f32 v[142:143], v[140:141], v[140:141]
	v_add_f32_e32 v6, v11, v6
	v_lshlrev_b32_e32 v138, 16, v12
	v_and_b32_e32 v139, 0xffff0000, v12
	v_add_f32_e32 v6, v142, v6
	v_lshlrev_b32_e32 v134, 16, v13
	v_and_b32_e32 v135, 0xffff0000, v13
	v_pk_mul_f32 v[12:13], v[138:139], v[138:139]
	v_add_f32_e32 v6, v143, v6
	v_add_f32_e32 v6, v12, v6
	v_pk_mul_f32 v[136:137], v[134:135], v[134:135]
	v_add_f32_e32 v6, v13, v6
	s_waitcnt vmcnt(9)
; DI float rsqrt_f(float x) { return __builtin_amdgcn_rsqf(x); }
; template <int DK>
; DI void attn_core(const bf16x8 (&qf)[DK / 16], const short* Kg, const short* VTg, size_t ldvt, int ntiles, char* smem,
;                   f32x16 (&O)[2], float& lsum) {
;     ...
;   for (int i = 0; i < NKC; i++) { int c = tid + 512 * i; koff[i] = (c / KCH) * KROW + (c % KCH) * 16; }
;   const int vrow = tid >> 4, vcol = tid & 15;
;   const short* vg = VTg + (size_t)vrow * ldvt + vcol * 8;
;   const int voff = KT_BYTES + vrow * VROW + vcol * 16;
; #pragma unroll
;   for (int i = 0; i < 16; i++) { O[0][i] = 0.f; O[1][i] = 0.f; }
;   float l0 = 0.f;
; DI void mla_item(PRef p, int j, int seq, int head, int qb, char* smem) {
;     ...
;     for (int e = 0; e < 8; e++) ss += qv[ks][e] * qv[ks][e];
;   }
;   ss += __shfl_xor(ss, 32);
;   const float f = rsqrt_f(ss * (1.f / 96.f) + EPS);
;   const float sc = 0.10206207261596575f * LOG2E;
; #pragma unroll
;   for (int ks = 0; ks < 6; ks++)
; #pragma unroll
;     for (int e = 0; e < 8; e++) qv[ks][e] *= f * gq[ks * 16 + 8 * h + e];
	v_lshlrev_b32_e32 v132, 16, v14
	v_and_b32_e32 v133, 0xffff0000, v14
	v_add_f32_e32 v6, v136, v6
	v_lshlrev_b32_e32 v126, 16, v15
	v_and_b32_e32 v127, 0xffff0000, v15
	v_pk_mul_f32 v[14:15], v[132:133], v[132:133]
	v_add_f32_e32 v6, v137, v6
	v_add_f32_e32 v6, v14, v6
	v_pk_mul_f32 v[130:131], v[126:127], v[126:127]
	v_add_f32_e32 v6, v15, v6
	v_lshlrev_b32_e32 v124, 16, v16
	v_and_b32_e32 v125, 0xffff0000, v16
	v_add_f32_e32 v6, v130, v6
	v_lshlrev_b32_e32 v120, 16, v17
	v_and_b32_e32 v121, 0xffff0000, v17
	v_pk_mul_f32 v[16:17], v[124:125], v[124:125]
	v_add_f32_e32 v6, v131, v6
	v_add_f32_e32 v6, v16, v6
	v_pk_mul_f32 v[122:123], v[120:121], v[120:121]
	v_add_f32_e32 v6, v17, v6
	v_add_f32_e32 v6, v122, v6
	v_pk_mul_f32 v[118:119], v[116:117], v[116:117]
	v_add_f32_e32 v6, v123, v6
	v_add_f32_e32 v6, v118, v6
	v_pk_mul_f32 v[114:115], v[112:113], v[112:113]
	v_add_f32_e32 v6, v119, v6
	v_add_f32_e32 v6, v114, v6
	v_pk_mul_f32 v[110:111], v[108:109], v[108:109]
	v_add_f32_e32 v6, v115, v6
	v_add_f32_e32 v6, v110, v6
	v_pk_mul_f32 v[106:107], v[104:105], v[104:105]
	v_add_f32_e32 v6, v111, v6
	v_lshlrev_b32_e32 v40, 16, v26
	v_and_b32_e32 v41, 0xffff0000, v26
	v_add_f32_e32 v6, v106, v6
	v_pk_mul_f32 v[100:101], v[40:41], v[40:41]
	v_add_f32_e32 v6, v107, v6
	v_cvt_f32_f64_e32 v30, v[32:33]
	v_cvt_f32_f64_e32 v33, v[38:39]
	v_lshlrev_b32_e32 v38, 16, v27
	v_and_b32_e32 v39, 0xffff0000, v27
	v_add_f32_e32 v6, v100, v6
	v_pk_mul_f32 v[96:97], v[38:39], v[38:39]
	v_add_f32_e32 v6, v101, v6
	v_cvt_f32_f64_e32 v32, v[36:37]
	v_lshlrev_b32_e32 v36, 16, v28
	v_and_b32_e32 v37, 0xffff0000, v28
	v_add_f32_e32 v6, v96, v6
	v_pk_mul_f32 v[54:55], v[36:37], v[36:37]
	v_add_f32_e32 v6, v97, v6
	v_cvt_f32_f64_e32 v31, v[34:35]
	v_lshlrev_b32_e32 v34, 16, v29
	v_and_b32_e32 v35, 0xffff0000, v29
	v_add_f32_e32 v6, v54, v6
	v_pk_mul_f32 v[46:47], v[34:35], v[34:35]
	v_add_f32_e32 v6, v55, v6
	v_lshlrev_b32_e32 v26, 16, v22
	v_and_b32_e32 v27, 0xffff0000, v22
	v_add_f32_e32 v6, v46, v6
	v_sin_f32_e32 v76, v30
	v_cos_f32_e32 v74, v30
	v_sin_f32_e32 v77, v31
	v_cos_f32_e32 v75, v31
	v_sin_f32_e32 v66, v32
	v_cos_f32_e32 v30, v32
	v_sin_f32_e32 v67, v33
	v_cos_f32_e32 v31, v33
	v_lshlrev_b32_e32 v32, 16, v25
	v_and_b32_e32 v33, 0xffff0000, v25
	v_lshlrev_b32_e32 v28, 16, v24
	v_and_b32_e32 v29, 0xffff0000, v24
	v_lshlrev_b32_e32 v24, 16, v23
	v_and_b32_e32 v25, 0xffff0000, v23
	v_pk_mul_f32 v[22:23], v[26:27], v[26:27]
	v_add_f32_e32 v6, v47, v6
	v_add_f32_e32 v6, v22, v6
	v_pk_mul_f32 v[98:99], v[24:25], v[24:25]
	v_add_f32_e32 v6, v23, v6
	v_add_f32_e32 v6, v98, v6
	v_pk_mul_f32 v[94:95], v[28:29], v[28:29]
	v_add_f32_e32 v6, v99, v6
	v_add_f32_e32 v6, v94, v6
	v_pk_mul_f32 v[48:49], v[32:33], v[32:33]
	v_add_f32_e32 v6, v95, v6
	v_add_f32_e32 v6, v48, v6
	v_add_f32_e32 v6, v49, v6
	ds_bpermute_b32 v7, v103, v6
	v_fma_f64 v[4:5], v[4:5], v[42:43], -v[44:45]
	v_cvt_f32_f64_e32 v4, v[4:5]
	v_sin_f32_e32 v71, v4
	v_cos_f32_e32 v69, v4
	s_waitcnt lgkmcnt(0)
	v_add_f32_e32 v4, v6, v7
	v_fmamk_f32 v4, v4, 0x3c2aaaab, v198
	v_rsq_f32_e32 v48, v4
	global_load_dwordx4 v[12:15], v128, s[6:7] offset:272
	global_load_dwordx4 v[4:7], v128, s[6:7] offset:336
	global_load_dwordx4 v[8:11], v128, s[6:7] offset:320
	s_waitcnt vmcnt(4)
	v_pk_mul_f32 v[16:17], v[50:51], v[48:49] op_sel_hi:[1,0]
	s_nop 0
	v_pk_mul_f32 v[46:47], v[16:17], v[156:157]
	v_pk_mul_f32 v[16:17], v[52:53], v[48:49] op_sel_hi:[1,0]
	v_pk_mul_f32 v[0:1], v[0:1], v[48:49] op_sel_hi:[1,0]
	v_pk_mul_f32 v[50:51], v[16:17], v[152:153]
	s_waitcnt vmcnt(3)
	v_pk_mul_f32 v[16:17], v[90:91], v[48:49] op_sel_hi:[1,0]
	s_nop 0
	v_pk_mul_f32 v[52:53], v[16:17], v[150:151]
	v_pk_mul_f32 v[16:17], v[92:93], v[48:49] op_sel_hi:[1,0]
	v_mov_b32_e32 v150, v196
	v_pk_mul_f32 v[54:55], v[16:17], v[146:147]
	v_pk_mul_f32 v[16:17], v[56:57], v[48:49] op_sel_hi:[1,0]
	s_nop 0
	v_pk_mul_f32 v[56:57], v[16:17], v[144:145]
	v_pk_mul_f32 v[16:17], v[58:59], v[48:49] op_sel_hi:[1,0]
	v_ashrrev_i32_e32 v151, 4, v150
	v_pk_mul_f32 v[58:59], v[16:17], v[140:141]
	v_pk_mul_f32 v[16:17], v[60:61], v[48:49] op_sel_hi:[1,0]
	v_lshlrev_b32_e32 v92, 3, v150
	v_pk_mul_f32 v[60:61], v[16:17], v[138:139]
	v_pk_mul_f32 v[16:17], v[62:63], v[48:49] op_sel_hi:[1,0]
	v_add_u32_e32 v96, 0x2000, v92
	v_pk_mul_f32 v[62:63], v[16:17], v[134:135]
	v_pk_mul_f32 v[16:17], v[78:79], v[48:49] op_sel_hi:[1,0]
	v_ashrrev_i32_e32 v93, 31, v92
	v_pk_mul_f32 v[78:79], v[16:17], v[132:133]
	v_pk_mul_f32 v[16:17], v[80:81], v[48:49] op_sel_hi:[1,0]
	v_ashrrev_i32_e32 v97, 31, v96
	v_pk_mul_f32 v[80:81], v[16:17], v[126:127]
	v_pk_mul_f32 v[16:17], v[18:19], v[48:49] op_sel_hi:[1,0]
	v_pk_mul_f32 v[18:19], v[82:83], v[48:49] op_sel_hi:[1,0]
	v_mov_b64_e32 v[82:83], s[14:15]
	s_mov_b32 s14, 0x28000
	v_pk_mul_f32 v[22:23], v[16:17], v[124:125]
	v_pk_mul_f32 v[16:17], v[20:21], v[48:49] op_sel_hi:[1,0]
	v_mad_i64_i32 v[90:91], s[14:15], v151, s14, v[82:83]
	v_pk_mul_f32 v[42:43], v[16:17], v[120:121]
	v_pk_mul_f32 v[16:17], v[86:87], v[48:49] op_sel_hi:[1,0]
	s_add_u32 s14, s8, 0x6000
	v_pk_mul_f32 v[44:45], v[16:17], v[116:117]
	v_pk_mul_f32 v[16:17], v[88:89], v[48:49] op_sel_hi:[1,0]
	v_pk_mul_f32 v[20:21], v[84:85], v[48:49] op_sel_hi:[1,0]
	v_lshlrev_b32_e32 v49, 4, v150
	v_lshlrev_b64 v[100:101], 1, v[92:93]
	v_add_u32_e32 v94, 0x1000, v92
	v_lshlrev_b64 v[106:107], 1, v[96:97]
	s_addc_u32 s15, s9, 0
	v_and_b32_e32 v128, 0xf0, v49
	v_lshl_add_u64 v[82:83], s[8:9], 0, v[100:101]
	v_ashrrev_i32_e32 v95, 31, v94
	v_lshl_add_u64 v[98:99], s[8:9], 0, v[106:107]
	v_lshl_add_u64 v[100:101], s[14:15], 0, v[100:101]
	v_pk_mul_f32 v[18:19], v[18:19], v[108:109]
	v_pk_mul_f32 v[20:21], v[20:21], v[104:105]
	v_lshlrev_b64 v[104:105], 1, v[94:95]
	global_load_dwordx4 v[108:111], v[98:99], off
	global_load_dwordx4 v[120:123], v[100:101], off
	v_lshl_add_u64 v[98:99], v[90:91], 0, v[128:129]
	v_add_co_u32_e32 v90, vcc, s39, v98
	v_lshl_add_u64 v[100:101], s[14:15], 0, v[104:105]
	v_lshl_add_u64 v[86:87], s[8:9], 0, v[104:105]
	v_addc_co_u32_e32 v91, vcc, 0, v99, vcc
	global_load_dwordx4 v[124:127], v[100:101], off
	v_lshl_add_u64 v[100:101], s[14:15], 0, v[106:107]
	v_pk_mul_f32 v[16:17], v[16:17], v[112:113]
	global_load_dwordx4 v[82:85], v[82:83], off
	s_movk_i32 s14, 0xd0
	global_load_dwordx4 v[86:89], v[86:87], off
	s_nop 0
	global_load_dwordx4 v[112:115], v[98:99], off
	global_load_dwordx4 v[116:119], v[90:91], off
	global_load_dwordx4 v[130:133], v[100:101], off
	global_load_dwordx4 v[134:137], v[98:99], off offset:256
	global_load_dwordx4 v[138:141], v[90:91], off offset:256
	v_pk_mul_f32 v[90:91], v[0:1], v[40:41]
	v_pk_mul_f32 v[0:1], v[2:3], v[48:49] op_sel_hi:[1,0]
	v_mul_hi_i32 v3, v150, s41
	v_pk_mul_f32 v[142:143], v[0:1], v[38:39]
	s_waitcnt vmcnt(12)
; #define KLOAD(kf_, base)                                                                       \
;   { _Pragma("unroll") for (int ks = 0; ks < NKS; ks++) kf_[ks] = *(const bf16x8*)((base) + kfo + ks * 32); }
; #define QKM(dst, kf_)                                                                          \
;   {                                                                                            \
;     _Pragma("unroll") for (int i = 0; i < 16; i++) dst[i] = 0.f;                               \
;     _Pragma("unroll") for (int ks = 0; ks < NKS; ks++) dst = MFMA(kf_[ks], qf[ks], dst);       \
;   }
; template <int DK>
; DI void attn_core(const bf16x8 (&qf)[DK / 16], const short* Kg, const short* VTg, size_t ldvt, int ntiles, char* smem,
;                   f32x16 (&O)[2], float& lsum) {
;     ...
;   const int kfo = pr * KROW + h * 16;
;   const int vfo = KT_BYTES + r * VROW + h * 16;
;   AGLOAD(0);
;   ASTORE(0);
;   AGLOAD(ntiles > 1 ? 1 : 0);
;   ASTORE(1);
;   __syncthreads();
;   f32x16 Sc;
;   {
;     bf16x8 kf[NKS];
;     KLOAD(kf, smem);
;     QKM(Sc, kf);
;   }
; DI void mla_item(PRef p, int j, int seq, int head, int qb, char* smem) {
;     ...
;   for (int e = 0; e < 8; e++) {
;     float cs, sn;
;     rope_cs(pos, 8 * h + e, cs, sn);
;     float x1 = qv[4][e], x2 = qv[5][e];
;     qv[4][e] = x1 * cs - x2 * sn;
;     qv[5][e] = x1 * sn + x2 * cs;
;   }
;   bf16x8 qf[6];
; #pragma unroll
;   for (int ks = 0; ks < 6; ks++) {
;     u32x4 t;
; #pragma unroll
;     for (int e = 0; e < 4; e++) t[e] = pack_bf16(qv[ks][2 * e] * sc, qv[ks][2 * e + 1] * sc);
;     qf[ks] = __builtin_bit_cast(bf16x8, t);
;   }
	v_pk_mul_f32 v[0:1], v[12:13], v[48:49] op_sel_hi:[1,0]
	s_nop 0
	v_pk_mul_f32 v[12:13], v[0:1], v[36:37]
	v_pk_mul_f32 v[0:1], v[14:15], v[48:49] op_sel_hi:[1,0]
	s_nop 0
	v_pk_mul_f32 v[14:15], v[0:1], v[34:35]
	s_waitcnt vmcnt(10)
	v_pk_mul_f32 v[0:1], v[8:9], v[48:49] op_sel_hi:[1,0]
	s_nop 0
	v_pk_mul_f32 v[8:9], v[0:1], v[26:27]
	v_pk_mul_f32 v[0:1], v[10:11], v[48:49] op_sel_hi:[1,0]
	s_nop 0
	v_pk_mul_f32 v[10:11], v[0:1], v[24:25]
	v_pk_mul_f32 v[0:1], v[4:5], v[48:49] op_sel_hi:[1,0]
	v_pk_mul_f32 v[4:5], v[80:81], s[30:31] op_sel_hi:[1,0]
	v_pk_mul_f32 v[24:25], v[0:1], v[28:29]
	v_pk_mul_f32 v[0:1], v[6:7], v[48:49] op_sel_hi:[1,0]
	v_lshrrev_b32_e32 v6, 31, v3
	v_pk_mul_f32 v[26:27], v[0:1], v[32:33]
	v_pk_mul_f32 v[0:1], v[8:9], v[64:65]
	v_lshrrev_b32_e32 v3, 1, v3
	v_pk_fma_f32 v[28:29], v[90:91], v[72:73], v[0:1]
	v_pk_mul_f32 v[0:1], v[10:11], v[74:75]
	v_add_u32_e32 v3, v3, v6
	v_pk_fma_f32 v[144:145], v[142:143], v[76:77], v[0:1]
	v_pk_mul_f32 v[0:1], v[24:25], v[30:31]
	v_add_lshl_u32 v104, v3, v150, 4
	v_pk_fma_f32 v[146:147], v[12:13], v[66:67], v[0:1]
	v_pk_mul_f32 v[0:1], v[26:27], v[68:69]
	v_add_u32_e32 v3, 0x200, v150
	v_pk_fma_f32 v[148:149], v[14:15], v[70:71], v[0:1]
	v_pk_mul_f32 v[0:1], v[46:47], s[30:31] op_sel_hi:[1,0]
	v_mul_hi_i32 v6, v3, s41
	v_cvt_pk_bf16_f32 v48, v0, v1
	v_pk_mul_f32 v[0:1], v[50:51], s[30:31] op_sel_hi:[1,0]
	v_lshrrev_b32_e32 v7, 31, v6
	v_cvt_pk_bf16_f32 v49, v0, v1
	v_pk_mul_f32 v[0:1], v[52:53], s[30:31] op_sel_hi:[1,0]
	v_lshrrev_b32_e32 v6, 1, v6
	v_cvt_pk_bf16_f32 v50, v0, v1
	v_pk_mul_f32 v[0:1], v[54:55], s[30:31] op_sel_hi:[1,0]
	v_add_u32_e32 v6, v6, v7
	v_cvt_pk_bf16_f32 v51, v0, v1
	v_pk_mul_f32 v[0:1], v[56:57], s[30:31] op_sel_hi:[1,0]
	v_add_lshl_u32 v105, v6, v3, 4
	v_cvt_pk_bf16_f32 v52, v0, v1
	v_pk_mul_f32 v[0:1], v[58:59], s[30:31] op_sel_hi:[1,0]
	v_add_u32_e32 v3, 0x400, v150
	v_cvt_pk_bf16_f32 v53, v0, v1
	v_pk_mul_f32 v[0:1], v[60:61], s[30:31] op_sel_hi:[1,0]
	v_mul_hi_i32 v6, v3, s41
	v_cvt_pk_bf16_f32 v54, v0, v1
	v_pk_mul_f32 v[0:1], v[62:63], s[30:31] op_sel_hi:[1,0]
	v_lshrrev_b32_e32 v7, 31, v6
	v_cvt_pk_bf16_f32 v55, v0, v1
	v_pk_mul_f32 v[0:1], v[78:79], s[30:31] op_sel_hi:[1,0]
	v_lshrrev_b32_e32 v6, 1, v6
	v_cvt_pk_bf16_f32 v56, v0, v1
	v_lshlrev_b32_e32 v0, 1, v150
	v_lshrrev_b32_e32 v1, 1, v150
	v_add_u32_e32 v6, v6, v7
	v_and_b32_e32 v0, 8, v0
	v_and_b32_e32 v2, 4, v1
	v_add_lshl_u32 v106, v6, v3, 4
	v_and_b32_e32 v3, 19, v150
	v_and_b32_e32 v78, 16, v1
	v_or3_b32 v0, v3, v0, v2
	v_mad_u32_u24 v107, v0, s14, v78
	v_mad_u64_u32 v[100:101], s[14:15], v151, s36, v[128:129]
	v_add_u32_e32 v0, 0x6800, v100
	s_waitcnt vmcnt(6)
	ds_write_b128 v104, v[82:85]
	s_waitcnt vmcnt(5)
	ds_write_b128 v105, v[86:89]
	ds_write_b128 v106, v[108:111]
	s_waitcnt vmcnt(4)
	ds_write_b128 v100, v[112:115] offset:26624
	s_waitcnt vmcnt(3)
	ds_write_b128 v100, v[116:119] offset:35328
	ds_write_b128 v104, v[120:123] offset:44032
	ds_write_b128 v105, v[124:127] offset:44032
	s_waitcnt vmcnt(2)
	ds_write_b128 v106, v[130:133] offset:44032
	s_waitcnt vmcnt(1)
	ds_write_b128 v0, v[134:137] offset:44032
	s_waitcnt vmcnt(0)
	ds_write_b128 v0, v[138:141] offset:52736
	s_waitcnt lgkmcnt(0)
	s_barrier
	ds_read_b128 v[0:3], v107
	v_cvt_pk_bf16_f32 v57, v4, v5
	v_pk_mul_f32 v[4:5], v[22:23], s[30:31] op_sel_hi:[1,0]
	v_mov_b32_e32 v108, 0
	v_cvt_pk_bf16_f32 v58, v4, v5
	v_pk_mul_f32 v[4:5], v[42:43], s[30:31] op_sel_hi:[1,0]
	s_add_i32 s14, s29, -1
	v_cvt_pk_bf16_f32 v59, v4, v5
	v_pk_mul_f32 v[4:5], v[44:45], s[30:31] op_sel_hi:[1,0]
	s_mov_b32 s15, 0
	v_cvt_pk_bf16_f32 v60, v4, v5
	ds_read_b128 v[4:7], v107 offset:32
	s_waitcnt lgkmcnt(1)
	v_mfma_f32_32x32x16_bf16 v[32:47], v[0:3], v[48:51], 0
	v_mul_f32_e64 v0, v16, s30
	v_mul_f32_e64 v1, v17, s30
	v_mov_b32_e32 v16, 0
	v_cvt_pk_bf16_f32 v61, v0, v1
	v_mul_f32_e64 v0, v18, s30
	v_mul_f32_e64 v1, v19, s30
	v_mov_b32_e32 v17, v108
	v_cvt_pk_bf16_f32 v62, v0, v1
	v_pk_mul_f32 v[0:1], v[20:21], s[30:31] op_sel_hi:[1,0]
	s_waitcnt lgkmcnt(0)
	v_mfma_f32_32x32x16_bf16 v[32:47], v[4:7], v[52:55], v[32:47]
	v_cvt_pk_bf16_f32 v63, v0, v1
	ds_read_b128 v[0:3], v107 offset:64
	v_mul_f32_e64 v4, v8, v72
	v_mul_f32_e64 v5, v9, v73
	v_mov_b32_e32 v18, v108
	v_pk_fma_f32 v[4:5], v[90:91], v[64:65], v[4:5] neg_lo:[0,0,1] neg_hi:[0,0,1]
	v_mov_b32_e32 v19, v108
	v_pk_mul_f32 v[4:5], v[4:5], s[30:31] op_sel_hi:[1,0]
	v_mov_b32_e32 v20, v108
	v_cvt_pk_bf16_f32 v64, v4, v5
	v_pk_mul_f32 v[4:5], v[10:11], v[76:77]
	v_mov_b32_e32 v10, v108
	v_pk_fma_f32 v[8:9], v[142:143], v[74:75], v[4:5] neg_lo:[0,0,1] neg_hi:[0,0,1]
	ds_read_b128 v[4:7], v107 offset:96
	s_waitcnt lgkmcnt(1)
	v_mfma_f32_32x32x16_bf16 v[32:47], v[0:3], v[56:59], v[32:47]
	v_mul_f32_e64 v0, v8, s30
	v_mul_f32_e64 v1, v9, s30
	v_mov_b32_e32 v8, v108
	v_cvt_pk_bf16_f32 v65, v0, v1
	v_mul_f32_e64 v0, v24, v66
	v_mul_f32_e64 v1, v25, v67
	v_mov_b32_e32 v9, v108
	v_pk_fma_f32 v[0:1], v[12:13], v[30:31], v[0:1] neg_lo:[0,0,1] neg_hi:[0,0,1]
	v_mov_b32_e32 v11, v108
	v_pk_mul_f32 v[0:1], v[0:1], s[30:31] op_sel_hi:[1,0]
	s_waitcnt lgkmcnt(0)
	v_mfma_f32_32x32x16_bf16 v[32:47], v[4:7], v[60:63], v[32:47]
	v_cvt_pk_bf16_f32 v66, v0, v1
	ds_read_b128 v[0:3], v107 offset:128
	v_mul_f32_e64 v4, v26, v70
	v_mul_f32_e64 v5, v27, v71
	v_mov_b32_e32 v12, v108
	v_pk_fma_f32 v[4:5], v[14:15], v[68:69], v[4:5] neg_lo:[0,0,1] neg_hi:[0,0,1]
	v_mov_b32_e32 v13, v108
	v_pk_mul_f32 v[4:5], v[4:5], s[30:31] op_sel_hi:[1,0]
	v_mov_b32_e32 v14, v108
	v_cvt_pk_bf16_f32 v67, v4, v5
	v_pk_mul_f32 v[4:5], v[28:29], s[30:31] op_sel_hi:[1,0]
	v_mov_b32_e32 v15, v108
	v_cvt_pk_bf16_f32 v68, v4, v5
	ds_read_b128 v[4:7], v107 offset:160
	s_waitcnt lgkmcnt(1)
; #define KLOAD(kf_, base)                                                                       \
;   { _Pragma("unroll") for (int ks = 0; ks < NKS; ks++) kf_[ks] = *(const bf16x8*)((base) + kfo + ks * 32); }
; #define VLOAD(vf_, base)                                                                       \
;   { _Pragma("unroll") for (int q = 0; q < 4; q++) vf_[q] = *(const bf16x8*)((base) + vfo + (q >> 1) * 32 * VROW + (q & 1) * 32); }
; #define QKM(dst, kf_)                                                                          \
;   {                                                                                            \
;     _Pragma("unroll") for (int i = 0; i < 16; i++) dst[i] = 0.f;                               \
;     _Pragma("unroll") for (int ks = 0; ks < NKS; ks++) dst = MFMA(kf_[ks], qf[ks], dst);       \
;   }
; template <int DK>
; DI void attn_core(const bf16x8 (&qf)[DK / 16], const short* Kg, const short* VTg, size_t ldvt, int ntiles, char* smem,
;                   f32x16 (&O)[2], float& lsum) {
;     ...
;   const int kfo = pr * KROW + h * 16;
;   const int vfo = KT_BYTES + r * VROW + h * 16;
;   AGLOAD(0);
;   ASTORE(0);
;   AGLOAD(ntiles > 1 ? 1 : 0);
;   ASTORE(1);
;   __syncthreads();
;   f32x16 Sc;
;   {
;     bf16x8 kf[NKS];
;     KLOAD(kf, smem);
;     QKM(Sc, kf);
;   }
;   int sc = 0, sn = 1, sw = 2;
;   for (int t = 0; t < ntiles; t++) {
;     const int tn = t + 2 < ntiles ? t + 2 : ntiles - 1;
;     AGLOAD(tn);
;     const char* cur = smem + sc * ST;
;     const char* nxt = smem + sn * ST;
;     f32x16 Sn;
;     bf16x8 pa, pb, qa, qb;
;     bf16x8 kf[NKS], vf[4];
;     KLOAD(kf, cur + 32 * KROW);
;     SB();
;     SOFTMAX(Sc, pa, pb, l0);
;     SB();
;     QKM(Sn, kf);
;     SB();
;     KLOAD(kf, cur + 64 * KROW);
;     VLOAD(vf, cur);
;     SB();
;     SOFTMAX(Sn, qa, qb, l0);
;     SB();
;     QKM(Sc, kf);
;     PVM(vf, pa, pb);
;     SB();
;     KLOAD(kf, cur + 96 * KROW);
;     VLOAD(vf, cur + 64);
;     SB();
;     SOFTMAX(Sc, pa, pb, l0);
;     SB();
;     QKM(Sn, kf);
;     PVM(vf, qa, qb);
;     SB();
;     KLOAD(kf, nxt);
;     VLOAD(vf, cur + 128);
;     SB();
;     SOFTMAX(Sn, qa, qb, l0);
;     SB();
;     QKM(Sc, kf);
;     PVM(vf, pa, pb);
;     SB();
;     VLOAD(vf, cur + 192);
;     PVM(vf, qa, qb);
;     ASTORE(sw);
;     __syncthreads();
;     const int tmp = sc; sc = sn; sn = sw; sw = tmp;
;   }
	v_mfma_f32_32x32x16_bf16 v[32:47], v[0:3], v[64:67], v[32:47]
	v_mul_f32_e64 v0, v144, s30
	v_mul_f32_e64 v1, v145, s30
	v_mov_b32_e32 v2, v108
	v_cvt_pk_bf16_f32 v69, v0, v1
	v_mul_f32_e64 v0, v146, s30
	v_mul_f32_e64 v1, v147, s30
	v_mov_b32_e32 v3, v108
	v_cvt_pk_bf16_f32 v70, v0, v1
	v_pk_mul_f32 v[0:1], v[148:149], s[30:31] op_sel_hi:[1,0]
	v_mov_b32_e32 v21, v108
	v_cvt_pk_bf16_f32 v71, v0, v1
	v_and_b32_e32 v0, 31, v150
	v_mad_u32_u24 v101, v0, s36, v78
	s_waitcnt lgkmcnt(0)
	v_mfma_f32_32x32x16_bf16 v[32:47], v[4:7], v[68:71], v[32:47]
	v_mov_b32_e32 v0, 0
	v_mov_b32_e32 v1, v108
	v_mov_b32_e32 v4, v108
	v_mov_b32_e32 v5, v108
	v_mov_b32_e32 v6, v108
	v_mov_b32_e32 v7, v108
	v_mov_b32_e32 v22, v108
	v_mov_b32_e32 v23, v108
	v_mov_b32_e32 v24, v108
	v_mov_b32_e32 v25, v108
	v_mov_b32_e32 v26, v108
	v_mov_b32_e32 v27, v108
	v_mov_b32_e32 v28, v108
	v_mov_b32_e32 v29, v108
	v_mov_b32_e32 v30, v108
	v_mov_b32_e32 v31, v108
	v_mov_b32_e32 v162, 0
	v_mov_b32_e32 v163, 0
	v_mov_b32_e32 v164, 0
	v_mov_b32_e32 v165, 0
	v_mov_b32_e32 v166, 0
	v_mov_b32_e32 v167, 0
	v_mov_b32_e32 v168, 0
	v_mov_b32_e32 v169, 0
	v_mov_b32_e32 v138, 0
	v_mov_b32_e32 v139, 0
	v_mov_b32_e32 v140, 0
	v_mov_b32_e32 v141, 0
	v_mov_b32_e32 v142, 0
	v_mov_b32_e32 v143, 0
	v_mov_b32_e32 v144, 0
	v_mov_b32_e32 v145, 0
	v_mov_b32_e32 v146, 0
	v_mov_b32_e32 v147, 0
	v_mov_b32_e32 v148, 0
	v_mov_b32_e32 v149, 0
	v_mov_b32_e32 v150, 0
	v_mov_b32_e32 v151, 0
	v_mov_b32_e32 v152, 0
	v_mov_b32_e32 v153, 0
	ds_read_b128 v[110:113], v107 offset:6656
	ds_read_b128 v[114:117], v107 offset:6688
	ds_read_b128 v[118:121], v107 offset:6720
	ds_read_b128 v[122:125], v107 offset:6752
	ds_read_b128 v[130:133], v107 offset:6784
	ds_read_b128 v[134:137], v107 offset:6816
	s_waitcnt lgkmcnt(0)
.Lmla_sample_loop:
	s_add_i32 s35, s23, 2
	s_min_u32 s35, s35, s14
	s_mul_i32 s36, s35, 0x6000
	s_mul_hi_u32 s37, s35, 0x6000
	s_add_u32 s36, s8, s36
	s_addc_u32 s37, s9, s37
	s_lshl_b32 s30, s35, 8
	s_mul_i32 s35, s15, 0xac00
	v_add_u32_e32 v128, s35, v107
	v_add_u32_e32 v170, s35, v101
	s_mul_i32 s35, s34, 0xac00
	v_add_u32_e32 v109, s35, v107
	s_waitcnt lgkmcnt(14)
	v_mfma_f32_32x32x16_bf16 v[172:187], v[110:113], v[48:51], 0
	ds_read_b128 v[110:113], v128 offset:13312
	v_exp_f32_e32 v32, v32
	v_exp_f32_e32 v33, v33
	v_add_f32_e32 v108, v32, v108
	v_exp_f32_e32 v34, v34
	v_lshl_add_u64 v[188:189], v[92:93], 1, s[36:37]
	global_load_dwordx4 v[84:87], v[188:189], off
	s_waitcnt lgkmcnt(13)
	v_mfma_f32_32x32x16_bf16 v[172:187], v[114:117], v[52:55], v[172:187]
	ds_read_b128 v[114:117], v128 offset:13344
	v_add_f32_e32 v108, v33, v108
	v_cvt_pk_bf16_f32 v154, v32, v33
	v_exp_f32_e32 v35, v35
	v_add_f32_e32 v108, v34, v108
	v_lshl_add_u64 v[190:191], v[94:95], 1, s[36:37]
	global_load_dwordx4 v[72:75], v[190:191], off
	s_waitcnt lgkmcnt(12)
	v_mfma_f32_32x32x16_bf16 v[172:187], v[118:121], v[56:59], v[172:187]
	ds_read_b128 v[118:121], v128 offset:13376
	v_exp_f32_e32 v36, v36
	v_add_f32_e32 v108, v35, v108
	v_cvt_pk_bf16_f32 v155, v34, v35
	v_exp_f32_e32 v37, v37
	v_lshl_add_u64 v[192:193], v[96:97], 1, s[36:37]
	global_load_dwordx4 v[76:79], v[192:193], off
	s_waitcnt lgkmcnt(11)
	v_mfma_f32_32x32x16_bf16 v[172:187], v[122:125], v[60:63], v[172:187]
	ds_read_b128 v[122:125], v128 offset:13408
	v_add_f32_e32 v108, v36, v108
	v_exp_f32_e32 v38, v38
	v_add_f32_e32 v108, v37, v108
	v_cvt_pk_bf16_f32 v156, v36, v37
	v_lshl_add_u64 v[188:189], v[98:99], 0, s[30:31]
	global_load_dwordx4 v[80:83], v[188:189], off
	s_add_u32 s30, s30, s39
	s_waitcnt lgkmcnt(10)
	v_mfma_f32_32x32x16_bf16 v[172:187], v[130:133], v[64:67], v[172:187]
	ds_read_b128 v[130:133], v128 offset:13440
	v_exp_f32_e32 v39, v39
	v_add_f32_e32 v108, v38, v108
	v_exp_f32_e32 v40, v40
	v_add_f32_e32 v108, v39, v108
	v_lshl_add_u64 v[190:191], v[98:99], 0, s[30:31]
	global_load_dwordx4 v[88:91], v[190:191], off
	s_mul_i32 s35, s28, 0xac00
	s_waitcnt lgkmcnt(9)
	v_mfma_f32_32x32x16_bf16 v[172:187], v[134:137], v[68:71], v[172:187]
	ds_read_b128 v[134:137], v128 offset:13472
	v_cvt_pk_bf16_f32 v157, v38, v39
	v_exp_f32_e32 v41, v41
	v_add_f32_e32 v108, v40, v108
	v_exp_f32_e32 v42, v42
	s_waitcnt lgkmcnt(9)
	v_mfma_f32_32x32x16_bf16 v[0:15], v[138:141], v[162:165], v[0:15]
	ds_read_b128 v[138:141], v170 offset:26624
	v_add_f32_e32 v108, v41, v108
	v_cvt_pk_bf16_f32 v158, v40, v41
	v_exp_f32_e32 v43, v43
	v_add_f32_e32 v108, v42, v108
	s_waitcnt lgkmcnt(9)
	v_mfma_f32_32x32x16_bf16 v[16:31], v[146:149], v[162:165], v[16:31]
	ds_read_b128 v[146:149], v170 offset:35328
	v_exp_f32_e32 v44, v44
	v_add_f32_e32 v108, v43, v108
	v_cvt_pk_bf16_f32 v159, v42, v43
	v_exp_f32_e32 v45, v45
	s_waitcnt lgkmcnt(9)
	v_mfma_f32_32x32x16_bf16 v[0:15], v[142:145], v[166:169], v[0:15]
	ds_read_b128 v[142:145], v170 offset:26656
	v_add_f32_e32 v108, v44, v108
	v_exp_f32_e32 v46, v46
	v_add_f32_e32 v108, v45, v108
	v_cvt_pk_bf16_f32 v160, v44, v45
	s_waitcnt lgkmcnt(9)
	v_mfma_f32_32x32x16_bf16 v[16:31], v[150:153], v[166:169], v[16:31]
	ds_read_b128 v[150:153], v170 offset:35360
	v_exp_f32_e32 v47, v47
	v_add_f32_e32 v108, v46, v108
	v_add_f32_e32 v108, v47, v108
	v_cvt_pk_bf16_f32 v161, v46, v47
	s_waitcnt lgkmcnt(9)
	v_mfma_f32_32x32x16_bf16 v[32:47], v[110:113], v[48:51], 0
	ds_read_b128 v[110:113], v128 offset:19968
	v_exp_f32_e32 v172, v172
	v_exp_f32_e32 v173, v173
	v_add_f32_e32 v108, v172, v108
	v_exp_f32_e32 v174, v174
	s_waitcnt lgkmcnt(9)
	v_mfma_f32_32x32x16_bf16 v[32:47], v[114:117], v[52:55], v[32:47]
	ds_read_b128 v[114:117], v128 offset:20000
	v_add_f32_e32 v108, v173, v108
	v_cvt_pk_bf16_f32 v162, v172, v173
	v_exp_f32_e32 v175, v175
	v_add_f32_e32 v108, v174, v108
	s_waitcnt lgkmcnt(9)
; #define KLOAD(kf_, base)                                                                       \
;   { _Pragma("unroll") for (int ks = 0; ks < NKS; ks++) kf_[ks] = *(const bf16x8*)((base) + kfo + ks * 32); }
; #define VLOAD(vf_, base)                                                                       \
;   { _Pragma("unroll") for (int q = 0; q < 4; q++) vf_[q] = *(const bf16x8*)((base) + vfo + (q >> 1) * 32 * VROW + (q & 1) * 32); }
; #define QKM(dst, kf_)                                                                          \
;   {                                                                                            \
;     _Pragma("unroll") for (int i = 0; i < 16; i++) dst[i] = 0.f;                               \
;     _Pragma("unroll") for (int ks = 0; ks < NKS; ks++) dst = MFMA(kf_[ks], qf[ks], dst);       \
;   }
; template <int DK>
; DI void attn_core(const bf16x8 (&qf)[DK / 16], const short* Kg, const short* VTg, size_t ldvt, int ntiles, char* smem,
;                   f32x16 (&O)[2], float& lsum) {
;     ...
;   const int kfo = pr * KROW + h * 16;
;   const int vfo = KT_BYTES + r * VROW + h * 16;
;   AGLOAD(0);
;   ASTORE(0);
;   AGLOAD(ntiles > 1 ? 1 : 0);
;   ASTORE(1);
;   __syncthreads();
;   f32x16 Sc;
;   {
;     bf16x8 kf[NKS];
;     KLOAD(kf, smem);
;     QKM(Sc, kf);
;   }
;   int sc = 0, sn = 1, sw = 2;
;   for (int t = 0; t < ntiles; t++) {
;     const int tn = t + 2 < ntiles ? t + 2 : ntiles - 1;
;     AGLOAD(tn);
;     const char* cur = smem + sc * ST;
;     const char* nxt = smem + sn * ST;
;     f32x16 Sn;
;     bf16x8 pa, pb, qa, qb;
;     bf16x8 kf[NKS], vf[4];
;     KLOAD(kf, cur + 32 * KROW);
;     SB();
;     SOFTMAX(Sc, pa, pb, l0);
;     SB();
;     QKM(Sn, kf);
;     SB();
;     KLOAD(kf, cur + 64 * KROW);
;     VLOAD(vf, cur);
;     SB();
;     SOFTMAX(Sn, qa, qb, l0);
;     SB();
;     QKM(Sc, kf);
;     PVM(vf, pa, pb);
;     SB();
;     KLOAD(kf, cur + 96 * KROW);
;     VLOAD(vf, cur + 64);
;     SB();
;     SOFTMAX(Sc, pa, pb, l0);
;     SB();
;     QKM(Sn, kf);
;     PVM(vf, qa, qb);
;     SB();
;     KLOAD(kf, nxt);
;     VLOAD(vf, cur + 128);
;     SB();
;     SOFTMAX(Sn, qa, qb, l0);
;     SB();
;     QKM(Sc, kf);
;     PVM(vf, pa, pb);
;     SB();
;     VLOAD(vf, cur + 192);
;     PVM(vf, qa, qb);
;     ASTORE(sw);
;     __syncthreads();
;     const int tmp = sc; sc = sn; sn = sw; sw = tmp;
;   }
	v_mfma_f32_32x32x16_bf16 v[32:47], v[118:121], v[56:59], v[32:47]
	ds_read_b128 v[118:121], v128 offset:20032
	v_exp_f32_e32 v176, v176
	v_add_f32_e32 v108, v175, v108
	v_cvt_pk_bf16_f32 v163, v174, v175
	v_exp_f32_e32 v177, v177
	s_waitcnt lgkmcnt(9)
	v_mfma_f32_32x32x16_bf16 v[32:47], v[122:125], v[60:63], v[32:47]
	ds_read_b128 v[122:125], v128 offset:20064
	v_add_f32_e32 v108, v176, v108
	v_exp_f32_e32 v178, v178
	v_add_f32_e32 v108, v177, v108
	v_cvt_pk_bf16_f32 v164, v176, v177
	s_waitcnt lgkmcnt(9)
	v_mfma_f32_32x32x16_bf16 v[32:47], v[130:133], v[64:67], v[32:47]
	ds_read_b128 v[130:133], v128 offset:20096
	v_exp_f32_e32 v179, v179
	v_add_f32_e32 v108, v178, v108
	v_exp_f32_e32 v180, v180
	v_add_f32_e32 v108, v179, v108
	s_waitcnt lgkmcnt(9)
	v_mfma_f32_32x32x16_bf16 v[32:47], v[134:137], v[68:71], v[32:47]
	ds_read_b128 v[134:137], v128 offset:20128
	v_cvt_pk_bf16_f32 v165, v178, v179
	v_exp_f32_e32 v181, v181
	v_add_f32_e32 v108, v180, v108
	v_exp_f32_e32 v182, v182
	s_waitcnt lgkmcnt(9)
	v_mfma_f32_32x32x16_bf16 v[0:15], v[138:141], v[154:157], v[0:15]
	ds_read_b128 v[138:141], v170 offset:26688
	v_add_f32_e32 v108, v181, v108
	v_cvt_pk_bf16_f32 v166, v180, v181
	v_exp_f32_e32 v183, v183
	v_add_f32_e32 v108, v182, v108
	s_waitcnt lgkmcnt(9)
	v_mfma_f32_32x32x16_bf16 v[16:31], v[146:149], v[154:157], v[16:31]
	ds_read_b128 v[146:149], v170 offset:35392
	v_exp_f32_e32 v184, v184
	v_add_f32_e32 v108, v183, v108
	v_cvt_pk_bf16_f32 v167, v182, v183
	v_exp_f32_e32 v185, v185
	s_waitcnt lgkmcnt(9)
	v_mfma_f32_32x32x16_bf16 v[0:15], v[142:145], v[158:161], v[0:15]
	ds_read_b128 v[142:145], v170 offset:26720
	v_add_f32_e32 v108, v184, v108
	v_exp_f32_e32 v186, v186
	v_add_f32_e32 v108, v185, v108
	v_cvt_pk_bf16_f32 v168, v184, v185
	s_waitcnt lgkmcnt(9)
	v_mfma_f32_32x32x16_bf16 v[16:31], v[150:153], v[158:161], v[16:31]
	ds_read_b128 v[150:153], v170 offset:35424
	v_exp_f32_e32 v187, v187
	v_add_f32_e32 v108, v186, v108
	v_add_f32_e32 v108, v187, v108
	v_cvt_pk_bf16_f32 v169, v186, v187
	s_waitcnt lgkmcnt(9)
	v_mfma_f32_32x32x16_bf16 v[172:187], v[110:113], v[48:51], 0
	ds_read_b128 v[110:113], v109 offset:0
	v_exp_f32_e32 v32, v32
	v_exp_f32_e32 v33, v33
	v_add_f32_e32 v108, v32, v108
	v_exp_f32_e32 v34, v34
	s_waitcnt lgkmcnt(9)
	v_mfma_f32_32x32x16_bf16 v[172:187], v[114:117], v[52:55], v[172:187]
	ds_read_b128 v[114:117], v109 offset:32
	v_add_f32_e32 v108, v33, v108
	v_cvt_pk_bf16_f32 v154, v32, v33
	v_exp_f32_e32 v35, v35
	v_add_f32_e32 v108, v34, v108
	s_waitcnt lgkmcnt(9)
	v_mfma_f32_32x32x16_bf16 v[172:187], v[118:121], v[56:59], v[172:187]
	ds_read_b128 v[118:121], v109 offset:64
	v_exp_f32_e32 v36, v36
	v_add_f32_e32 v108, v35, v108
	v_cvt_pk_bf16_f32 v155, v34, v35
	v_exp_f32_e32 v37, v37
	s_waitcnt lgkmcnt(9)
	v_mfma_f32_32x32x16_bf16 v[172:187], v[122:125], v[60:63], v[172:187]
	ds_read_b128 v[122:125], v109 offset:96
	v_add_f32_e32 v108, v36, v108
	v_exp_f32_e32 v38, v38
	v_add_f32_e32 v108, v37, v108
	v_cvt_pk_bf16_f32 v156, v36, v37
	s_waitcnt lgkmcnt(9)
	v_mfma_f32_32x32x16_bf16 v[172:187], v[130:133], v[64:67], v[172:187]
	ds_read_b128 v[130:133], v109 offset:128
	v_exp_f32_e32 v39, v39
	v_add_f32_e32 v108, v38, v108
	v_exp_f32_e32 v40, v40
	v_add_f32_e32 v108, v39, v108
	s_waitcnt lgkmcnt(9)
	v_mfma_f32_32x32x16_bf16 v[172:187], v[134:137], v[68:71], v[172:187]
	ds_read_b128 v[134:137], v109 offset:160
	v_cvt_pk_bf16_f32 v157, v38, v39
	v_exp_f32_e32 v41, v41
	v_add_f32_e32 v108, v40, v108
	v_exp_f32_e32 v42, v42
	s_waitcnt lgkmcnt(9)
	v_mfma_f32_32x32x16_bf16 v[0:15], v[138:141], v[162:165], v[0:15]
	ds_read_b128 v[138:141], v170 offset:26752
	v_add_f32_e32 v108, v41, v108
	v_cvt_pk_bf16_f32 v158, v40, v41
	v_exp_f32_e32 v43, v43
	v_add_f32_e32 v108, v42, v108
	s_waitcnt lgkmcnt(9)
	v_mfma_f32_32x32x16_bf16 v[16:31], v[146:149], v[162:165], v[16:31]
	ds_read_b128 v[146:149], v170 offset:35456
	v_exp_f32_e32 v44, v44
	v_add_f32_e32 v108, v43, v108
	v_cvt_pk_bf16_f32 v159, v42, v43
	v_exp_f32_e32 v45, v45
	s_waitcnt lgkmcnt(9)
	v_mfma_f32_32x32x16_bf16 v[0:15], v[142:145], v[166:169], v[0:15]
	ds_read_b128 v[142:145], v170 offset:26784
	v_add_f32_e32 v108, v44, v108
	v_exp_f32_e32 v46, v46
	v_add_f32_e32 v108, v45, v108
	v_cvt_pk_bf16_f32 v160, v44, v45
	s_waitcnt lgkmcnt(9)
	v_mfma_f32_32x32x16_bf16 v[16:31], v[150:153], v[166:169], v[16:31]
	ds_read_b128 v[150:153], v170 offset:35488
	v_exp_f32_e32 v47, v47
	v_add_f32_e32 v108, v46, v108
	v_add_f32_e32 v108, v47, v108
	v_cvt_pk_bf16_f32 v161, v46, v47
	s_waitcnt lgkmcnt(9)
	v_mfma_f32_32x32x16_bf16 v[32:47], v[110:113], v[48:51], 0
	ds_read_b128 v[110:113], v109 offset:6656
	v_exp_f32_e32 v172, v172
	v_exp_f32_e32 v173, v173
	v_add_f32_e32 v108, v172, v108
	v_exp_f32_e32 v174, v174
	v_add_u32_e32 v188, s35, v104
	s_waitcnt vmcnt(4)
	ds_write_b128 v188, v[84:87]
	s_waitcnt lgkmcnt(10)
	v_mfma_f32_32x32x16_bf16 v[32:47], v[114:117], v[52:55], v[32:47]
	ds_read_b128 v[114:117], v109 offset:6688
	v_add_f32_e32 v108, v173, v108
	v_cvt_pk_bf16_f32 v162, v172, v173
	v_exp_f32_e32 v175, v175
	v_add_f32_e32 v108, v174, v108
	v_add_u32_e32 v189, s35, v105
	s_waitcnt vmcnt(3)
	ds_write_b128 v189, v[72:75]
	s_waitcnt lgkmcnt(11)
	v_mfma_f32_32x32x16_bf16 v[32:47], v[118:121], v[56:59], v[32:47]
	ds_read_b128 v[118:121], v109 offset:6720
	v_exp_f32_e32 v176, v176
	v_add_f32_e32 v108, v175, v108
	v_cvt_pk_bf16_f32 v163, v174, v175
	v_exp_f32_e32 v177, v177
	v_add_u32_e32 v190, s35, v106
	s_waitcnt vmcnt(2)
	ds_write_b128 v190, v[76:79]
	s_waitcnt lgkmcnt(12)
; #define KLOAD(kf_, base)                                                                       \
;   { _Pragma("unroll") for (int ks = 0; ks < NKS; ks++) kf_[ks] = *(const bf16x8*)((base) + kfo + ks * 32); }
; #define VLOAD(vf_, base)                                                                       \
;   { _Pragma("unroll") for (int q = 0; q < 4; q++) vf_[q] = *(const bf16x8*)((base) + vfo + (q >> 1) * 32 * VROW + (q & 1) * 32); }
; #define QKM(dst, kf_)                                                                          \
;   {                                                                                            \
;     _Pragma("unroll") for (int i = 0; i < 16; i++) dst[i] = 0.f;                               \
;     _Pragma("unroll") for (int ks = 0; ks < NKS; ks++) dst = MFMA(kf_[ks], qf[ks], dst);       \
;   }
; template <int DK>
; DI void attn_core(const bf16x8 (&qf)[DK / 16], const short* Kg, const short* VTg, size_t ldvt, int ntiles, char* smem,
;                   f32x16 (&O)[2], float& lsum) {
;     ...
;   const int kfo = pr * KROW + h * 16;
;   const int vfo = KT_BYTES + r * VROW + h * 16;
;   AGLOAD(0);
;   ASTORE(0);
;   AGLOAD(ntiles > 1 ? 1 : 0);
;   ASTORE(1);
;   __syncthreads();
;   f32x16 Sc;
;   {
;     bf16x8 kf[NKS];
;     KLOAD(kf, smem);
;     QKM(Sc, kf);
;   }
;   int sc = 0, sn = 1, sw = 2;
;   for (int t = 0; t < ntiles; t++) {
;     const int tn = t + 2 < ntiles ? t + 2 : ntiles - 1;
;     AGLOAD(tn);
;     const char* cur = smem + sc * ST;
;     const char* nxt = smem + sn * ST;
;     f32x16 Sn;
;     bf16x8 pa, pb, qa, qb;
;     bf16x8 kf[NKS], vf[4];
;     KLOAD(kf, cur + 32 * KROW);
;     SB();
;     SOFTMAX(Sc, pa, pb, l0);
;     SB();
;     QKM(Sn, kf);
;     SB();
;     KLOAD(kf, cur + 64 * KROW);
;     VLOAD(vf, cur);
;     SB();
;     SOFTMAX(Sn, qa, qb, l0);
;     SB();
;     QKM(Sc, kf);
;     PVM(vf, pa, pb);
;     SB();
;     KLOAD(kf, cur + 96 * KROW);
;     VLOAD(vf, cur + 64);
;     SB();
;     SOFTMAX(Sc, pa, pb, l0);
;     SB();
;     QKM(Sn, kf);
;     PVM(vf, qa, qb);
;     SB();
;     KLOAD(kf, nxt);
;     VLOAD(vf, cur + 128);
;     SB();
;     SOFTMAX(Sn, qa, qb, l0);
;     SB();
;     QKM(Sc, kf);
;     PVM(vf, pa, pb);
;     SB();
;     VLOAD(vf, cur + 192);
;     PVM(vf, qa, qb);
;     ASTORE(sw);
;     __syncthreads();
;     const int tmp = sc; sc = sn; sn = sw; sw = tmp;
;   }
	v_mfma_f32_32x32x16_bf16 v[32:47], v[122:125], v[60:63], v[32:47]
	ds_read_b128 v[122:125], v109 offset:6752
	v_add_f32_e32 v108, v176, v108
	v_exp_f32_e32 v178, v178
	v_add_f32_e32 v108, v177, v108
	v_cvt_pk_bf16_f32 v164, v176, v177
	v_add_u32_e32 v191, s35, v100
	s_waitcnt vmcnt(1)
	ds_write_b128 v191, v[80:83] offset:26624
	s_waitcnt lgkmcnt(13)
	v_mfma_f32_32x32x16_bf16 v[32:47], v[130:133], v[64:67], v[32:47]
	ds_read_b128 v[130:133], v109 offset:6784
	v_exp_f32_e32 v179, v179
	v_add_f32_e32 v108, v178, v108
	v_exp_f32_e32 v180, v180
	v_add_f32_e32 v108, v179, v108
	s_waitcnt vmcnt(0)
	ds_write_b128 v191, v[88:91] offset:35328
	s_waitcnt lgkmcnt(14)
	v_mfma_f32_32x32x16_bf16 v[32:47], v[134:137], v[68:71], v[32:47]
	ds_read_b128 v[134:137], v109 offset:6816
	v_cvt_pk_bf16_f32 v165, v178, v179
	v_exp_f32_e32 v181, v181
	v_add_f32_e32 v108, v180, v108
	v_exp_f32_e32 v182, v182
	s_waitcnt lgkmcnt(14)
	v_mfma_f32_32x32x16_bf16 v[0:15], v[138:141], v[154:157], v[0:15]
	ds_read_b128 v[138:141], v170 offset:26816
	v_add_f32_e32 v108, v181, v108
	v_cvt_pk_bf16_f32 v166, v180, v181
	v_exp_f32_e32 v183, v183
	v_add_f32_e32 v108, v182, v108
	s_waitcnt lgkmcnt(14)
	v_mfma_f32_32x32x16_bf16 v[16:31], v[146:149], v[154:157], v[16:31]
	ds_read_b128 v[146:149], v170 offset:35520
	v_exp_f32_e32 v184, v184
	v_add_f32_e32 v108, v183, v108
	v_cvt_pk_bf16_f32 v167, v182, v183
	v_exp_f32_e32 v185, v185
	s_waitcnt lgkmcnt(14)
	v_mfma_f32_32x32x16_bf16 v[0:15], v[142:145], v[158:161], v[0:15]
	ds_read_b128 v[142:145], v170 offset:26848
	v_add_f32_e32 v108, v184, v108
	v_exp_f32_e32 v186, v186
	v_add_f32_e32 v108, v185, v108
	v_cvt_pk_bf16_f32 v168, v184, v185
	s_waitcnt lgkmcnt(14)
	v_mfma_f32_32x32x16_bf16 v[16:31], v[150:153], v[158:161], v[16:31]
	ds_read_b128 v[150:153], v170 offset:35552
	v_exp_f32_e32 v187, v187
	v_add_f32_e32 v108, v186, v108
	v_add_f32_e32 v108, v187, v108
	v_cvt_pk_bf16_f32 v169, v186, v187
	s_add_i32 s23, s23, 1
	s_mov_b32 s30, s15
	s_mov_b32 s15, s34
	s_mov_b32 s34, s28
	s_mov_b32 s28, s30
	s_cmp_lg_u32 s29, s23
	s_waitcnt lgkmcnt(5)
	s_barrier
	s_cbranch_scc1 .Lmla_sample_loop
	s_waitcnt lgkmcnt(0)
	s_barrier
; DI int my_tid() { int t = threadIdx.x; asm volatile("" : "+v"(t)); return t; }
; DI float bf_lo(unsigned u) { return __uint_as_float(u << 16); }
; DI float bf_hi(unsigned u) { return __uint_as_float(u & 0xffff0000u); }
; DI void attn_store(const f32x16 (&O)[2], float lsum, int tok, int col0, const short* gate, short* o, char* smem) {
;   const int tid = my_tid(), lane = tid & 63, w = tid >> 6, r = lane & 31, h = lane >> 5;
;   float l = lsum + __shfl_xor(lsum, 32);
;   float inv = __builtin_amdgcn_rcpf(l);
;   float* pw = (float*)(smem + w * (32 * 68 * 4));
;   const int tokw = tok - r;
;   const int ch = lane & 7;
;   u32x4 gpre[4];
; #pragma unroll
;   for (int j = 0; j < 4; j++) gpre[j] = *(const u32x4*)(gate + (size_t)(tokw + j * 8 + (lane >> 3)) * 1024 + col0 + ch * 8);
; #pragma unroll
;   for (int dt = 0; dt < 2; dt++)
; #pragma unroll
;     for (int q = 0; q < 4; q++) {
;       f32x4 t = {O[dt][q * 4 + 0] * inv, O[dt][q * 4 + 1] * inv, O[dt][q * 4 + 2] * inv, O[dt][q * 4 + 3] * inv};
;       *(f32x4*)(pw + r * 68 + dt * 32 + 8 * q + 4 * h) = t;
;     }
;   asm volatile("s_waitcnt lgkmcnt(0)" ::: "memory");
; #pragma unroll
;   for (int j = 0; j < 4; j++) {
;     const int row = j * 8 + (lane >> 3);
;     const size_t g = (size_t)(tokw + row) * 1024 + col0 + ch * 8;
;     const u32x4 gv = gpre[j];
;     const f32x4 a = *(const f32x4*)(pw + row * 68 + ch * 8), c = *(const f32x4*)(pw + row * 68 + ch * 8 + 4);
;     u32x4 ov;
;     ov[0] = pack_bf16(a[0] * bf_lo(gv[0]), a[1] * bf_hi(gv[0]));
;     ov[1] = pack_bf16(a[2] * bf_lo(gv[1]), a[3] * bf_hi(gv[1]));
;     ov[2] = pack_bf16(c[0] * bf_lo(gv[2]), c[1] * bf_hi(gv[2]));
;     ov[3] = pack_bf16(c[2] * bf_lo(gv[3]), c[3] * bf_hi(gv[3]));
;     __builtin_nontemporal_store(ov, (u32x4*)(o + g));
;   }
;   __syncthreads();
; }
	v_mfma_f32_32x32x16_bf16 v[0:15], v[138:141], v[162:165], v[0:15]
	v_mfma_f32_32x32x16_bf16 v[16:31], v[146:149], v[162:165], v[16:31]
	v_mfma_f32_32x32x16_bf16 v[0:15], v[142:145], v[166:169], v[0:15]
	v_mfma_f32_32x32x16_bf16 v[16:31], v[150:153], v[166:169], v[16:31]
	s_nop 10
	ds_bpermute_b32 v33, v103, v108
	s_lshl_b32 s8, s16, 6
	v_mov_b32_e32 v57, v196
	s_ashr_i32 s9, s8, 31
	v_lshrrev_b32_e32 v32, 6, v57
	v_and_b32_e32 v58, 31, v57
	s_waitcnt lgkmcnt(0)
	v_add_f32_e32 v56, v108, v33
	v_mul_lo_u32 v59, v32, s38
	v_sub_u32_e32 v32, v102, v58
	v_bfe_u32 v60, v57, 3, 3
	s_lshl_b64 s[8:9], s[8:9], 1
	v_lshlrev_b32_e32 v33, 3, v57
	v_add_u32_e32 v32, v60, v32
	s_add_u32 s14, s18, s8
	v_and_b32_e32 v61, 56, v33
	s_addc_u32 s15, s19, s9
	v_lshlrev_b32_e32 v128, 1, v61
	v_ashrrev_i32_e32 v33, 31, v32
	v_lshl_add_u64 v[34:35], s[14:15], 0, v[128:129]
	v_lshlrev_b64 v[54:55], 11, v[32:33]
	v_lshl_add_u64 v[36:37], v[34:35], 0, v[54:55]
	global_load_dwordx4 v[44:47], v[36:37], off
	v_add_u32_e32 v36, 8, v32
	v_ashrrev_i32_e32 v37, 31, v36
	v_lshlrev_b64 v[52:53], 11, v[36:37]
	v_lshl_add_u64 v[36:37], v[34:35], 0, v[52:53]
	global_load_dwordx4 v[40:43], v[36:37], off
	v_add_u32_e32 v36, 16, v32
	v_ashrrev_i32_e32 v37, 31, v36
	v_lshlrev_b64 v[50:51], 11, v[36:37]
	v_lshl_add_u64 v[36:37], v[34:35], 0, v[50:51]
	global_load_dwordx4 v[36:39], v[36:37], off
	v_add_u32_e32 v32, 24, v32
	v_ashrrev_i32_e32 v33, 31, v32
	v_lshlrev_b64 v[48:49], 11, v[32:33]
	v_lshl_add_u64 v[32:33], v[34:35], 0, v[48:49]
	global_load_dwordx4 v[32:35], v[32:33], off
	v_rcp_f32_e32 v56, v56
	v_lshrrev_b32_e32 v57, 1, v57
	v_mul_u32_u24_e32 v58, 0x110, v58
	v_and_b32_e32 v57, 16, v57
	v_add3_u32 v57, v59, v58, v57
	v_pk_mul_f32 v[0:1], v[0:1], v[56:57] op_sel_hi:[1,0]
	v_pk_mul_f32 v[2:3], v[2:3], v[56:57] op_sel_hi:[1,0]
	ds_write_b128 v57, v[0:3]
	v_pk_mul_f32 v[0:1], v[4:5], v[56:57] op_sel_hi:[1,0]
	v_pk_mul_f32 v[2:3], v[6:7], v[56:57] op_sel_hi:[1,0]
	ds_write_b128 v57, v[0:3] offset:32
	v_pk_mul_f32 v[0:1], v[8:9], v[56:57] op_sel_hi:[1,0]
	v_pk_mul_f32 v[2:3], v[10:11], v[56:57] op_sel_hi:[1,0]
	ds_write_b128 v57, v[0:3] offset:64
	v_pk_mul_f32 v[0:1], v[12:13], v[56:57] op_sel_hi:[1,0]
	v_pk_mul_f32 v[2:3], v[14:15], v[56:57] op_sel_hi:[1,0]
	ds_write_b128 v57, v[0:3] offset:96
	v_pk_mul_f32 v[0:1], v[16:17], v[56:57] op_sel_hi:[1,0]
	v_pk_mul_f32 v[2:3], v[18:19], v[56:57] op_sel_hi:[1,0]
	ds_write_b128 v57, v[0:3] offset:128
	v_pk_mul_f32 v[0:1], v[20:21], v[56:57] op_sel_hi:[1,0]
	v_pk_mul_f32 v[2:3], v[22:23], v[56:57] op_sel_hi:[1,0]
	ds_write_b128 v57, v[0:3] offset:160
	v_pk_mul_f32 v[0:1], v[24:25], v[56:57] op_sel_hi:[1,0]
	v_pk_mul_f32 v[2:3], v[26:27], v[56:57] op_sel_hi:[1,0]
	ds_write_b128 v57, v[0:3] offset:192
	v_pk_mul_f32 v[0:1], v[28:29], v[56:57] op_sel_hi:[1,0]
	v_pk_mul_f32 v[2:3], v[30:31], v[56:57] op_sel_hi:[1,0]
	ds_write_b128 v57, v[0:3] offset:224
	v_lshl_or_b32 v2, v61, 2, v59
	s_movk_i32 s36, 0x110
	s_waitcnt lgkmcnt(0)
	v_mad_u32_u24 v12, v60, s36, v2
	ds_read_b128 v[2:5], v12
	ds_read_b128 v[6:9], v12 offset:16
	s_add_u32 s8, s20, s8
	s_addc_u32 s9, s21, s9
	v_lshl_add_u64 v[0:1], s[8:9], 0, v[128:129]
	v_readlane_b32 s8, v226, 12
	s_add_i32 s22, s22, s8
	s_cmpk_gt_i32 s22, 0x17f
	s_waitcnt vmcnt(3)
	v_lshlrev_b32_e32 v10, 16, v44
	v_and_b32_e32 v11, 0xffff0000, v44
	s_waitcnt lgkmcnt(1)
	v_pk_mul_f32 v[2:3], v[2:3], v[10:11]
	v_lshlrev_b32_e32 v10, 16, v45
	v_and_b32_e32 v11, 0xffff0000, v45
	v_pk_mul_f32 v[4:5], v[4:5], v[10:11]
	v_cvt_pk_bf16_f32 v2, v2, v3
	v_cvt_pk_bf16_f32 v3, v4, v5
	v_lshlrev_b32_e32 v4, 16, v46
	v_and_b32_e32 v5, 0xffff0000, v46
	s_waitcnt lgkmcnt(0)
	v_pk_mul_f32 v[4:5], v[6:7], v[4:5]
	v_lshlrev_b32_e32 v6, 16, v47
	v_and_b32_e32 v7, 0xffff0000, v47
	v_pk_mul_f32 v[6:7], v[8:9], v[6:7]
	v_cvt_pk_bf16_f32 v4, v4, v5
	v_cvt_pk_bf16_f32 v5, v6, v7
	v_lshl_add_u64 v[6:7], v[0:1], 0, v[54:55]
	global_store_dwordx4 v[6:7], v[2:5], off nt
	ds_read_b128 v[2:5], v12 offset:2176
	ds_read_b128 v[6:9], v12 offset:2192
	s_waitcnt vmcnt(3)
	v_lshlrev_b32_e32 v10, 16, v40
	v_and_b32_e32 v11, 0xffff0000, v40
	s_waitcnt lgkmcnt(1)
	v_pk_mul_f32 v[2:3], v[2:3], v[10:11]
	v_lshlrev_b32_e32 v10, 16, v41
	v_and_b32_e32 v11, 0xffff0000, v41
	v_pk_mul_f32 v[4:5], v[4:5], v[10:11]
	v_cvt_pk_bf16_f32 v2, v2, v3
	v_cvt_pk_bf16_f32 v3, v4, v5
	v_lshlrev_b32_e32 v4, 16, v42
	v_and_b32_e32 v5, 0xffff0000, v42
	s_waitcnt lgkmcnt(0)
	v_pk_mul_f32 v[4:5], v[6:7], v[4:5]
	v_lshlrev_b32_e32 v6, 16, v43
	v_and_b32_e32 v7, 0xffff0000, v43
	v_pk_mul_f32 v[6:7], v[8:9], v[6:7]
	v_cvt_pk_bf16_f32 v4, v4, v5
	v_cvt_pk_bf16_f32 v5, v6, v7
	v_lshl_add_u64 v[6:7], v[0:1], 0, v[52:53]
	global_store_dwordx4 v[6:7], v[2:5], off nt
	ds_read_b128 v[2:5], v12 offset:4352
	ds_read_b128 v[6:9], v12 offset:4368
	s_waitcnt vmcnt(3)
	v_lshlrev_b32_e32 v10, 16, v36
	v_and_b32_e32 v11, 0xffff0000, v36
	s_waitcnt lgkmcnt(1)
	v_pk_mul_f32 v[2:3], v[2:3], v[10:11]
	v_lshlrev_b32_e32 v10, 16, v37
	v_and_b32_e32 v11, 0xffff0000, v37
	v_pk_mul_f32 v[4:5], v[4:5], v[10:11]
	v_cvt_pk_bf16_f32 v2, v2, v3
	v_cvt_pk_bf16_f32 v3, v4, v5
	v_lshlrev_b32_e32 v4, 16, v38
	v_and_b32_e32 v5, 0xffff0000, v38
	s_waitcnt lgkmcnt(0)
	v_pk_mul_f32 v[4:5], v[6:7], v[4:5]
	v_lshlrev_b32_e32 v6, 16, v39
	v_and_b32_e32 v7, 0xffff0000, v39
	v_pk_mul_f32 v[6:7], v[8:9], v[6:7]
	v_cvt_pk_bf16_f32 v4, v4, v5
	v_cvt_pk_bf16_f32 v5, v6, v7
	v_lshl_add_u64 v[6:7], v[0:1], 0, v[50:51]
	global_store_dwordx4 v[6:7], v[2:5], off nt
	ds_read_b128 v[2:5], v12 offset:6528
	ds_read_b128 v[6:9], v12 offset:6544
	s_waitcnt vmcnt(3)
	v_lshlrev_b32_e32 v10, 16, v32
	v_and_b32_e32 v11, 0xffff0000, v32
	v_lshl_add_u64 v[0:1], v[0:1], 0, v[48:49]
	s_waitcnt lgkmcnt(1)
	v_pk_mul_f32 v[2:3], v[2:3], v[10:11]
	v_lshlrev_b32_e32 v10, 16, v33
	v_and_b32_e32 v11, 0xffff0000, v33
	v_pk_mul_f32 v[4:5], v[4:5], v[10:11]
	v_cvt_pk_bf16_f32 v2, v2, v3
	v_cvt_pk_bf16_f32 v3, v4, v5
	v_lshlrev_b32_e32 v4, 16, v34
	v_and_b32_e32 v5, 0xffff0000, v34
	s_waitcnt lgkmcnt(0)
	v_pk_mul_f32 v[4:5], v[6:7], v[4:5]
	v_lshlrev_b32_e32 v6, 16, v35
	v_and_b32_e32 v7, 0xffff0000, v35
	v_pk_mul_f32 v[6:7], v[8:9], v[6:7]
	v_cvt_pk_bf16_f32 v4, v4, v5
	v_cvt_pk_bf16_f32 v5, v6, v7
	global_store_dwordx4 v[0:1], v[2:5], off nt
	s_barrier
	s_cbranch_scc0 .LBB0_170

; #define RAW_BARRIER() do { asm volatile("s_waitcnt lgkmcnt(0)" ::: "memory"); __builtin_amdgcn_s_barrier(); } while (0)
; #define WAIT_VM(n) asm volatile("s_waitcnt vmcnt(" #n ")" ::: "memory")
; template <bool AF32>
; DI void gemm_main(const void* Ap, int lda, const short* Bp, int K, char* smem, f32x16 (&acc)[4][2]) {
;     ...
;   const int x = (r >> 2) & 3;
;   const int off0 = ((h ^ x) << 4);
;   const int aoff = (wm * 128 + r) * 64, boff = GBOFF + (wn * 64 + r) * 64;
;   struct Frag { bf16x8 a[4], b0, b1; };
;     ...
;   const int nk = K >> 5;
;   Frag F0, F1;
;   GLDS(0, 0);
;   GLDS(1, 1);
;   GLDS(2, 2);
;   GLDS(3, 3);
;   WAIT_VM(12);
;   RAW_BARRIER();
;   LOADF(F0, 0, 0);
;   for (int kt = 0; kt < nk - 3; kt++) {
;     LOADF(F1, kt & 3, 1);
;     MM(F0);
;     WAIT_VM(8);
;     RAW_BARRIER();
;     if (kt + 4 < nk) GLDS(kt + 4, kt & 3);
;     LOADF(F0, (kt + 1) & 3, 0);
;     MM(F1);
;   }
.LBB0_450:
	s_and_b32 s12, s11, 0x10000
	v_add3_u32 v158, s12, v186, v187
	v_or_b32_e32 v154, s12, v188
	s_waitcnt lgkmcnt(0)
	v_mfma_f32_32x32x16_bf16 v[112:127], v[150:153], v[138:141], v[112:127]
	v_lshl_add_u64 v[182:183], v[180:181], 0, s[6:7]
	v_lshl_add_u64 v[184:185], v[178:179], 0, s[6:7]
	v_add_u32_e32 v154, v154, v187
	ds_read_b128 v[162:165], v154 offset:16384
	ds_read_b128 v[154:157], v154 offset:18432
	ds_read_b128 v[174:177], v158
	ds_read_b128 v[170:173], v158 offset:2048
	ds_read_b128 v[166:169], v158 offset:4096
	ds_read_b128 v[158:161], v158 offset:6144
	v_mfma_f32_32x32x16_bf16 v[80:95], v[146:149], v[138:141], v[80:95]
	v_mfma_f32_32x32x16_bf16 v[48:63], v[142:145], v[138:141], v[48:63]
	v_mfma_f32_32x32x16_bf16 v[16:31], v[130:133], v[138:141], v[16:31]
	v_add_u32_e32 v138, s12, v189
	s_mov_b64 s[12:13], 0x1a38100
	v_add_u32_e32 v141, 0x400, v138
	v_add_u32_e32 v140, 0x4000, v138
	v_add_u32_e32 v139, 0x4400, v138
	v_mfma_f32_32x32x16_bf16 v[0:15], v[130:133], v[134:137], v[0:15]
	v_lshl_add_u64 v[130:131], v[182:183], 0, s[12:13]
	s_mov_b64 s[12:13], 0x1a30100
	v_lshl_add_u64 v[132:133], v[182:183], 0, s[12:13]
	s_mov_b64 s[12:13], 0x3f60100
	v_mfma_f32_32x32x16_bf16 v[96:111], v[150:153], v[134:137], v[96:111]
	v_mfma_f32_32x32x16_bf16 v[64:79], v[146:149], v[134:137], v[64:79]
	v_mfma_f32_32x32x16_bf16 v[32:47], v[142:145], v[134:137], v[32:47]
	v_lshl_add_u64 v[134:135], v[184:185], 0, s[12:13]
	s_mov_b64 s[12:13], 0x3f58100
	v_lshl_add_u64 v[136:137], v[184:185], 0, s[12:13]
	v_readfirstlane_b32 s12, v138
	s_mov_b32 m0, s12
	v_readfirstlane_b32 s12, v141
	s_waitcnt vmcnt(8)
	s_waitcnt lgkmcnt(0)
	s_barrier
	global_load_lds_dwordx4 v[136:137], off
	s_mov_b32 m0, s12
	v_readfirstlane_b32 s12, v140
	global_load_lds_dwordx4 v[134:135], off
	s_mov_b32 m0, s12
	v_readfirstlane_b32 s12, v139
	global_load_lds_dwordx4 v[132:133], off
	s_mov_b32 m0, s12
	s_add_i32 s12, s11, 0x8000
	s_and_b32 s12, s12, 0x18000
	s_waitcnt lgkmcnt(0)
	v_mfma_f32_32x32x16_bf16 v[16:31], v[158:161], v[162:165], v[16:31]
	v_add_u32_e32 v190, s12, v186
	v_or_b32_e32 v191, s12, v188
	global_load_lds_dwordx4 v[130:131], off
	v_add_u32_e32 v138, v190, v128
	v_add_u32_e32 v130, v191, v128
	ds_read_b128 v[134:137], v130 offset:16384
	ds_read_b128 v[130:133], v130 offset:18432
	ds_read_b128 v[150:153], v138
	ds_read_b128 v[146:149], v138 offset:2048
	ds_read_b128 v[142:145], v138 offset:4096
	ds_read_b128 v[138:141], v138 offset:6144
	v_mfma_f32_32x32x16_bf16 v[0:15], v[158:161], v[154:157], v[0:15]
	v_add_u32_e32 v158, v190, v187
	s_add_i32 s11, s11, 0x10000
	v_mfma_f32_32x32x16_bf16 v[96:111], v[174:177], v[154:157], v[96:111]
	v_mfma_f32_32x32x16_bf16 v[64:79], v[170:173], v[154:157], v[64:79]
	v_mfma_f32_32x32x16_bf16 v[32:47], v[166:169], v[154:157], v[32:47]
	v_add_u32_e32 v154, v191, v187
	v_mfma_f32_32x32x16_bf16 v[112:127], v[174:177], v[162:165], v[112:127]
	v_mfma_f32_32x32x16_bf16 v[80:95], v[170:173], v[162:165], v[80:95]
	v_mfma_f32_32x32x16_bf16 v[48:63], v[166:169], v[162:165], v[48:63]
	ds_read_b128 v[162:165], v154 offset:16384
	ds_read_b128 v[154:157], v154 offset:18432
	ds_read_b128 v[190:193], v158
	ds_read_b128 v[170:173], v158 offset:2048
	ds_read_b128 v[166:169], v158 offset:4096
	ds_read_b128 v[158:161], v158 offset:6144
	s_waitcnt lgkmcnt(6)
	v_mfma_f32_32x32x16_bf16 v[16:31], v[138:141], v[134:137], v[16:31]
	v_mfma_f32_32x32x16_bf16 v[0:15], v[138:141], v[130:133], v[0:15]
	v_add_u32_e32 v138, s12, v189
	s_mov_b64 s[12:13], 0x1a38140
	v_add_u32_e32 v141, 0x400, v138
	v_add_u32_e32 v140, 0x4000, v138
	v_add_u32_e32 v139, 0x4400, v138
	v_mfma_f32_32x32x16_bf16 v[96:111], v[150:153], v[130:133], v[96:111]
	v_mfma_f32_32x32x16_bf16 v[64:79], v[146:149], v[130:133], v[64:79]
	v_mfma_f32_32x32x16_bf16 v[32:47], v[142:145], v[130:133], v[32:47]
	v_lshl_add_u64 v[130:131], v[182:183], 0, s[12:13]
	s_mov_b64 s[12:13], 0x1a30140
	v_lshl_add_u64 v[132:133], v[182:183], 0, s[12:13]
	s_mov_b64 s[12:13], 0x3f60140
	v_mfma_f32_32x32x16_bf16 v[112:127], v[150:153], v[134:137], v[112:127]
	v_mfma_f32_32x32x16_bf16 v[80:95], v[146:149], v[134:137], v[80:95]
	v_mfma_f32_32x32x16_bf16 v[48:63], v[142:145], v[134:137], v[48:63]
	v_lshl_add_u64 v[134:135], v[184:185], 0, s[12:13]
	s_mov_b64 s[12:13], 0x3f58140
	v_lshl_add_u64 v[136:137], v[184:185], 0, s[12:13]
	v_readfirstlane_b32 s12, v138
	s_mov_b32 m0, s12
	v_readfirstlane_b32 s12, v141
	s_waitcnt vmcnt(8)
	s_waitcnt lgkmcnt(0)
	s_barrier
	global_load_lds_dwordx4 v[136:137], off
	s_mov_b32 m0, s12
	v_readfirstlane_b32 s12, v140
	global_load_lds_dwordx4 v[134:135], off
	s_mov_b32 m0, s12
	v_readfirstlane_b32 s12, v139
	global_load_lds_dwordx4 v[132:133], off
	s_mov_b32 m0, s12
	s_and_b32 s12, s11, 0x10000
	global_load_lds_dwordx4 v[130:131], off
	v_add_u32_e32 v174, s12, v186
	v_or_b32_e32 v131, s12, v188
	v_add_u32_e32 v130, v174, v128
	v_add_u32_e32 v131, v131, v128
	ds_read_b128 v[138:141], v131 offset:16384
	ds_read_b128 v[134:137], v131 offset:18432
	ds_read_b128 v[150:153], v130
	ds_read_b128 v[146:149], v130 offset:2048
	ds_read_b128 v[142:145], v130 offset:4096
	ds_read_b128 v[130:133], v130 offset:6144
	v_mfma_f32_32x32x16_bf16 v[112:127], v[190:193], v[162:165], v[112:127]
	s_add_u32 s6, s6, 0x80
	s_addc_u32 s7, s7, 0
	s_cmpk_eq_i32 s6, 0x700
	v_mfma_f32_32x32x16_bf16 v[96:111], v[190:193], v[154:157], v[96:111]
	v_mfma_f32_32x32x16_bf16 v[80:95], v[170:173], v[162:165], v[80:95]
	v_mfma_f32_32x32x16_bf16 v[64:79], v[170:173], v[154:157], v[64:79]
	v_mfma_f32_32x32x16_bf16 v[48:63], v[166:169], v[162:165], v[48:63]
	v_mfma_f32_32x32x16_bf16 v[32:47], v[166:169], v[154:157], v[32:47]
	v_mfma_f32_32x32x16_bf16 v[16:31], v[158:161], v[162:165], v[16:31]
	v_mfma_f32_32x32x16_bf16 v[0:15], v[158:161], v[154:157], v[0:15]
	s_cbranch_scc0 .LBB0_450
; #define RAW_BARRIER() do { asm volatile("s_waitcnt lgkmcnt(0)" ::: "memory"); __builtin_amdgcn_s_barrier(); } while (0)
; #define WAIT_VM(n) asm volatile("s_waitcnt vmcnt(" #n ")" ::: "memory")
; template <bool AF32>
; DI void gemm_main(const void* Ap, int lda, const short* Bp, int K, char* smem, f32x16 (&acc)[4][2]) {
;     ...
;   LOADF(F1, (nk - 3) & 3, 1);
;   MM(F0);
;   WAIT_VM(4);
;   RAW_BARRIER();
;   LOADF(F0, (nk - 2) & 3, 0);
;   MM(F1);
;   LOADF(F1, (nk - 2) & 3, 1);
;   MM(F0);
;   WAIT_VM(0);
;   RAW_BARRIER();
;   LOADF(F0, (nk - 1) & 3, 0);
;   MM(F1);
;   LOADF(F1, (nk - 1) & 3, 1);
;   MM(F0);
;   MM(F1);
;   __syncthreads();
	s_waitcnt lgkmcnt(0)
	v_mfma_f32_32x32x16_bf16 v[80:95], v[146:149], v[138:141], v[80:95]
	s_lshl_b32 s16, s9, 8
	s_and_b64 vcc, exec, s[26:27]
	v_mfma_f32_32x32x16_bf16 v[64:79], v[146:149], v[134:137], v[64:79]
	v_add_u32_e32 v146, v174, v187
	v_add_u32_e32 v147, v188, v187
	v_mfma_f32_32x32x16_bf16 v[16:31], v[130:133], v[138:141], v[16:31]
	v_mfma_f32_32x32x16_bf16 v[0:15], v[130:133], v[134:137], v[0:15]
	ds_read_b128 v[130:133], v146
	v_mfma_f32_32x32x16_bf16 v[112:127], v[150:153], v[138:141], v[112:127]
	v_mfma_f32_32x32x16_bf16 v[96:111], v[150:153], v[134:137], v[96:111]
	v_mfma_f32_32x32x16_bf16 v[48:63], v[142:145], v[138:141], v[48:63]
	v_mfma_f32_32x32x16_bf16 v[32:47], v[142:145], v[134:137], v[32:47]
	ds_read_b128 v[134:137], v147 offset:16384
	ds_read_b128 v[138:141], v147 offset:18432
	ds_read_b128 v[142:145], v146 offset:2048
	s_waitcnt lgkmcnt(0)
	v_mfma_f32_32x32x16_bf16 v[112:127], v[130:133], v[134:137], v[112:127]
	v_mfma_f32_32x32x16_bf16 v[96:111], v[130:133], v[138:141], v[96:111]
	v_mfma_f32_32x32x16_bf16 v[80:95], v[142:145], v[134:137], v[80:95]
	v_mfma_f32_32x32x16_bf16 v[64:79], v[142:145], v[138:141], v[64:79]
	ds_read_b128 v[130:133], v146 offset:4096
	ds_read_b128 v[142:145], v146 offset:6144
	s_waitcnt vmcnt(8)
	v_add_u32_e32 v146, v186, v128
	s_waitcnt lgkmcnt(0)
	s_barrier
	s_waitcnt lgkmcnt(0)
	v_mfma_f32_32x32x16_bf16 v[48:63], v[130:133], v[134:137], v[48:63]
	v_mfma_f32_32x32x16_bf16 v[32:47], v[130:133], v[138:141], v[32:47]
	ds_read_b128 v[130:133], v146 offset:32768
	v_mfma_f32_32x32x16_bf16 v[0:15], v[142:145], v[138:141], v[0:15]
	v_add_u32_e32 v138, v188, v128
	v_mfma_f32_32x32x16_bf16 v[16:31], v[142:145], v[134:137], v[16:31]
	ds_read_b128 v[134:137], v138 offset:49152
	ds_read_b128 v[138:141], v138 offset:51200
	ds_read_b128 v[142:145], v146 offset:34816
	s_waitcnt lgkmcnt(0)
	v_mfma_f32_32x32x16_bf16 v[112:127], v[130:133], v[134:137], v[112:127]
	v_mfma_f32_32x32x16_bf16 v[96:111], v[130:133], v[138:141], v[96:111]
	v_mfma_f32_32x32x16_bf16 v[80:95], v[142:145], v[134:137], v[80:95]
	v_mfma_f32_32x32x16_bf16 v[64:79], v[142:145], v[138:141], v[64:79]
	ds_read_b128 v[130:133], v146 offset:36864
	ds_read_b128 v[142:145], v146 offset:38912
	v_add_u32_e32 v146, v186, v187
	s_waitcnt lgkmcnt(0)
	v_mfma_f32_32x32x16_bf16 v[48:63], v[130:133], v[134:137], v[48:63]
	v_mfma_f32_32x32x16_bf16 v[32:47], v[130:133], v[138:141], v[32:47]
	v_mfma_f32_32x32x16_bf16 v[16:31], v[142:145], v[134:137], v[16:31]
	v_mfma_f32_32x32x16_bf16 v[0:15], v[142:145], v[138:141], v[0:15]
	ds_read_b128 v[130:133], v146 offset:32768
	ds_read_b128 v[134:137], v147 offset:49152
	ds_read_b128 v[138:141], v147 offset:51200
	ds_read_b128 v[142:145], v146 offset:34816
	v_add_u32_e32 v147, 0x10000, v186
	v_add_u32_e32 v148, v147, v128
	v_add_u32_e32 v147, v147, v187
	s_waitcnt lgkmcnt(0)
	v_mfma_f32_32x32x16_bf16 v[112:127], v[130:133], v[134:137], v[112:127]
	v_mfma_f32_32x32x16_bf16 v[96:111], v[130:133], v[138:141], v[96:111]
	v_mfma_f32_32x32x16_bf16 v[80:95], v[142:145], v[134:137], v[80:95]
	v_mfma_f32_32x32x16_bf16 v[64:79], v[142:145], v[138:141], v[64:79]
	ds_read_b128 v[130:133], v146 offset:36864
	ds_read_b128 v[142:145], v146 offset:38912
	s_waitcnt vmcnt(4)
	s_waitcnt lgkmcnt(0)
	s_barrier
	v_or_b32_e32 v146, 0x4000, v188
	v_add_u32_e32 v149, v146, v128
	v_add_u32_e32 v146, v146, v187
	s_waitcnt lgkmcnt(0)
	v_mfma_f32_32x32x16_bf16 v[48:63], v[130:133], v[134:137], v[48:63]
	v_mfma_f32_32x32x16_bf16 v[32:47], v[130:133], v[138:141], v[32:47]
	ds_read_b128 v[130:133], v148
	v_mfma_f32_32x32x16_bf16 v[16:31], v[142:145], v[134:137], v[16:31]
	v_or_b32_e32 v134, 0x10000, v149
	ds_read_b128 v[134:137], v134
	v_mfma_f32_32x32x16_bf16 v[0:15], v[142:145], v[138:141], v[0:15]
	v_add_u32_e32 v138, 0x10800, v149
	ds_read_b128 v[138:141], v138
	ds_read_b128 v[142:145], v148 offset:2048
	s_waitcnt lgkmcnt(0)
	v_mfma_f32_32x32x16_bf16 v[112:127], v[130:133], v[134:137], v[112:127]
	v_mfma_f32_32x32x16_bf16 v[96:111], v[130:133], v[138:141], v[96:111]
	v_mfma_f32_32x32x16_bf16 v[80:95], v[142:145], v[134:137], v[80:95]
	v_mfma_f32_32x32x16_bf16 v[64:79], v[142:145], v[138:141], v[64:79]
	ds_read_b128 v[130:133], v148 offset:4096
	ds_read_b128 v[142:145], v148 offset:6144
	s_waitcnt lgkmcnt(0)
	v_mfma_f32_32x32x16_bf16 v[48:63], v[130:133], v[134:137], v[48:63]
	v_mfma_f32_32x32x16_bf16 v[32:47], v[130:133], v[138:141], v[32:47]
	ds_read_b128 v[130:133], v147
	v_mfma_f32_32x32x16_bf16 v[16:31], v[142:145], v[134:137], v[16:31]
	v_or_b32_e32 v134, 0x10000, v146
	ds_read_b128 v[134:137], v134
	v_mfma_f32_32x32x16_bf16 v[0:15], v[142:145], v[138:141], v[0:15]
	v_add_u32_e32 v138, 0x10800, v146
	ds_read_b128 v[138:141], v138
	ds_read_b128 v[142:145], v147 offset:2048
	s_waitcnt lgkmcnt(0)
	v_mfma_f32_32x32x16_bf16 v[112:127], v[130:133], v[134:137], v[112:127]
	v_mfma_f32_32x32x16_bf16 v[96:111], v[130:133], v[138:141], v[96:111]
	v_mfma_f32_32x32x16_bf16 v[80:95], v[142:145], v[134:137], v[80:95]
	v_mfma_f32_32x32x16_bf16 v[64:79], v[142:145], v[138:141], v[64:79]
	ds_read_b128 v[130:133], v147 offset:4096
	ds_read_b128 v[142:145], v147 offset:6144
	v_add_u32_e32 v147, 0x18000, v186
	s_waitcnt vmcnt(0)
	v_add_u32_e32 v128, v147, v128
	s_waitcnt lgkmcnt(0)
	s_barrier
; DI int my_tid() { int t = threadIdx.x; asm volatile("" : "+v"(t)); return t; }
; #define RAW_BARRIER() do { asm volatile("s_waitcnt lgkmcnt(0)" ::: "memory"); __builtin_amdgcn_s_barrier(); } while (0)
; #define WAIT_VM(n) asm volatile("s_waitcnt vmcnt(" #n ")" ::: "memory")
; DI short* xb_ptr(PRef p, int layer) { return (layer == 1 || layer == 2) ? (short*)p.out : (short*)(p.ws + OFF_XB); }
; template <bool AF32>
; DI void gemm_main(const void* Ap, int lda, const short* Bp, int K, char* smem, f32x16 (&acc)[4][2]) {
;     ...
;   LOADF(F1, (nk - 3) & 3, 1);
;   MM(F0);
;   WAIT_VM(4);
;   RAW_BARRIER();
;   LOADF(F0, (nk - 2) & 3, 0);
;   MM(F1);
;   LOADF(F1, (nk - 2) & 3, 1);
;   MM(F0);
;   WAIT_VM(0);
;   RAW_BARRIER();
;   LOADF(F0, (nk - 1) & 3, 0);
;   MM(F1);
;   LOADF(F1, (nk - 1) & 3, 1);
;   MM(F0);
;   MM(F1);
;   __syncthreads();
; DI void outproj_tile(PRef p, int layer, int mt, int nt2, char* smem, int noatom) {
;     ...
;     u32x4 pre[8];
; #pragma unroll
;     for (int s_ = 0; s_ < 8; s_++) pre[s_] = u32x4{0u, 0u, 0u, 0u};
;     if (layer > 0) {
;       const short* xb = xb_ptr(p, layer);
;       const int t_ = my_tid() & 255, ln_ = t_ & 63, ww_ = t_ >> 6;
; #pragma unroll
;       for (int s_ = 0; s_ < 8; s_++) {
;         const int row_ = ww_ * 32 + s_ * 4 + (ln_ >> 4);
;         pre[s_] = *(const u32x4*)(xb + (size_t)(mt * 256 + pm * 128 + row_) * 1024 + nt * 128 + (ln_ & 15) * 8);
;       }
;     }
	s_waitcnt lgkmcnt(0)
	v_mfma_f32_32x32x16_bf16 v[48:63], v[130:133], v[134:137], v[48:63]
	v_mfma_f32_32x32x16_bf16 v[32:47], v[130:133], v[138:141], v[32:47]
	ds_read_b128 v[130:133], v128
	v_mfma_f32_32x32x16_bf16 v[0:15], v[142:145], v[138:141], v[0:15]
	v_add_u32_e32 v138, 0x18000, v149
	v_mfma_f32_32x32x16_bf16 v[16:31], v[142:145], v[134:137], v[16:31]
	ds_read_b128 v[134:137], v138
	ds_read_b128 v[138:141], v138 offset:2048
	ds_read_b128 v[142:145], v128 offset:2048
	s_waitcnt lgkmcnt(0)
	v_mfma_f32_32x32x16_bf16 v[112:127], v[130:133], v[134:137], v[112:127]
	v_mfma_f32_32x32x16_bf16 v[96:111], v[130:133], v[138:141], v[96:111]
	v_mfma_f32_32x32x16_bf16 v[80:95], v[142:145], v[134:137], v[80:95]
	v_mfma_f32_32x32x16_bf16 v[64:79], v[142:145], v[138:141], v[64:79]
	ds_read_b128 v[130:133], v128 offset:4096
	ds_read_b128 v[142:145], v128 offset:6144
	v_add_u32_e32 v128, v147, v187
	s_waitcnt lgkmcnt(0)
	v_mfma_f32_32x32x16_bf16 v[48:63], v[130:133], v[134:137], v[48:63]
	v_mfma_f32_32x32x16_bf16 v[32:47], v[130:133], v[138:141], v[32:47]
	ds_read_b128 v[130:133], v128
	v_mfma_f32_32x32x16_bf16 v[0:15], v[142:145], v[138:141], v[0:15]
	v_add_u32_e32 v138, 0x18000, v146
	v_mfma_f32_32x32x16_bf16 v[16:31], v[142:145], v[134:137], v[16:31]
	ds_read_b128 v[134:137], v138
	ds_read_b128 v[138:141], v138 offset:2048
	ds_read_b128 v[142:145], v128 offset:2048
	s_waitcnt lgkmcnt(0)
	v_mfma_f32_32x32x16_bf16 v[112:127], v[130:133], v[134:137], v[112:127]
	v_mfma_f32_32x32x16_bf16 v[96:111], v[130:133], v[138:141], v[96:111]
	v_mfma_f32_32x32x16_bf16 v[80:95], v[142:145], v[134:137], v[80:95]
	v_mfma_f32_32x32x16_bf16 v[64:79], v[142:145], v[138:141], v[64:79]
	ds_read_b128 v[130:133], v128 offset:4096
	ds_read_b128 v[142:145], v128 offset:6144
	v_mov_b32_e32 v128, v196
	s_waitcnt vmcnt(0) lgkmcnt(0)
	s_barrier
	v_mfma_f32_32x32x16_bf16 v[48:63], v[130:133], v[134:137], v[48:63]
	v_ashrrev_i32_e32 v128, 1, v128
	v_and_b32_e32 v128, 0xffffff80, v128
	v_add_u32_e32 v182, s10, v128
	v_ashrrev_i32_e32 v183, 31, v182
	v_lshl_add_u64 v[184:185], v[182:183], 1, s[4:5]
	v_mfma_f32_32x32x16_bf16 v[32:47], v[130:133], v[138:141], v[32:47]
	v_mfma_f32_32x32x16_bf16 v[16:31], v[142:145], v[134:137], v[16:31]
	v_mfma_f32_32x32x16_bf16 v[0:15], v[142:145], v[138:141], v[0:15]
	s_cbranch_vccz .LBB0_453
	v_mov_b32_e32 v128, v196
	s_nop 0
	v_lshrrev_b32_e32 v130, 1, v128
	v_and_b32_e32 v130, 0x60, v130
	v_bfe_u32 v131, v128, 4, 2
	v_lshlrev_b32_e32 v128, 4, v128
	v_or3_b32 v132, v131, v130, s16
	v_and_b32_e32 v128, 0xf0, v128
	v_lshl_add_u64 v[130:131], v[184:185], 0, v[128:129]
	v_lshlrev_b32_e32 v128, 11, v132
	v_lshl_add_u64 v[130:131], v[130:131], 0, v[128:129]
	v_add_co_u32_e32 v132, vcc, 0x2000, v130
	s_nop 1
	v_addc_co_u32_e32 v133, vcc, 0, v131, vcc
	global_load_dwordx4 v[158:161], v[130:131], off
	global_load_dwordx4 v[154:157], v[132:133], off
	v_add_co_u32_e32 v132, vcc, s84, v130
	s_nop 1
	v_addc_co_u32_e32 v133, vcc, 0, v131, vcc
	v_add_co_u32_e32 v134, vcc, 0x6000, v130
	s_nop 1
	v_addc_co_u32_e32 v135, vcc, 0, v131, vcc
	global_load_dwordx4 v[150:153], v[132:133], off
	global_load_dwordx4 v[146:149], v[134:135], off
	v_add_co_u32_e32 v132, vcc, 0x8000, v130
	s_nop 1
	v_addc_co_u32_e32 v133, vcc, 0, v131, vcc
	v_add_co_u32_e32 v134, vcc, 0xa000, v130
	s_nop 1
	v_addc_co_u32_e32 v135, vcc, 0, v131, vcc
	global_load_dwordx4 v[142:145], v[132:133], off
	global_load_dwordx4 v[138:141], v[134:135], off
	v_add_co_u32_e32 v132, vcc, 0xc000, v130
	s_nop 1
	v_addc_co_u32_e32 v133, vcc, 0, v131, vcc
	v_add_co_u32_e32 v130, vcc, 0xe000, v130
	s_nop 1
	v_addc_co_u32_e32 v131, vcc, 0, v131, vcc
	global_load_dwordx4 v[134:137], v[132:133], off
	s_nop 0
	global_load_dwordx4 v[130:133], v[130:131], off
	s_branch .LBB0_454

; #define RAW_BARRIER() do { asm volatile("s_waitcnt lgkmcnt(0)" ::: "memory"); __builtin_amdgcn_s_barrier(); } while (0)
; #define WAIT_VM(n) asm volatile("s_waitcnt vmcnt(" #n ")" ::: "memory")
; template <bool AF32>
; DI void gemm_main(const void* Ap, int lda, const short* Bp, int K, char* smem, f32x16 (&acc)[4][2]) {
;     ...
;   const int x = (r >> 2) & 3;
;   const int off0 = ((h ^ x) << 4);
;   const int aoff = (wm * 128 + r) * 64, boff = GBOFF + (wn * 64 + r) * 64;
;   struct Frag { bf16x8 a[4], b0, b1; };
;     ...
;   const int nk = K >> 5;
;   Frag F0, F1;
;   GLDS(0, 0);
;   GLDS(1, 1);
;   GLDS(2, 2);
;   GLDS(3, 3);
;   WAIT_VM(12);
;   RAW_BARRIER();
;   LOADF(F0, 0, 0);
;   for (int kt = 0; kt < nk - 3; kt++) {
;     LOADF(F1, kt & 3, 1);
;     MM(F0);
;     WAIT_VM(8);
;     RAW_BARRIER();
;     if (kt + 4 < nk) GLDS(kt + 4, kt & 3);
;     LOADF(F0, (kt + 1) & 3, 0);
;     MM(F1);
;   }
.LBB0_665:
	s_and_b32 s9, s8, 0x10000
	s_waitcnt lgkmcnt(0)
	v_mfma_f32_32x32x16_bf16 v[16:31], v[130:133], v[138:141], v[16:31]
	v_or_b32_e32 v154, s9, v188
	v_add3_u32 v158, s9, v186, v187
	v_add_u32_e32 v154, v154, v187
	ds_read_b128 v[162:165], v154 offset:16384
	ds_read_b128 v[154:157], v154 offset:18432
	ds_read_b128 v[174:177], v158
	ds_read_b128 v[170:173], v158 offset:2048
	ds_read_b128 v[166:169], v158 offset:4096
	ds_read_b128 v[158:161], v158 offset:6144
	v_lshl_add_u64 v[184:185], v[178:179], 0, s[6:7]
	v_lshl_add_u64 v[182:183], v[180:181], 0, s[6:7]
	v_mfma_f32_32x32x16_bf16 v[0:15], v[130:133], v[134:137], v[0:15]
	s_mov_b64 s[10:11], 0x808100
	v_lshl_add_u64 v[130:131], v[182:183], 0, s[10:11]
	s_mov_b64 s[10:11], 0x800100
	v_lshl_add_u64 v[132:133], v[182:183], 0, s[10:11]
	s_mov_b64 s[10:11], 0x808140
	v_mfma_f32_32x32x16_bf16 v[112:127], v[150:153], v[138:141], v[112:127]
	v_mfma_f32_32x32x16_bf16 v[80:95], v[146:149], v[138:141], v[80:95]
	v_mfma_f32_32x32x16_bf16 v[48:63], v[142:145], v[138:141], v[48:63]
	v_add_u32_e32 v138, s9, v189
	v_add_u32_e32 v141, 0x400, v138
	v_readfirstlane_b32 s9, v138
	v_add_u32_e32 v140, 0x4000, v138
	s_mov_b32 m0, s9
	v_readfirstlane_b32 s9, v141
	v_add_u32_e32 v139, 0x4400, v138
	v_mfma_f32_32x32x16_bf16 v[96:111], v[150:153], v[134:137], v[96:111]
	v_mfma_f32_32x32x16_bf16 v[64:79], v[146:149], v[134:137], v[64:79]
	v_mfma_f32_32x32x16_bf16 v[32:47], v[142:145], v[134:137], v[32:47]
	v_lshl_add_u64 v[136:137], v[184:185], 0, s[78:79]
	v_lshl_add_u64 v[134:135], v[184:185], 0, s[76:77]
	s_waitcnt vmcnt(8)
	s_waitcnt lgkmcnt(0)
	s_barrier
	global_load_lds_dwordx4 v[136:137], off
	s_mov_b32 m0, s9
	v_readfirstlane_b32 s9, v140
	global_load_lds_dwordx4 v[134:135], off
	s_mov_b32 m0, s9
	v_readfirstlane_b32 s9, v139
	global_load_lds_dwordx4 v[132:133], off
	s_mov_b32 m0, s9
	s_add_i32 s9, s8, 0x8000
	s_and_b32 s9, s9, 0x18000
	s_waitcnt lgkmcnt(0)
	v_mfma_f32_32x32x16_bf16 v[16:31], v[158:161], v[162:165], v[16:31]
	v_add_u32_e32 v190, s9, v186
	v_or_b32_e32 v191, s9, v188
	global_load_lds_dwordx4 v[130:131], off
	v_add_u32_e32 v138, v190, v128
	v_add_u32_e32 v130, v191, v128
	ds_read_b128 v[134:137], v130 offset:16384
	ds_read_b128 v[130:133], v130 offset:18432
	ds_read_b128 v[150:153], v138
	ds_read_b128 v[146:149], v138 offset:2048
	ds_read_b128 v[142:145], v138 offset:4096
	ds_read_b128 v[138:141], v138 offset:6144
	v_mfma_f32_32x32x16_bf16 v[0:15], v[158:161], v[154:157], v[0:15]
	v_add_u32_e32 v158, v190, v187
	s_add_i32 s8, s8, 0x10000
	v_mfma_f32_32x32x16_bf16 v[112:127], v[174:177], v[162:165], v[112:127]
	v_mfma_f32_32x32x16_bf16 v[80:95], v[170:173], v[162:165], v[80:95]
	v_mfma_f32_32x32x16_bf16 v[48:63], v[166:169], v[162:165], v[48:63]
	v_mfma_f32_32x32x16_bf16 v[96:111], v[174:177], v[154:157], v[96:111]
	v_mfma_f32_32x32x16_bf16 v[64:79], v[170:173], v[154:157], v[64:79]
	v_mfma_f32_32x32x16_bf16 v[32:47], v[166:169], v[154:157], v[32:47]
	v_add_u32_e32 v154, v191, v187
	ds_read_b128 v[162:165], v154 offset:16384
	ds_read_b128 v[154:157], v154 offset:18432
	ds_read_b128 v[190:193], v158
	ds_read_b128 v[170:173], v158 offset:2048
	ds_read_b128 v[166:169], v158 offset:4096
	ds_read_b128 v[158:161], v158 offset:6144
	s_waitcnt lgkmcnt(6)
	v_mfma_f32_32x32x16_bf16 v[16:31], v[138:141], v[134:137], v[16:31]
	v_mfma_f32_32x32x16_bf16 v[0:15], v[138:141], v[130:133], v[0:15]
	v_add_u32_e32 v138, s9, v189
	v_add_u32_e32 v141, 0x400, v138
	v_readfirstlane_b32 s9, v138
	v_add_u32_e32 v140, 0x4000, v138
	s_mov_b32 m0, s9
	v_readfirstlane_b32 s9, v141
	v_add_u32_e32 v139, 0x4400, v138
	v_mfma_f32_32x32x16_bf16 v[112:127], v[150:153], v[134:137], v[112:127]
	v_mfma_f32_32x32x16_bf16 v[80:95], v[146:149], v[134:137], v[80:95]
	v_mfma_f32_32x32x16_bf16 v[48:63], v[142:145], v[134:137], v[48:63]
	v_lshl_add_u64 v[136:137], v[184:185], 0, s[82:83]
	v_lshl_add_u64 v[134:135], v[184:185], 0, s[80:81]
	s_waitcnt vmcnt(8)
	s_waitcnt lgkmcnt(0)
	s_barrier
	global_load_lds_dwordx4 v[136:137], off
	s_mov_b32 m0, s9
	v_readfirstlane_b32 s9, v140
	global_load_lds_dwordx4 v[134:135], off
	v_mfma_f32_32x32x16_bf16 v[96:111], v[150:153], v[130:133], v[96:111]
	s_mov_b32 m0, s9
	v_readfirstlane_b32 s9, v139
	v_mfma_f32_32x32x16_bf16 v[64:79], v[146:149], v[130:133], v[64:79]
	v_mfma_f32_32x32x16_bf16 v[32:47], v[142:145], v[130:133], v[32:47]
	v_lshl_add_u64 v[130:131], v[182:183], 0, s[10:11]
	s_mov_b64 s[10:11], 0x800140
	v_lshl_add_u64 v[132:133], v[182:183], 0, s[10:11]
	global_load_lds_dwordx4 v[132:133], off
	s_mov_b32 m0, s9
	s_and_b32 s9, s8, 0x10000
	global_load_lds_dwordx4 v[130:131], off
	v_add_u32_e32 v174, s9, v186
	v_or_b32_e32 v131, s9, v188
	v_add_u32_e32 v130, v174, v128
	v_add_u32_e32 v131, v131, v128
	ds_read_b128 v[138:141], v131 offset:16384
	ds_read_b128 v[134:137], v131 offset:18432
	ds_read_b128 v[150:153], v130
	ds_read_b128 v[146:149], v130 offset:2048
	ds_read_b128 v[142:145], v130 offset:4096
	ds_read_b128 v[130:133], v130 offset:6144
	v_mfma_f32_32x32x16_bf16 v[112:127], v[190:193], v[162:165], v[112:127]
	s_add_u32 s6, s6, 0x80
	s_addc_u32 s7, s7, 0
	s_cmpk_eq_i32 s6, 0x700
	v_mfma_f32_32x32x16_bf16 v[96:111], v[190:193], v[154:157], v[96:111]
	v_mfma_f32_32x32x16_bf16 v[80:95], v[170:173], v[162:165], v[80:95]
	v_mfma_f32_32x32x16_bf16 v[64:79], v[170:173], v[154:157], v[64:79]
	v_mfma_f32_32x32x16_bf16 v[48:63], v[166:169], v[162:165], v[48:63]
	v_mfma_f32_32x32x16_bf16 v[32:47], v[166:169], v[154:157], v[32:47]
	v_mfma_f32_32x32x16_bf16 v[16:31], v[158:161], v[162:165], v[16:31]
	v_mfma_f32_32x32x16_bf16 v[0:15], v[158:161], v[154:157], v[0:15]
	s_cbranch_scc0 .LBB0_665
; #define RAW_BARRIER() do { asm volatile("s_waitcnt lgkmcnt(0)" ::: "memory"); __builtin_amdgcn_s_barrier(); } while (0)
; #define WAIT_VM(n) asm volatile("s_waitcnt vmcnt(" #n ")" ::: "memory")
; template <bool AF32>
; DI void gemm_main(const void* Ap, int lda, const short* Bp, int K, char* smem, f32x16 (&acc)[4][2]) {
;     ...
;   LOADF(F1, (nk - 3) & 3, 1);
;   MM(F0);
;   WAIT_VM(4);
;   RAW_BARRIER();
;   LOADF(F0, (nk - 2) & 3, 0);
;   MM(F1);
;   LOADF(F1, (nk - 2) & 3, 1);
;   MM(F0);
;   WAIT_VM(0);
;   RAW_BARRIER();
;   LOADF(F0, (nk - 1) & 3, 0);
;   MM(F1);
;   LOADF(F1, (nk - 1) & 3, 1);
;   MM(F0);
;   MM(F1);
;   __syncthreads();
	s_waitcnt lgkmcnt(0)
	v_mfma_f32_32x32x16_bf16 v[80:95], v[146:149], v[138:141], v[80:95]
	s_lshl_b32 s56, s38, 8
	v_mfma_f32_32x32x16_bf16 v[64:79], v[146:149], v[134:137], v[64:79]
	v_add_u32_e32 v146, v174, v187
	v_add_u32_e32 v147, v188, v187
	v_mfma_f32_32x32x16_bf16 v[16:31], v[130:133], v[138:141], v[16:31]
	v_mfma_f32_32x32x16_bf16 v[0:15], v[130:133], v[134:137], v[0:15]
	ds_read_b128 v[130:133], v146
	v_mfma_f32_32x32x16_bf16 v[112:127], v[150:153], v[138:141], v[112:127]
	v_mfma_f32_32x32x16_bf16 v[96:111], v[150:153], v[134:137], v[96:111]
	v_mfma_f32_32x32x16_bf16 v[48:63], v[142:145], v[138:141], v[48:63]
	v_mfma_f32_32x32x16_bf16 v[32:47], v[142:145], v[134:137], v[32:47]
	ds_read_b128 v[134:137], v147 offset:16384
	ds_read_b128 v[138:141], v147 offset:18432
	ds_read_b128 v[142:145], v146 offset:2048
	s_waitcnt lgkmcnt(0)
	v_mfma_f32_32x32x16_bf16 v[112:127], v[130:133], v[134:137], v[112:127]
	v_mfma_f32_32x32x16_bf16 v[96:111], v[130:133], v[138:141], v[96:111]
	v_mfma_f32_32x32x16_bf16 v[80:95], v[142:145], v[134:137], v[80:95]
	v_mfma_f32_32x32x16_bf16 v[64:79], v[142:145], v[138:141], v[64:79]
	ds_read_b128 v[130:133], v146 offset:4096
	ds_read_b128 v[142:145], v146 offset:6144
	s_waitcnt vmcnt(8)
	v_add_u32_e32 v146, v186, v128
	s_waitcnt lgkmcnt(0)
	s_barrier
	s_waitcnt lgkmcnt(0)
	v_mfma_f32_32x32x16_bf16 v[48:63], v[130:133], v[134:137], v[48:63]
	v_mfma_f32_32x32x16_bf16 v[32:47], v[130:133], v[138:141], v[32:47]
	ds_read_b128 v[130:133], v146 offset:32768
	v_mfma_f32_32x32x16_bf16 v[0:15], v[142:145], v[138:141], v[0:15]
	v_add_u32_e32 v138, v188, v128
	v_mfma_f32_32x32x16_bf16 v[16:31], v[142:145], v[134:137], v[16:31]
	ds_read_b128 v[134:137], v138 offset:49152
	ds_read_b128 v[138:141], v138 offset:51200
	ds_read_b128 v[142:145], v146 offset:34816
	s_waitcnt lgkmcnt(0)
	v_mfma_f32_32x32x16_bf16 v[112:127], v[130:133], v[134:137], v[112:127]
	v_mfma_f32_32x32x16_bf16 v[96:111], v[130:133], v[138:141], v[96:111]
	v_mfma_f32_32x32x16_bf16 v[80:95], v[142:145], v[134:137], v[80:95]
	v_mfma_f32_32x32x16_bf16 v[64:79], v[142:145], v[138:141], v[64:79]
	ds_read_b128 v[130:133], v146 offset:36864
	ds_read_b128 v[142:145], v146 offset:38912
	v_add_u32_e32 v146, v186, v187
	s_waitcnt lgkmcnt(0)
	v_mfma_f32_32x32x16_bf16 v[48:63], v[130:133], v[134:137], v[48:63]
	v_mfma_f32_32x32x16_bf16 v[32:47], v[130:133], v[138:141], v[32:47]
	v_mfma_f32_32x32x16_bf16 v[16:31], v[142:145], v[134:137], v[16:31]
	v_mfma_f32_32x32x16_bf16 v[0:15], v[142:145], v[138:141], v[0:15]
	ds_read_b128 v[130:133], v146 offset:32768
	ds_read_b128 v[134:137], v147 offset:49152
	ds_read_b128 v[138:141], v147 offset:51200
	ds_read_b128 v[142:145], v146 offset:34816
	v_add_u32_e32 v147, 0x10000, v186
	v_add_u32_e32 v148, v147, v128
	v_add_u32_e32 v147, v147, v187
	s_waitcnt lgkmcnt(0)
	v_mfma_f32_32x32x16_bf16 v[112:127], v[130:133], v[134:137], v[112:127]
	v_mfma_f32_32x32x16_bf16 v[96:111], v[130:133], v[138:141], v[96:111]
	v_mfma_f32_32x32x16_bf16 v[80:95], v[142:145], v[134:137], v[80:95]
	v_mfma_f32_32x32x16_bf16 v[64:79], v[142:145], v[138:141], v[64:79]
	ds_read_b128 v[130:133], v146 offset:36864
	ds_read_b128 v[142:145], v146 offset:38912
	s_waitcnt vmcnt(4)
	s_waitcnt lgkmcnt(0)
	s_barrier
	v_or_b32_e32 v146, 0x4000, v188
	v_add_u32_e32 v149, v146, v128
	v_add_u32_e32 v146, v146, v187
	s_waitcnt lgkmcnt(0)
	v_mfma_f32_32x32x16_bf16 v[48:63], v[130:133], v[134:137], v[48:63]
	v_mfma_f32_32x32x16_bf16 v[32:47], v[130:133], v[138:141], v[32:47]
	ds_read_b128 v[130:133], v148
	v_mfma_f32_32x32x16_bf16 v[16:31], v[142:145], v[134:137], v[16:31]
	v_or_b32_e32 v134, 0x10000, v149
	ds_read_b128 v[134:137], v134
	v_mfma_f32_32x32x16_bf16 v[0:15], v[142:145], v[138:141], v[0:15]
	v_add_u32_e32 v138, 0x10800, v149
	ds_read_b128 v[138:141], v138
	ds_read_b128 v[142:145], v148 offset:2048
	s_waitcnt lgkmcnt(0)
	v_mfma_f32_32x32x16_bf16 v[112:127], v[130:133], v[134:137], v[112:127]
	v_mfma_f32_32x32x16_bf16 v[96:111], v[130:133], v[138:141], v[96:111]
	v_mfma_f32_32x32x16_bf16 v[80:95], v[142:145], v[134:137], v[80:95]
	v_mfma_f32_32x32x16_bf16 v[64:79], v[142:145], v[138:141], v[64:79]
	ds_read_b128 v[130:133], v148 offset:4096
	ds_read_b128 v[142:145], v148 offset:6144
	s_waitcnt lgkmcnt(0)
	v_mfma_f32_32x32x16_bf16 v[48:63], v[130:133], v[134:137], v[48:63]
	v_mfma_f32_32x32x16_bf16 v[32:47], v[130:133], v[138:141], v[32:47]
	ds_read_b128 v[130:133], v147
	v_mfma_f32_32x32x16_bf16 v[16:31], v[142:145], v[134:137], v[16:31]
	v_or_b32_e32 v134, 0x10000, v146
	ds_read_b128 v[134:137], v134
	v_mfma_f32_32x32x16_bf16 v[0:15], v[142:145], v[138:141], v[0:15]
	v_add_u32_e32 v138, 0x10800, v146
	ds_read_b128 v[138:141], v138
	ds_read_b128 v[142:145], v147 offset:2048
	s_waitcnt lgkmcnt(0)
	v_mfma_f32_32x32x16_bf16 v[112:127], v[130:133], v[134:137], v[112:127]
	v_mfma_f32_32x32x16_bf16 v[96:111], v[130:133], v[138:141], v[96:111]
	v_mfma_f32_32x32x16_bf16 v[80:95], v[142:145], v[134:137], v[80:95]
	v_mfma_f32_32x32x16_bf16 v[64:79], v[142:145], v[138:141], v[64:79]
	ds_read_b128 v[130:133], v147 offset:4096
	ds_read_b128 v[142:145], v147 offset:6144
	v_add_u32_e32 v147, 0x18000, v186
	s_waitcnt vmcnt(0)
	v_add_u32_e32 v128, v147, v128
	s_waitcnt lgkmcnt(0)
	s_barrier
; DI int my_tid() { int t = threadIdx.x; asm volatile("" : "+v"(t)); return t; }
; #define RAW_BARRIER() do { asm volatile("s_waitcnt lgkmcnt(0)" ::: "memory"); __builtin_amdgcn_s_barrier(); } while (0)
; #define WAIT_VM(n) asm volatile("s_waitcnt vmcnt(" #n ")" ::: "memory")
; template <bool AF32>
; DI void gemm_main(const void* Ap, int lda, const short* Bp, int K, char* smem, f32x16 (&acc)[4][2]) {
;     ...
;   LOADF(F1, (nk - 3) & 3, 1);
;   MM(F0);
;   WAIT_VM(4);
;   RAW_BARRIER();
;   LOADF(F0, (nk - 2) & 3, 0);
;   MM(F1);
;   LOADF(F1, (nk - 2) & 3, 1);
;   MM(F0);
;   WAIT_VM(0);
;   RAW_BARRIER();
;   LOADF(F0, (nk - 1) & 3, 0);
;   MM(F1);
;   LOADF(F1, (nk - 1) & 3, 1);
;   MM(F0);
;   MM(F1);
;   __syncthreads();
; DI void prefetch_ssq(u32x4 (&pre)[8], const float* ssq, int m0) {
;   const int t_ = my_tid() & 255, ln_ = t_ & 63, ww_ = t_ >> 6;
; #pragma unroll
;   for (int s_ = 0; s_ < 8; s_++) pre[s_] = u32x4{__float_as_uint(ssq[m0 + ww_ * 32 + s_ * 4 + (ln_ >> 4)]), 0u, 0u, 0u};
; }
	s_waitcnt lgkmcnt(0)
	v_mfma_f32_32x32x16_bf16 v[48:63], v[130:133], v[134:137], v[48:63]
	v_mfma_f32_32x32x16_bf16 v[32:47], v[130:133], v[138:141], v[32:47]
	ds_read_b128 v[130:133], v128
	v_mfma_f32_32x32x16_bf16 v[0:15], v[142:145], v[138:141], v[0:15]
	v_add_u32_e32 v138, 0x18000, v149
	v_mfma_f32_32x32x16_bf16 v[16:31], v[142:145], v[134:137], v[16:31]
	ds_read_b128 v[134:137], v138
	ds_read_b128 v[138:141], v138 offset:2048
	ds_read_b128 v[142:145], v128 offset:2048
	s_waitcnt lgkmcnt(0)
	v_mfma_f32_32x32x16_bf16 v[112:127], v[130:133], v[134:137], v[112:127]
	v_mfma_f32_32x32x16_bf16 v[96:111], v[130:133], v[138:141], v[96:111]
	v_mfma_f32_32x32x16_bf16 v[80:95], v[142:145], v[134:137], v[80:95]
	v_mfma_f32_32x32x16_bf16 v[64:79], v[142:145], v[138:141], v[64:79]
	ds_read_b128 v[130:133], v128 offset:4096
	ds_read_b128 v[142:145], v128 offset:6144
	v_add_u32_e32 v128, v147, v187
	s_waitcnt lgkmcnt(0)
	v_mfma_f32_32x32x16_bf16 v[48:63], v[130:133], v[134:137], v[48:63]
	v_mfma_f32_32x32x16_bf16 v[32:47], v[130:133], v[138:141], v[32:47]
	ds_read_b128 v[130:133], v128
	v_mfma_f32_32x32x16_bf16 v[0:15], v[142:145], v[138:141], v[0:15]
	v_add_u32_e32 v138, 0x18000, v146
	v_mov_b32_e32 v146, v196
	v_mfma_f32_32x32x16_bf16 v[16:31], v[142:145], v[134:137], v[16:31]
	ds_read_b128 v[134:137], v138
	ds_read_b128 v[138:141], v138 offset:2048
	ds_read_b128 v[142:145], v128 offset:2048
	s_waitcnt lgkmcnt(0)
	v_mfma_f32_32x32x16_bf16 v[112:127], v[130:133], v[134:137], v[112:127]
	v_mfma_f32_32x32x16_bf16 v[96:111], v[130:133], v[138:141], v[96:111]
	v_mfma_f32_32x32x16_bf16 v[80:95], v[142:145], v[134:137], v[80:95]
	v_mfma_f32_32x32x16_bf16 v[64:79], v[142:145], v[138:141], v[64:79]
	ds_read_b128 v[130:133], v128 offset:4096
	ds_read_b128 v[142:145], v128 offset:6144
	v_mov_b32_e32 v128, v196
	s_waitcnt vmcnt(0) lgkmcnt(0)
	s_barrier
	v_mfma_f32_32x32x16_bf16 v[48:63], v[130:133], v[134:137], v[48:63]
	v_mfma_f32_32x32x16_bf16 v[32:47], v[130:133], v[138:141], v[32:47]
	v_lshrrev_b32_e32 v130, 1, v146
	v_and_b32_e32 v130, 0x60, v130
	v_bfe_u32 v131, v146, 4, 2
	v_or3_b32 v130, v131, v130, s56
	v_ashrrev_i32_e32 v131, 31, v130
	v_lshl_add_u64 v[130:131], v[130:131], 2, s[20:21]
	v_mfma_f32_32x32x16_bf16 v[16:31], v[142:145], v[134:137], v[16:31]
	global_load_dword v134, v[130:131], off
	global_load_dword v164, v[130:131], off offset:16
	global_load_dword v159, v[130:131], off offset:32
	global_load_dword v158, v[130:131], off offset:48
	global_load_dword v157, v[130:131], off offset:64
	global_load_dword v156, v[130:131], off offset:80
	global_load_dword v155, v[130:131], off offset:96
	global_load_dword v154, v[130:131], off offset:112
	v_mov_b32_e32 v130, v196
	s_nop 0
	v_cmp_gt_u32_e32 vcc, s49, v130
	v_mfma_f32_32x32x16_bf16 v[0:15], v[142:145], v[138:141], v[0:15]
	s_and_saveexec_b64 s[6:7], vcc
	s_cbranch_execz .LBB0_668
; DI int my_tid() { int t = threadIdx.x; asm volatile("" : "+v"(t)); return t; }
; DI void stage_half(const f32x16 (&acc)[4][2], int pm, char* smem) {
;   const int tid = my_tid(), lane = tid & 63, w = tid >> 6, r = lane & 31, h = lane >> 5;
;   const int wm = w >> 2, wn = w & 3;
;   float* sf = (float*)(smem + (wn >> 1) * SF_BYTES);
;   if (wm == pm) {
; #pragma unroll
;     for (int mi = 0; mi < 4; mi++)
; #pragma unroll
;       for (int ni = 0; ni < 2; ni++)
; #pragma unroll
;         for (int i = 0; i < 16; i++) {
;           int row = mi * 32 + (i & 3) + 8 * (i >> 2) + 4 * h;
;           int col = (wn & 1) * 64 + ni * 32 + r;
;           sf[row * SF_LD + col] = acc[mi][ni][i];
;         }
;   }
;   __syncthreads();
; }
	s_movk_i32 s8, 0x80
	v_cmp_gt_u32_e32 vcc, s8, v130
	v_lshrrev_b32_e32 v132, 3, v130
	v_and_b32_e32 v130, 0x5f, v130
	v_cndmask_b32_e64 v131, v199, 0, vcc
	v_and_b32_e32 v132, 4, v132
	v_lshl_or_b32 v130, v130, 2, v131
	v_mad_u32_u24 v130, v132, s3, v130
	v_add_u32_e32 v131, 0x400, v130
	ds_write2_b32 v130, v112, v96 offset1:32
	ds_write2_b32 v130, v113, v97 offset0:132 offset1:164
	ds_write2_b32 v131, v114, v98 offset0:8 offset1:40
	ds_write2_b32 v131, v115, v99 offset0:140 offset1:172
	v_add_u32_e32 v131, 0x1000, v130
	ds_write2_b32 v131, v116, v100 offset0:32 offset1:64
	ds_write2_b32 v131, v117, v101 offset0:164 offset1:196
	v_add_u32_e32 v131, 0x1400, v130
	ds_write2_b32 v131, v118, v102 offset0:40 offset1:72
	ds_write2_b32 v131, v119, v103 offset0:172 offset1:204
	v_add_u32_e32 v131, 0x2000, v130
	ds_write2_b32 v131, v120, v104 offset0:64 offset1:96
	ds_write2_b32 v131, v121, v105 offset0:196 offset1:228
	v_add_u32_e32 v131, 0x2400, v130
	ds_write2_b32 v131, v122, v106 offset0:72 offset1:104
	ds_write2_b32 v131, v123, v107 offset0:204 offset1:236
	v_add_u32_e32 v131, 0x3000, v130
	ds_write2_b32 v131, v124, v108 offset0:96 offset1:128
	v_add_u32_e32 v131, 0x3200, v130
	ds_write2_b32 v131, v125, v109 offset0:100 offset1:132
	v_add_u32_e32 v131, 0x3400, v130
	ds_write2_b32 v131, v126, v110 offset0:104 offset1:136
	v_add_u32_e32 v131, 0x3600, v130
	ds_write2_b32 v131, v127, v111 offset0:108 offset1:140
	v_add_u32_e32 v131, 0x4000, v130
	ds_write2_b32 v131, v80, v64 offset0:128 offset1:160
	v_add_u32_e32 v131, 0x4400, v130
	ds_write2_b32 v131, v81, v65 offset0:4 offset1:36
	ds_write2_b32 v131, v82, v66 offset0:136 offset1:168
	v_add_u32_e32 v131, 0x4800, v130
	ds_write2_b32 v131, v83, v67 offset0:12 offset1:44
	v_add_u32_e32 v131, 0x5000, v130
	ds_write2_b32 v131, v84, v68 offset0:160 offset1:192
	v_add_u32_e32 v131, 0x5400, v130
	ds_write2_b32 v131, v85, v69 offset0:36 offset1:68
	ds_write2_b32 v131, v86, v70 offset0:168 offset1:200
	v_add_u32_e32 v131, 0x5800, v130
	ds_write2_b32 v131, v87, v71 offset0:44 offset1:76
	v_add_u32_e32 v131, 0x6000, v130
	ds_write2_b32 v131, v88, v72 offset0:192 offset1:224
	v_add_u32_e32 v131, 0x6400, v130
	ds_write2_b32 v131, v89, v73 offset0:68 offset1:100
	ds_write2_b32 v131, v90, v74 offset0:200 offset1:232
	v_add_u32_e32 v131, 0x6800, v130
	ds_write2_b32 v131, v91, v75 offset0:76 offset1:108
	v_add_u32_e32 v131, 0x7200, v130
	ds_write2_b32 v131, v92, v76 offset0:96 offset1:128
	v_add_u32_e32 v131, 0x7400, v130
	ds_write2_b32 v131, v93, v77 offset0:100 offset1:132
	v_add_u32_e32 v131, 0x7600, v130
	ds_write2_b32 v131, v94, v78 offset0:104 offset1:136
	v_add_u32_e32 v131, 0x7800, v130
	ds_write2_b32 v131, v95, v79 offset0:108 offset1:140
	v_add_u32_e32 v131, 0x8400, v130
	ds_write2_b32 v131, v48, v32 offset1:32
	ds_write2_b32 v131, v49, v33 offset0:132 offset1:164
	v_add_u32_e32 v131, 0x8800, v130
	ds_write2_b32 v131, v50, v34 offset0:8 offset1:40
	ds_write2_b32 v131, v51, v35 offset0:140 offset1:172
	v_add_u32_e32 v131, 0x9400, v130
	ds_write2_b32 v131, v52, v36 offset0:32 offset1:64
	ds_write2_b32 v131, v53, v37 offset0:164 offset1:196
	v_add_u32_e32 v131, 0x9800, v130
	ds_write2_b32 v131, v54, v38 offset0:40 offset1:72
	ds_write2_b32 v131, v55, v39 offset0:172 offset1:204
	v_add_u32_e32 v131, 0xa400, v130
	ds_write2_b32 v131, v56, v40 offset0:64 offset1:96
	ds_write2_b32 v131, v57, v41 offset0:196 offset1:228
	v_add_u32_e32 v131, 0xa800, v130
	ds_write2_b32 v131, v58, v42 offset0:72 offset1:104
	ds_write2_b32 v131, v59, v43 offset0:204 offset1:236
	v_add_u32_e32 v131, 0xb400, v130
	ds_write2_b32 v131, v60, v44 offset0:96 offset1:128
	v_add_u32_e32 v131, 0xb600, v130
	ds_write2_b32 v131, v61, v45 offset0:100 offset1:132
	v_add_u32_e32 v131, 0xb800, v130
	ds_write2_b32 v131, v62, v46 offset0:104 offset1:136
	v_add_u32_e32 v131, 0xba00, v130
	ds_write2_b32 v131, v63, v47 offset0:108 offset1:140
	v_add_u32_e32 v131, 0xc400, v130
	ds_write2_b32 v131, v16, v0 offset0:128 offset1:160
	v_add_u32_e32 v131, 0xc800, v130
	ds_write2_b32 v131, v17, v1 offset0:4 offset1:36
	ds_write2_b32 v131, v18, v2 offset0:136 offset1:168
	v_add_u32_e32 v131, 0xcc00, v130
	ds_write2_b32 v131, v19, v3 offset0:12 offset1:44
	v_add_u32_e32 v131, 0xd400, v130
	ds_write2_b32 v131, v20, v4 offset0:160 offset1:192
	v_add_u32_e32 v131, 0xd800, v130
	ds_write2_b32 v131, v21, v5 offset0:36 offset1:68
	ds_write2_b32 v131, v22, v6 offset0:168 offset1:200
	v_add_u32_e32 v131, 0xdc00, v130
	ds_write2_b32 v131, v23, v7 offset0:44 offset1:76
	v_add_u32_e32 v131, 0xe400, v130
	ds_write2_b32 v131, v24, v8 offset0:192 offset1:224
	v_add_u32_e32 v131, 0xe800, v130
	ds_write2_b32 v131, v25, v9 offset0:68 offset1:100
	ds_write2_b32 v131, v26, v10 offset0:200 offset1:232
	v_add_u32_e32 v131, 0xec00, v130
	ds_write2_b32 v131, v27, v11 offset0:76 offset1:108
	v_add_u32_e32 v131, 0xf600, v130
	ds_write2_b32 v131, v28, v12 offset0:96 offset1:128
	v_add_u32_e32 v131, 0xf800, v130
	ds_write2_b32 v131, v29, v13 offset0:100 offset1:132
	v_add_u32_e32 v131, 0xfa00, v130
	v_add_u32_e32 v130, 0xfc00, v130
	ds_write2_b32 v131, v30, v14 offset0:104 offset1:136
	ds_write2_b32 v130, v31, v15 offset0:108 offset1:140

; #define RAW_BARRIER() do { asm volatile("s_waitcnt lgkmcnt(0)" ::: "memory"); __builtin_amdgcn_s_barrier(); } while (0)
; #define WAIT_VM(n) asm volatile("s_waitcnt vmcnt(" #n ")" ::: "memory")
; template <bool AF32>
; DI void gemm_main(const void* Ap, int lda, const short* Bp, int K, char* smem, f32x16 (&acc)[4][2]) {
;     ...
;   const int x = (r >> 2) & 3;
;   const int off0 = ((h ^ x) << 4);
;   const int aoff = (wm * 128 + r) * 64, boff = GBOFF + (wn * 64 + r) * 64;
;   struct Frag { bf16x8 a[4], b0, b1; };
;     ...
;   const int nk = K >> 5;
;   Frag F0, F1;
;   GLDS(0, 0);
;   GLDS(1, 1);
;   GLDS(2, 2);
;   GLDS(3, 3);
;   WAIT_VM(12);
;   RAW_BARRIER();
;   LOADF(F0, 0, 0);
;   for (int kt = 0; kt < nk - 3; kt++) {
;     LOADF(F1, kt & 3, 1);
;     MM(F0);
;     WAIT_VM(8);
;     RAW_BARRIER();
;     if (kt + 4 < nk) GLDS(kt + 4, kt & 3);
;     LOADF(F0, (kt + 1) & 3, 0);
;     MM(F1);
;   }
.LBB0_768:
	s_and_b32 s9, s8, 0x10000
	s_waitcnt lgkmcnt(0)
	v_mfma_f32_32x32x16_bf16 v[16:31], v[130:133], v[138:141], v[16:31]
	v_or_b32_e32 v154, s9, v188
	v_add3_u32 v158, s9, v186, v187
	v_add_u32_e32 v154, v154, v187
	ds_read_b128 v[162:165], v154 offset:16384
	ds_read_b128 v[154:157], v154 offset:18432
	ds_read_b128 v[174:177], v158
	ds_read_b128 v[170:173], v158 offset:2048
	ds_read_b128 v[166:169], v158 offset:4096
	ds_read_b128 v[158:161], v158 offset:6144
	v_lshl_add_u64 v[184:185], v[178:179], 0, s[6:7]
	v_mfma_f32_32x32x16_bf16 v[0:15], v[130:133], v[134:137], v[0:15]
	v_lshl_add_u64 v[182:183], v[180:181], 0, s[6:7]
	v_lshl_add_u64 v[132:133], v[182:183], 0, s[78:79]
	v_lshl_add_u64 v[130:131], v[182:183], 0, s[76:77]
	v_mfma_f32_32x32x16_bf16 v[112:127], v[150:153], v[138:141], v[112:127]
	v_mfma_f32_32x32x16_bf16 v[80:95], v[146:149], v[138:141], v[80:95]
	v_mfma_f32_32x32x16_bf16 v[48:63], v[142:145], v[138:141], v[48:63]
	v_add_u32_e32 v138, s9, v189
	v_add_u32_e32 v141, 0x400, v138
	v_readfirstlane_b32 s9, v138
	v_add_u32_e32 v140, 0x4000, v138
	s_mov_b32 m0, s9
	v_readfirstlane_b32 s9, v141
	v_add_u32_e32 v139, 0x4400, v138
	v_mfma_f32_32x32x16_bf16 v[96:111], v[150:153], v[134:137], v[96:111]
	v_mfma_f32_32x32x16_bf16 v[64:79], v[146:149], v[134:137], v[64:79]
	v_mfma_f32_32x32x16_bf16 v[32:47], v[142:145], v[134:137], v[32:47]
	v_lshl_add_u64 v[136:137], v[184:185], 0, s[78:79]
	v_lshl_add_u64 v[134:135], v[184:185], 0, s[76:77]
	s_waitcnt vmcnt(8)
	s_waitcnt lgkmcnt(0)
	s_barrier
	global_load_lds_dwordx4 v[136:137], off
	s_mov_b32 m0, s9
	v_readfirstlane_b32 s9, v140
	global_load_lds_dwordx4 v[134:135], off
	s_mov_b32 m0, s9
	v_readfirstlane_b32 s9, v139
	global_load_lds_dwordx4 v[132:133], off
	s_mov_b32 m0, s9
	s_add_i32 s9, s8, 0x8000
	s_and_b32 s9, s9, 0x18000
	s_waitcnt lgkmcnt(0)
	v_mfma_f32_32x32x16_bf16 v[16:31], v[158:161], v[162:165], v[16:31]
	v_add_u32_e32 v190, s9, v186
	v_or_b32_e32 v191, s9, v188
	global_load_lds_dwordx4 v[130:131], off
	v_add_u32_e32 v138, v190, v128
	v_add_u32_e32 v130, v191, v128
	ds_read_b128 v[134:137], v130 offset:16384
	ds_read_b128 v[130:133], v130 offset:18432
	ds_read_b128 v[150:153], v138
	ds_read_b128 v[146:149], v138 offset:2048
	ds_read_b128 v[142:145], v138 offset:4096
	ds_read_b128 v[138:141], v138 offset:6144
	v_mfma_f32_32x32x16_bf16 v[0:15], v[158:161], v[154:157], v[0:15]
	v_add_u32_e32 v158, v190, v187
	s_add_i32 s8, s8, 0x10000
	v_mfma_f32_32x32x16_bf16 v[112:127], v[174:177], v[162:165], v[112:127]
	v_mfma_f32_32x32x16_bf16 v[80:95], v[170:173], v[162:165], v[80:95]
	v_mfma_f32_32x32x16_bf16 v[48:63], v[166:169], v[162:165], v[48:63]
	v_mfma_f32_32x32x16_bf16 v[96:111], v[174:177], v[154:157], v[96:111]
	v_mfma_f32_32x32x16_bf16 v[64:79], v[170:173], v[154:157], v[64:79]
	v_mfma_f32_32x32x16_bf16 v[32:47], v[166:169], v[154:157], v[32:47]
	v_add_u32_e32 v154, v191, v187
	ds_read_b128 v[162:165], v154 offset:16384
	ds_read_b128 v[154:157], v154 offset:18432
	ds_read_b128 v[190:193], v158
	ds_read_b128 v[170:173], v158 offset:2048
	ds_read_b128 v[166:169], v158 offset:4096
	ds_read_b128 v[158:161], v158 offset:6144
	s_waitcnt lgkmcnt(6)
	v_mfma_f32_32x32x16_bf16 v[16:31], v[138:141], v[134:137], v[16:31]
	v_mfma_f32_32x32x16_bf16 v[0:15], v[138:141], v[130:133], v[0:15]
	v_add_u32_e32 v138, s9, v189
	v_add_u32_e32 v141, 0x400, v138
	v_readfirstlane_b32 s9, v138
	v_add_u32_e32 v140, 0x4000, v138
	s_mov_b32 m0, s9
	v_readfirstlane_b32 s9, v141
	v_add_u32_e32 v139, 0x4400, v138
	v_mfma_f32_32x32x16_bf16 v[112:127], v[150:153], v[134:137], v[112:127]
	v_mfma_f32_32x32x16_bf16 v[80:95], v[146:149], v[134:137], v[80:95]
	v_mfma_f32_32x32x16_bf16 v[48:63], v[142:145], v[134:137], v[48:63]
	v_lshl_add_u64 v[136:137], v[184:185], 0, s[82:83]
	v_lshl_add_u64 v[134:135], v[184:185], 0, s[80:81]
	s_waitcnt vmcnt(8)
	s_waitcnt lgkmcnt(0)
	s_barrier
	global_load_lds_dwordx4 v[136:137], off
	s_mov_b32 m0, s9
	v_readfirstlane_b32 s9, v140
	global_load_lds_dwordx4 v[134:135], off
	v_mfma_f32_32x32x16_bf16 v[96:111], v[150:153], v[130:133], v[96:111]
	s_mov_b32 m0, s9
	v_readfirstlane_b32 s9, v139
	v_mfma_f32_32x32x16_bf16 v[64:79], v[146:149], v[130:133], v[64:79]
	v_mfma_f32_32x32x16_bf16 v[32:47], v[142:145], v[130:133], v[32:47]
	v_lshl_add_u64 v[132:133], v[182:183], 0, s[82:83]
	v_lshl_add_u64 v[130:131], v[182:183], 0, s[80:81]
	global_load_lds_dwordx4 v[132:133], off
	s_mov_b32 m0, s9
	s_and_b32 s9, s8, 0x10000
	global_load_lds_dwordx4 v[130:131], off
	v_add_u32_e32 v174, s9, v186
	v_or_b32_e32 v131, s9, v188
	v_add_u32_e32 v130, v174, v128
	v_add_u32_e32 v131, v131, v128
	ds_read_b128 v[138:141], v131 offset:16384
	ds_read_b128 v[134:137], v131 offset:18432
	ds_read_b128 v[150:153], v130
	ds_read_b128 v[146:149], v130 offset:2048
	ds_read_b128 v[142:145], v130 offset:4096
	ds_read_b128 v[130:133], v130 offset:6144
	v_mfma_f32_32x32x16_bf16 v[112:127], v[190:193], v[162:165], v[112:127]
	s_add_u32 s6, s6, 0x80
	s_addc_u32 s7, s7, 0
	s_cmpk_eq_i32 s6, 0x700
	v_mfma_f32_32x32x16_bf16 v[96:111], v[190:193], v[154:157], v[96:111]
	v_mfma_f32_32x32x16_bf16 v[80:95], v[170:173], v[162:165], v[80:95]
	v_mfma_f32_32x32x16_bf16 v[64:79], v[170:173], v[154:157], v[64:79]
	v_mfma_f32_32x32x16_bf16 v[48:63], v[166:169], v[162:165], v[48:63]
	v_mfma_f32_32x32x16_bf16 v[32:47], v[166:169], v[154:157], v[32:47]
	v_mfma_f32_32x32x16_bf16 v[16:31], v[158:161], v[162:165], v[16:31]
	v_mfma_f32_32x32x16_bf16 v[0:15], v[158:161], v[154:157], v[0:15]
	s_cbranch_scc0 .LBB0_768
; #define RAW_BARRIER() do { asm volatile("s_waitcnt lgkmcnt(0)" ::: "memory"); __builtin_amdgcn_s_barrier(); } while (0)
; #define WAIT_VM(n) asm volatile("s_waitcnt vmcnt(" #n ")" ::: "memory")
; template <bool AF32>
; DI void gemm_main(const void* Ap, int lda, const short* Bp, int K, char* smem, f32x16 (&acc)[4][2]) {
;     ...
;   LOADF(F1, (nk - 3) & 3, 1);
;   MM(F0);
;   WAIT_VM(4);
;   RAW_BARRIER();
;   LOADF(F0, (nk - 2) & 3, 0);
;   MM(F1);
;   LOADF(F1, (nk - 2) & 3, 1);
;   MM(F0);
;   WAIT_VM(0);
;   RAW_BARRIER();
;   LOADF(F0, (nk - 1) & 3, 0);
;   MM(F1);
;   LOADF(F1, (nk - 1) & 3, 1);
;   MM(F0);
;   MM(F1);
;   __syncthreads();
	s_waitcnt lgkmcnt(0)
	v_mfma_f32_32x32x16_bf16 v[80:95], v[146:149], v[138:141], v[80:95]
	s_lshl_b32 s88, s86, 8
	v_mfma_f32_32x32x16_bf16 v[64:79], v[146:149], v[134:137], v[64:79]
	v_add_u32_e32 v146, v174, v187
	v_add_u32_e32 v147, v188, v187
	v_mfma_f32_32x32x16_bf16 v[16:31], v[130:133], v[138:141], v[16:31]
	v_mfma_f32_32x32x16_bf16 v[0:15], v[130:133], v[134:137], v[0:15]
	ds_read_b128 v[130:133], v146
	v_mfma_f32_32x32x16_bf16 v[112:127], v[150:153], v[138:141], v[112:127]
	v_mfma_f32_32x32x16_bf16 v[96:111], v[150:153], v[134:137], v[96:111]
	v_mfma_f32_32x32x16_bf16 v[48:63], v[142:145], v[138:141], v[48:63]
	v_mfma_f32_32x32x16_bf16 v[32:47], v[142:145], v[134:137], v[32:47]
	ds_read_b128 v[134:137], v147 offset:16384
	ds_read_b128 v[138:141], v147 offset:18432
	ds_read_b128 v[142:145], v146 offset:2048
	s_waitcnt lgkmcnt(0)
	v_mfma_f32_32x32x16_bf16 v[112:127], v[130:133], v[134:137], v[112:127]
	v_mfma_f32_32x32x16_bf16 v[96:111], v[130:133], v[138:141], v[96:111]
	v_mfma_f32_32x32x16_bf16 v[80:95], v[142:145], v[134:137], v[80:95]
	v_mfma_f32_32x32x16_bf16 v[64:79], v[142:145], v[138:141], v[64:79]
	ds_read_b128 v[130:133], v146 offset:4096
	ds_read_b128 v[142:145], v146 offset:6144
	s_waitcnt vmcnt(8)
	v_add_u32_e32 v146, v186, v128
	s_waitcnt lgkmcnt(0)
	s_barrier
	s_waitcnt lgkmcnt(0)
	v_mfma_f32_32x32x16_bf16 v[48:63], v[130:133], v[134:137], v[48:63]
	v_mfma_f32_32x32x16_bf16 v[32:47], v[130:133], v[138:141], v[32:47]
	ds_read_b128 v[130:133], v146 offset:32768
	v_mfma_f32_32x32x16_bf16 v[0:15], v[142:145], v[138:141], v[0:15]
	v_add_u32_e32 v138, v188, v128
	v_mfma_f32_32x32x16_bf16 v[16:31], v[142:145], v[134:137], v[16:31]
	ds_read_b128 v[134:137], v138 offset:49152
	ds_read_b128 v[138:141], v138 offset:51200
	ds_read_b128 v[142:145], v146 offset:34816
	s_waitcnt lgkmcnt(0)
	v_mfma_f32_32x32x16_bf16 v[112:127], v[130:133], v[134:137], v[112:127]
	v_mfma_f32_32x32x16_bf16 v[96:111], v[130:133], v[138:141], v[96:111]
	v_mfma_f32_32x32x16_bf16 v[80:95], v[142:145], v[134:137], v[80:95]
	v_mfma_f32_32x32x16_bf16 v[64:79], v[142:145], v[138:141], v[64:79]
	ds_read_b128 v[130:133], v146 offset:36864
	ds_read_b128 v[142:145], v146 offset:38912
	v_add_u32_e32 v146, v186, v187
	s_waitcnt lgkmcnt(0)
	v_mfma_f32_32x32x16_bf16 v[48:63], v[130:133], v[134:137], v[48:63]
	v_mfma_f32_32x32x16_bf16 v[32:47], v[130:133], v[138:141], v[32:47]
	v_mfma_f32_32x32x16_bf16 v[16:31], v[142:145], v[134:137], v[16:31]
	v_mfma_f32_32x32x16_bf16 v[0:15], v[142:145], v[138:141], v[0:15]
	ds_read_b128 v[130:133], v146 offset:32768
	ds_read_b128 v[134:137], v147 offset:49152
	ds_read_b128 v[138:141], v147 offset:51200
	ds_read_b128 v[142:145], v146 offset:34816
	v_add_u32_e32 v147, 0x10000, v186
	v_add_u32_e32 v148, v147, v128
	v_add_u32_e32 v147, v147, v187
	s_waitcnt lgkmcnt(0)
	v_mfma_f32_32x32x16_bf16 v[112:127], v[130:133], v[134:137], v[112:127]
	v_mfma_f32_32x32x16_bf16 v[96:111], v[130:133], v[138:141], v[96:111]
	v_mfma_f32_32x32x16_bf16 v[80:95], v[142:145], v[134:137], v[80:95]
	v_mfma_f32_32x32x16_bf16 v[64:79], v[142:145], v[138:141], v[64:79]
	ds_read_b128 v[130:133], v146 offset:36864
	ds_read_b128 v[142:145], v146 offset:38912
	s_waitcnt vmcnt(4)
	s_waitcnt lgkmcnt(0)
	s_barrier
	v_or_b32_e32 v146, 0x4000, v188
	v_add_u32_e32 v149, v146, v128
	v_add_u32_e32 v146, v146, v187
	s_waitcnt lgkmcnt(0)
	v_mfma_f32_32x32x16_bf16 v[48:63], v[130:133], v[134:137], v[48:63]
	v_mfma_f32_32x32x16_bf16 v[32:47], v[130:133], v[138:141], v[32:47]
	ds_read_b128 v[130:133], v148
	v_mfma_f32_32x32x16_bf16 v[16:31], v[142:145], v[134:137], v[16:31]
	v_or_b32_e32 v134, 0x10000, v149
	ds_read_b128 v[134:137], v134
	v_mfma_f32_32x32x16_bf16 v[0:15], v[142:145], v[138:141], v[0:15]
	v_add_u32_e32 v138, 0x10800, v149
	ds_read_b128 v[138:141], v138
	ds_read_b128 v[142:145], v148 offset:2048
	s_waitcnt lgkmcnt(0)
	v_mfma_f32_32x32x16_bf16 v[112:127], v[130:133], v[134:137], v[112:127]
	v_mfma_f32_32x32x16_bf16 v[96:111], v[130:133], v[138:141], v[96:111]
	v_mfma_f32_32x32x16_bf16 v[80:95], v[142:145], v[134:137], v[80:95]
	v_mfma_f32_32x32x16_bf16 v[64:79], v[142:145], v[138:141], v[64:79]
	ds_read_b128 v[130:133], v148 offset:4096
	ds_read_b128 v[142:145], v148 offset:6144
	s_waitcnt lgkmcnt(0)
	v_mfma_f32_32x32x16_bf16 v[48:63], v[130:133], v[134:137], v[48:63]
	v_mfma_f32_32x32x16_bf16 v[32:47], v[130:133], v[138:141], v[32:47]
	ds_read_b128 v[130:133], v147
	v_mfma_f32_32x32x16_bf16 v[16:31], v[142:145], v[134:137], v[16:31]
	v_or_b32_e32 v134, 0x10000, v146
	ds_read_b128 v[134:137], v134
	v_mfma_f32_32x32x16_bf16 v[0:15], v[142:145], v[138:141], v[0:15]
	v_add_u32_e32 v138, 0x10800, v146
	ds_read_b128 v[138:141], v138
	ds_read_b128 v[142:145], v147 offset:2048
	s_waitcnt lgkmcnt(0)
	v_mfma_f32_32x32x16_bf16 v[112:127], v[130:133], v[134:137], v[112:127]
	v_mfma_f32_32x32x16_bf16 v[96:111], v[130:133], v[138:141], v[96:111]
	v_mfma_f32_32x32x16_bf16 v[80:95], v[142:145], v[134:137], v[80:95]
	v_mfma_f32_32x32x16_bf16 v[64:79], v[142:145], v[138:141], v[64:79]
	ds_read_b128 v[130:133], v147 offset:4096
	ds_read_b128 v[142:145], v147 offset:6144
	v_add_u32_e32 v147, 0x18000, v186
	s_waitcnt vmcnt(0)
	v_add_u32_e32 v128, v147, v128
	s_waitcnt lgkmcnt(0)
	s_barrier
; DI int my_tid() { int t = threadIdx.x; asm volatile("" : "+v"(t)); return t; }
; #define RAW_BARRIER() do { asm volatile("s_waitcnt lgkmcnt(0)" ::: "memory"); __builtin_amdgcn_s_barrier(); } while (0)
; #define WAIT_VM(n) asm volatile("s_waitcnt vmcnt(" #n ")" ::: "memory")
; template <bool AF32>
; DI void gemm_main(const void* Ap, int lda, const short* Bp, int K, char* smem, f32x16 (&acc)[4][2]) {
;     ...
;   LOADF(F1, (nk - 3) & 3, 1);
;   MM(F0);
;   WAIT_VM(4);
;   RAW_BARRIER();
;   LOADF(F0, (nk - 2) & 3, 0);
;   MM(F1);
;   LOADF(F1, (nk - 2) & 3, 1);
;   MM(F0);
;   WAIT_VM(0);
;   RAW_BARRIER();
;   LOADF(F0, (nk - 1) & 3, 0);
;   MM(F1);
;   LOADF(F1, (nk - 1) & 3, 1);
;   MM(F0);
;   MM(F1);
;   __syncthreads();
; DI void prefetch_ssq(u32x4 (&pre)[8], const float* ssq, int m0) {
;   const int t_ = my_tid() & 255, ln_ = t_ & 63, ww_ = t_ >> 6;
; #pragma unroll
;   for (int s_ = 0; s_ < 8; s_++) pre[s_] = u32x4{__float_as_uint(ssq[m0 + ww_ * 32 + s_ * 4 + (ln_ >> 4)]), 0u, 0u, 0u};
; }
	s_waitcnt lgkmcnt(0)
	v_mfma_f32_32x32x16_bf16 v[48:63], v[130:133], v[134:137], v[48:63]
	v_mfma_f32_32x32x16_bf16 v[32:47], v[130:133], v[138:141], v[32:47]
	ds_read_b128 v[130:133], v128
	v_mfma_f32_32x32x16_bf16 v[0:15], v[142:145], v[138:141], v[0:15]
	v_add_u32_e32 v138, 0x18000, v149
	v_mfma_f32_32x32x16_bf16 v[16:31], v[142:145], v[134:137], v[16:31]
	ds_read_b128 v[134:137], v138
	ds_read_b128 v[138:141], v138 offset:2048
	ds_read_b128 v[142:145], v128 offset:2048
	s_waitcnt lgkmcnt(0)
	v_mfma_f32_32x32x16_bf16 v[112:127], v[130:133], v[134:137], v[112:127]
	v_mfma_f32_32x32x16_bf16 v[96:111], v[130:133], v[138:141], v[96:111]
	v_mfma_f32_32x32x16_bf16 v[80:95], v[142:145], v[134:137], v[80:95]
	v_mfma_f32_32x32x16_bf16 v[64:79], v[142:145], v[138:141], v[64:79]
	ds_read_b128 v[130:133], v128 offset:4096
	ds_read_b128 v[142:145], v128 offset:6144
	v_add_u32_e32 v128, v147, v187
	s_waitcnt lgkmcnt(0)
	v_mfma_f32_32x32x16_bf16 v[48:63], v[130:133], v[134:137], v[48:63]
	v_mfma_f32_32x32x16_bf16 v[32:47], v[130:133], v[138:141], v[32:47]
	ds_read_b128 v[130:133], v128
	v_mfma_f32_32x32x16_bf16 v[0:15], v[142:145], v[138:141], v[0:15]
	v_add_u32_e32 v138, 0x18000, v146
	v_mfma_f32_32x32x16_bf16 v[16:31], v[142:145], v[134:137], v[16:31]
	ds_read_b128 v[134:137], v138
	ds_read_b128 v[138:141], v138 offset:2048
	ds_read_b128 v[142:145], v128 offset:2048
	s_waitcnt lgkmcnt(0)
	v_mfma_f32_32x32x16_bf16 v[112:127], v[130:133], v[134:137], v[112:127]
	v_mfma_f32_32x32x16_bf16 v[96:111], v[130:133], v[138:141], v[96:111]
	v_mov_b32_e32 v130, v196
	v_mfma_f32_32x32x16_bf16 v[80:95], v[142:145], v[134:137], v[80:95]
	v_mfma_f32_32x32x16_bf16 v[64:79], v[142:145], v[138:141], v[64:79]
	ds_read_b128 v[142:145], v128 offset:4096
	ds_read_b128 v[146:149], v128 offset:6144
	v_mov_b32_e32 v128, v196
	s_waitcnt vmcnt(0) lgkmcnt(0)
	s_barrier
	v_mfma_f32_32x32x16_bf16 v[48:63], v[142:145], v[134:137], v[48:63]
	v_lshrrev_b32_e32 v131, 1, v128
	v_and_b32_e32 v131, 0x60, v131
	v_bfe_u32 v128, v128, 4, 2
	v_or3_b32 v132, v128, v131, s88
	v_ashrrev_i32_e32 v133, 31, v132
	v_lshl_add_u64 v[132:133], v[132:133], 2, s[20:21]
	global_load_dword v128, v[132:133], off
	global_load_dword v164, v[132:133], off offset:16
	global_load_dword v160, v[132:133], off offset:32
	global_load_dword v159, v[132:133], off offset:48
	global_load_dword v158, v[132:133], off offset:64
	global_load_dword v157, v[132:133], off offset:80
	global_load_dword v156, v[132:133], off offset:96
	global_load_dword v155, v[132:133], off offset:112
	v_mfma_f32_32x32x16_bf16 v[32:47], v[142:145], v[138:141], v[32:47]
	v_mov_b32_e32 v131, v196
	s_nop 0
	v_cmp_gt_u32_e32 vcc, s49, v131
	v_mfma_f32_32x32x16_bf16 v[16:31], v[146:149], v[134:137], v[16:31]
	v_mfma_f32_32x32x16_bf16 v[0:15], v[146:149], v[138:141], v[0:15]
	s_and_saveexec_b64 s[6:7], vcc
	s_cbranch_execz .LBB0_771
; DI int my_tid() { int t = threadIdx.x; asm volatile("" : "+v"(t)); return t; }
; DI void stage_half(const f32x16 (&acc)[4][2], int pm, char* smem) {
;   const int tid = my_tid(), lane = tid & 63, w = tid >> 6, r = lane & 31, h = lane >> 5;
;   const int wm = w >> 2, wn = w & 3;
;   float* sf = (float*)(smem + (wn >> 1) * SF_BYTES);
;   if (wm == pm) {
; #pragma unroll
;     for (int mi = 0; mi < 4; mi++)
; #pragma unroll
;       for (int ni = 0; ni < 2; ni++)
; #pragma unroll
;         for (int i = 0; i < 16; i++) {
;           int row = mi * 32 + (i & 3) + 8 * (i >> 2) + 4 * h;
;           int col = (wn & 1) * 64 + ni * 32 + r;
;           sf[row * SF_LD + col] = acc[mi][ni][i];
;         }
;   }
;   __syncthreads();
; }
	s_movk_i32 s8, 0x80
	v_cmp_gt_u32_e32 vcc, s8, v131
	v_lshrrev_b32_e32 v133, 3, v131
	v_and_b32_e32 v131, 0x5f, v131
	v_cndmask_b32_e64 v132, v199, 0, vcc
	v_and_b32_e32 v133, 4, v133
	v_lshl_or_b32 v131, v131, 2, v132
	v_mad_u32_u24 v131, v133, s3, v131
	v_add_u32_e32 v132, 0x400, v131
	ds_write2_b32 v131, v112, v96 offset1:32
	ds_write2_b32 v131, v113, v97 offset0:132 offset1:164
	ds_write2_b32 v132, v114, v98 offset0:8 offset1:40
	ds_write2_b32 v132, v115, v99 offset0:140 offset1:172
	v_add_u32_e32 v132, 0x1000, v131
	ds_write2_b32 v132, v116, v100 offset0:32 offset1:64
	ds_write2_b32 v132, v117, v101 offset0:164 offset1:196
	v_add_u32_e32 v132, 0x1400, v131
	ds_write2_b32 v132, v118, v102 offset0:40 offset1:72
	ds_write2_b32 v132, v119, v103 offset0:172 offset1:204
	v_add_u32_e32 v132, 0x2000, v131
	ds_write2_b32 v132, v120, v104 offset0:64 offset1:96
	ds_write2_b32 v132, v121, v105 offset0:196 offset1:228
	v_add_u32_e32 v132, 0x2400, v131
	ds_write2_b32 v132, v122, v106 offset0:72 offset1:104
	ds_write2_b32 v132, v123, v107 offset0:204 offset1:236
	v_add_u32_e32 v132, 0x3000, v131
	ds_write2_b32 v132, v124, v108 offset0:96 offset1:128
	v_add_u32_e32 v132, 0x3200, v131
	ds_write2_b32 v132, v125, v109 offset0:100 offset1:132
	v_add_u32_e32 v132, 0x3400, v131
	ds_write2_b32 v132, v126, v110 offset0:104 offset1:136
	v_add_u32_e32 v132, 0x3600, v131
	ds_write2_b32 v132, v127, v111 offset0:108 offset1:140
	v_add_u32_e32 v132, 0x4000, v131
	ds_write2_b32 v132, v80, v64 offset0:128 offset1:160
	v_add_u32_e32 v132, 0x4400, v131
	ds_write2_b32 v132, v81, v65 offset0:4 offset1:36
	ds_write2_b32 v132, v82, v66 offset0:136 offset1:168
	v_add_u32_e32 v132, 0x4800, v131
	ds_write2_b32 v132, v83, v67 offset0:12 offset1:44
	v_add_u32_e32 v132, 0x5000, v131
	ds_write2_b32 v132, v84, v68 offset0:160 offset1:192
	v_add_u32_e32 v132, 0x5400, v131
	ds_write2_b32 v132, v85, v69 offset0:36 offset1:68
	ds_write2_b32 v132, v86, v70 offset0:168 offset1:200
	v_add_u32_e32 v132, 0x5800, v131
	ds_write2_b32 v132, v87, v71 offset0:44 offset1:76
	v_add_u32_e32 v132, 0x6000, v131
	ds_write2_b32 v132, v88, v72 offset0:192 offset1:224
	v_add_u32_e32 v132, 0x6400, v131
	ds_write2_b32 v132, v89, v73 offset0:68 offset1:100
	ds_write2_b32 v132, v90, v74 offset0:200 offset1:232
	v_add_u32_e32 v132, 0x6800, v131
	ds_write2_b32 v132, v91, v75 offset0:76 offset1:108
	v_add_u32_e32 v132, 0x7200, v131
	ds_write2_b32 v132, v92, v76 offset0:96 offset1:128
	v_add_u32_e32 v132, 0x7400, v131
	ds_write2_b32 v132, v93, v77 offset0:100 offset1:132
	v_add_u32_e32 v132, 0x7600, v131
	ds_write2_b32 v132, v94, v78 offset0:104 offset1:136
	v_add_u32_e32 v132, 0x7800, v131
	ds_write2_b32 v132, v95, v79 offset0:108 offset1:140
	v_add_u32_e32 v132, 0x8400, v131
	ds_write2_b32 v132, v48, v32 offset1:32
	ds_write2_b32 v132, v49, v33 offset0:132 offset1:164
	v_add_u32_e32 v132, 0x8800, v131
	ds_write2_b32 v132, v50, v34 offset0:8 offset1:40
	ds_write2_b32 v132, v51, v35 offset0:140 offset1:172
	v_add_u32_e32 v132, 0x9400, v131
	ds_write2_b32 v132, v52, v36 offset0:32 offset1:64
	ds_write2_b32 v132, v53, v37 offset0:164 offset1:196
	v_add_u32_e32 v132, 0x9800, v131
	ds_write2_b32 v132, v54, v38 offset0:40 offset1:72
	ds_write2_b32 v132, v55, v39 offset0:172 offset1:204
	v_add_u32_e32 v132, 0xa400, v131
	ds_write2_b32 v132, v56, v40 offset0:64 offset1:96
	ds_write2_b32 v132, v57, v41 offset0:196 offset1:228
	v_add_u32_e32 v132, 0xa800, v131
	ds_write2_b32 v132, v58, v42 offset0:72 offset1:104
	ds_write2_b32 v132, v59, v43 offset0:204 offset1:236
	v_add_u32_e32 v132, 0xb400, v131
	ds_write2_b32 v132, v60, v44 offset0:96 offset1:128
	v_add_u32_e32 v132, 0xb600, v131
	ds_write2_b32 v132, v61, v45 offset0:100 offset1:132
	v_add_u32_e32 v132, 0xb800, v131
	ds_write2_b32 v132, v62, v46 offset0:104 offset1:136
	v_add_u32_e32 v132, 0xba00, v131
	ds_write2_b32 v132, v63, v47 offset0:108 offset1:140
	v_add_u32_e32 v132, 0xc400, v131
	ds_write2_b32 v132, v16, v0 offset0:128 offset1:160
	v_add_u32_e32 v132, 0xc800, v131
	ds_write2_b32 v132, v17, v1 offset0:4 offset1:36
	ds_write2_b32 v132, v18, v2 offset0:136 offset1:168
	v_add_u32_e32 v132, 0xcc00, v131
	ds_write2_b32 v132, v19, v3 offset0:12 offset1:44
	v_add_u32_e32 v132, 0xd400, v131
	ds_write2_b32 v132, v20, v4 offset0:160 offset1:192
	v_add_u32_e32 v132, 0xd800, v131
	ds_write2_b32 v132, v21, v5 offset0:36 offset1:68
	ds_write2_b32 v132, v22, v6 offset0:168 offset1:200
	v_add_u32_e32 v132, 0xdc00, v131
	ds_write2_b32 v132, v23, v7 offset0:44 offset1:76
	v_add_u32_e32 v132, 0xe400, v131
	ds_write2_b32 v132, v24, v8 offset0:192 offset1:224
	v_add_u32_e32 v132, 0xe800, v131
	ds_write2_b32 v132, v25, v9 offset0:68 offset1:100
	ds_write2_b32 v132, v26, v10 offset0:200 offset1:232
	v_add_u32_e32 v132, 0xec00, v131
	ds_write2_b32 v132, v27, v11 offset0:76 offset1:108
	v_add_u32_e32 v132, 0xf600, v131
	ds_write2_b32 v132, v28, v12 offset0:96 offset1:128
	v_add_u32_e32 v132, 0xf800, v131
	ds_write2_b32 v132, v29, v13 offset0:100 offset1:132
	v_add_u32_e32 v132, 0xfa00, v131
	v_add_u32_e32 v131, 0xfc00, v131
	ds_write2_b32 v132, v30, v14 offset0:104 offset1:136
	ds_write2_b32 v131, v31, v15 offset0:108 offset1:140
